# v35 + GEMM SP1 load segments issue the A-fragment ds_reads first (v14's edit) stacked
# speedup vs baseline: 1.0043x; 1.0043x over previous
; #define PG8_STAGE(bufoff, gbase, voff) do { _Pragma("unroll") for (int _i = 0; _i < 2; ++_i) \
;         __builtin_amdgcn_global_load_lds((const unsigned*)((const char*)(gbase) + (voff)[_i]), (LAS unsigned*)(lds + (bufoff) + ldsw + _i * 8192), 16, 0, 0); } while (0)
; #define PG8_LDA(dst, b, h) do { _Pragma("unroll") for (int m = 0; m < 4; ++m) _Pragma("unroll") for (int k = 0; k < 2; ++k) dst[m][k] = *(const LAS bf16x8*)(lds + PG8_SA(b, h) + aoff + m * 2048 + k * 1024); } while (0)
; #define PG8_LDB(dst, b, h) do { _Pragma("unroll") for (int n = 0; n < 2; ++n) _Pragma("unroll") for (int k = 0; k < 2; ++k) dst[n][k] = *(const LAS bf16x8*)(lds + PG8_SB(b, h) + boff + n * 2048 + k * 1024); } while (0)
; #define PG8_MMA(ai, bj, At, Bt) do { __builtin_amdgcn_s_setprio(1); _Pragma("unroll") for (int m = 0; m < 4; ++m) _Pragma("unroll") for (int n = 0; n < 2; ++n) _Pragma("unroll") for (int k = 0; k < 2; ++k) \
;         acc[ai][bj][m][n] = __builtin_amdgcn_mfma_f32_16x16x32_bf16(Bt[n][k], At[m][k], acc[ai][bj][m][n], 0, 0, 0); __builtin_amdgcn_s_setprio(0); } while (0)
; #define PG8_WAIT_V(n) asm volatile("s_waitcnt vmcnt(" #n ")" ::: "memory")
; #define PG8_WAIT_L(n) asm volatile("s_waitcnt lgkmcnt(" #n ")" ::: "memory")
; #define PG8_BAR __builtin_amdgcn_s_barrier()
; #define PG8_SCHED __builtin_amdgcn_sched_barrier(0)
; template <class Epi, class Sched, int LDA, int LDB, bool ALIGN_EPI = true>
; __device__ __forceinline__ void gemm_phase(LAS unsigned char* lds, const Gemm g, const Sched& S, const Epi& E, int wave) {
;     ...
;             PG8_LDB(B0, 0, 0); PG8_LDB(B1, 0, 1); PG8_SCHED; PG8_LDA(At, 0, 0); PG8_STAGE(PG8_SA(1, 1), a1 + hstepA, voffA);
;             PG8_WAIT_V(8); PG8_WAIT_L(0); PG8_BAR; PG8_MMA(0, 0, At, B0); PG8_MMA(0, 1, At, B1); PG8_BAR; PG8_SCHED;
;             PG8_LDA(At, 0, 1); PG8_STAGE(PG8_SB(0, 0), b2, voffB); PG8_STAGE(PG8_SB(0, 1), b2 + hstepB, voffB); PG8_STAGE(PG8_SA(0, 0), a2, voffA);
;             PG8_WAIT_V(8); PG8_WAIT_L(0); PG8_BAR; PG8_MMA(1, 0, At, B0); PG8_MMA(1, 1, At, B1); PG8_BAR; PG8_SCHED;
.LBB0_485:
	ds_read_b128 v[184:187], v145
	ds_read_b128 v[188:191], v145 offset:1024
	ds_read_b128 v[192:195], v145 offset:2048
	ds_read_b128 v[196:199], v145 offset:3072
	ds_read_b128 v[200:203], v145 offset:4096
	ds_read_b128 v[204:207], v145 offset:5120
	ds_read_b128 v[208:211], v145 offset:6144
	ds_read_b128 v[212:215], v145 offset:7168
	s_add_u32 s24, s18, 0x100
	s_addc_u32 s25, s19, 0
	s_add_i32 s54, 0, 0x10000
	s_cmp_eq_u32 s53, 28
	s_cselect_b32 s35, s3, s25
	s_cselect_b32 s34, s2, s24
	v_add_u32_e32 v140, s54, v143
	s_cselect_b32 s29, s1, s45
	s_cselect_b32 s28, s17, s44
	s_add_i32 s55, 0, 0x14000
	ds_read_b128 v[146:149], v140
	ds_read_b128 v[150:153], v140 offset:1024
	ds_read_b128 v[154:157], v140 offset:2048
	ds_read_b128 v[158:161], v140 offset:3072
	v_add_u32_e32 v140, s55, v143
	ds_read_b128 v[162:165], v140
	ds_read_b128 v[166:169], v140 offset:1024
	ds_read_b128 v[170:173], v140 offset:2048
	ds_read_b128 v[180:183], v140 offset:3072
	v_lshl_add_u64 v[140:141], s[18:19], 0, v[136:137]
	s_add_i32 m0, s38, 0xc000
	s_nop 0
	global_load_lds_dwordx4 v[140:141], off
	v_lshl_add_u64 v[140:141], s[18:19], 0, v[138:139]
	s_add_i32 m0, s38, 0xe000
	s_nop 0
	global_load_lds_dwordx4 v[140:141], off
	s_waitcnt vmcnt(8)
	s_waitcnt lgkmcnt(0)
	s_setprio 1
	s_barrier
	v_mfma_f32_16x16x32_bf16 v[126:129], v[146:149], v[184:187], v[126:129]
	v_mfma_f32_16x16x32_bf16 v[126:129], v[150:153], v[188:191], v[126:129]
	v_mfma_f32_16x16x32_bf16 v[118:121], v[154:157], v[184:187], v[118:121]
	v_mfma_f32_16x16x32_bf16 v[118:121], v[158:161], v[188:191], v[118:121]
	v_mfma_f32_16x16x32_bf16 v[110:113], v[146:149], v[192:195], v[110:113]
	v_mfma_f32_16x16x32_bf16 v[110:113], v[150:153], v[196:199], v[110:113]
	v_mfma_f32_16x16x32_bf16 v[102:105], v[154:157], v[192:195], v[102:105]
	v_mfma_f32_16x16x32_bf16 v[102:105], v[158:161], v[196:199], v[102:105]
	v_mfma_f32_16x16x32_bf16 v[94:97], v[146:149], v[200:203], v[94:97]
	v_mfma_f32_16x16x32_bf16 v[94:97], v[150:153], v[204:207], v[94:97]
	v_mfma_f32_16x16x32_bf16 v[86:89], v[154:157], v[200:203], v[86:89]
	v_mfma_f32_16x16x32_bf16 v[86:89], v[158:161], v[204:207], v[86:89]
	v_mfma_f32_16x16x32_bf16 v[78:81], v[146:149], v[208:211], v[78:81]
	v_mfma_f32_16x16x32_bf16 v[78:81], v[150:153], v[212:215], v[78:81]
	v_mfma_f32_16x16x32_bf16 v[70:73], v[154:157], v[208:211], v[70:73]
	v_mfma_f32_16x16x32_bf16 v[70:73], v[158:161], v[212:215], v[70:73]
	v_mfma_f32_16x16x32_bf16 v[122:125], v[162:165], v[184:187], v[122:125]
	v_mfma_f32_16x16x32_bf16 v[122:125], v[166:169], v[188:191], v[122:125]
	v_mfma_f32_16x16x32_bf16 v[114:117], v[170:173], v[184:187], v[114:117]
	v_mfma_f32_16x16x32_bf16 v[114:117], v[180:183], v[188:191], v[114:117]
	v_mfma_f32_16x16x32_bf16 v[106:109], v[162:165], v[192:195], v[106:109]
	v_mfma_f32_16x16x32_bf16 v[106:109], v[166:169], v[196:199], v[106:109]
	v_mfma_f32_16x16x32_bf16 v[98:101], v[170:173], v[192:195], v[98:101]
	v_mfma_f32_16x16x32_bf16 v[98:101], v[180:183], v[196:199], v[98:101]
	v_mfma_f32_16x16x32_bf16 v[90:93], v[162:165], v[200:203], v[90:93]
	v_mfma_f32_16x16x32_bf16 v[90:93], v[166:169], v[204:207], v[90:93]
	v_mfma_f32_16x16x32_bf16 v[82:85], v[170:173], v[200:203], v[82:85]
	v_mfma_f32_16x16x32_bf16 v[82:85], v[180:183], v[204:207], v[82:85]
	v_mfma_f32_16x16x32_bf16 v[74:77], v[162:165], v[208:211], v[74:77]
	v_mfma_f32_16x16x32_bf16 v[74:77], v[166:169], v[212:215], v[74:77]
	v_mfma_f32_16x16x32_bf16 v[66:69], v[170:173], v[208:211], v[66:69]
	v_mfma_f32_16x16x32_bf16 v[66:69], v[180:183], v[212:215], v[66:69]
	s_barrier
	s_setprio 0
	s_add_i32 s18, s54, s5
	v_lshl_add_u64 v[140:141], s[28:29], 0, v[0:1]
	s_mov_b32 m0, s18
	ds_read_b128 v[184:187], v145 offset:16384
	ds_read_b128 v[188:191], v145 offset:17408
	ds_read_b128 v[192:195], v145 offset:18432
	ds_read_b128 v[196:199], v145 offset:19456
	ds_read_b128 v[200:203], v145 offset:20480
	ds_read_b128 v[204:207], v145 offset:21504
	ds_read_b128 v[208:211], v145 offset:22528
	ds_read_b128 v[212:215], v145 offset:23552
	global_load_lds_dwordx4 v[140:141], off
	s_add_i32 m0, s18, 0x2000
	s_add_u32 s18, s28, 0x80000
	v_lshl_add_u64 v[174:175], s[28:29], 0, v[130:131]
	s_addc_u32 s19, s29, 0
	s_add_i32 s54, s55, s5
	global_load_lds_dwordx4 v[174:175], off
	v_lshl_add_u64 v[216:217], s[18:19], 0, v[0:1]
	s_mov_b32 m0, s54
	v_lshl_add_u64 v[218:219], s[34:35], 0, v[132:133]
	global_load_lds_dwordx4 v[216:217], off
	v_lshl_add_u64 v[216:217], s[18:19], 0, v[130:131]
	s_add_i32 m0, s54, 0x2000
	s_nop 0
	global_load_lds_dwordx4 v[216:217], off
	v_lshl_add_u64 v[216:217], s[34:35], 0, v[134:135]
	s_mov_b32 m0, s38
	s_nop 0
	global_load_lds_dwordx4 v[216:217], off
	s_mov_b32 m0, s39
	s_nop 0
	global_load_lds_dwordx4 v[218:219], off
	s_waitcnt vmcnt(8)
	s_waitcnt lgkmcnt(0)
	s_setprio 1
	s_barrier
; #define PG8_STAGE(bufoff, gbase, voff) do { _Pragma("unroll") for (int _i = 0; _i < 2; ++_i) \
;         __builtin_amdgcn_global_load_lds((const unsigned*)((const char*)(gbase) + (voff)[_i]), (LAS unsigned*)(lds + (bufoff) + ldsw + _i * 8192), 16, 0, 0); } while (0)
; #define PG8_LDA(dst, b, h) do { _Pragma("unroll") for (int m = 0; m < 4; ++m) _Pragma("unroll") for (int k = 0; k < 2; ++k) dst[m][k] = *(const LAS bf16x8*)(lds + PG8_SA(b, h) + aoff + m * 2048 + k * 1024); } while (0)
; #define PG8_LDB(dst, b, h) do { _Pragma("unroll") for (int n = 0; n < 2; ++n) _Pragma("unroll") for (int k = 0; k < 2; ++k) dst[n][k] = *(const LAS bf16x8*)(lds + PG8_SB(b, h) + boff + n * 2048 + k * 1024); } while (0)
; #define PG8_MMA(ai, bj, At, Bt) do { __builtin_amdgcn_s_setprio(1); _Pragma("unroll") for (int m = 0; m < 4; ++m) _Pragma("unroll") for (int n = 0; n < 2; ++n) _Pragma("unroll") for (int k = 0; k < 2; ++k) \
;         acc[ai][bj][m][n] = __builtin_amdgcn_mfma_f32_16x16x32_bf16(Bt[n][k], At[m][k], acc[ai][bj][m][n], 0, 0, 0); __builtin_amdgcn_s_setprio(0); } while (0)
; #define PG8_WAIT_V(n) asm volatile("s_waitcnt vmcnt(" #n ")" ::: "memory")
; #define PG8_WAIT_L(n) asm volatile("s_waitcnt lgkmcnt(" #n ")" ::: "memory")
; #define PG8_BAR __builtin_amdgcn_s_barrier()
; #define PG8_SCHED __builtin_amdgcn_sched_barrier(0)
; template <class Epi, class Sched, int LDA, int LDB, bool ALIGN_EPI = true>
; __device__ __forceinline__ void gemm_phase(LAS unsigned char* lds, const Gemm g, const Sched& S, const Epi& E, int wave) {
;     ...
;             PG8_WAIT_V(8); PG8_WAIT_L(0); PG8_BAR; PG8_MMA(1, 0, At, B0); PG8_MMA(1, 1, At, B1); PG8_BAR; PG8_SCHED;
;             PG8_LDB(B0, 1, 0); PG8_LDB(B1, 1, 1); PG8_SCHED; PG8_LDA(At, 1, 0); PG8_STAGE(PG8_SA(0, 1), a2 + hstepA, voffA);
;             PG8_WAIT_V(8); PG8_WAIT_L(0); PG8_BAR; PG8_MMA(0, 0, At, B0); PG8_MMA(0, 1, At, B1); PG8_BAR; PG8_SCHED;
	v_mfma_f32_16x16x32_bf16 v[62:65], v[146:149], v[184:187], v[62:65]
	v_mfma_f32_16x16x32_bf16 v[62:65], v[150:153], v[188:191], v[62:65]
	v_mfma_f32_16x16x32_bf16 v[54:57], v[154:157], v[184:187], v[54:57]
	v_mfma_f32_16x16x32_bf16 v[54:57], v[158:161], v[188:191], v[54:57]
	v_mfma_f32_16x16x32_bf16 v[46:49], v[146:149], v[192:195], v[46:49]
	v_mfma_f32_16x16x32_bf16 v[46:49], v[150:153], v[196:199], v[46:49]
	v_mfma_f32_16x16x32_bf16 v[38:41], v[154:157], v[192:195], v[38:41]
	v_mfma_f32_16x16x32_bf16 v[38:41], v[158:161], v[196:199], v[38:41]
	v_mfma_f32_16x16x32_bf16 v[30:33], v[146:149], v[200:203], v[30:33]
	v_mfma_f32_16x16x32_bf16 v[30:33], v[150:153], v[204:207], v[30:33]
	v_mfma_f32_16x16x32_bf16 v[22:25], v[154:157], v[200:203], v[22:25]
	v_mfma_f32_16x16x32_bf16 v[22:25], v[158:161], v[204:207], v[22:25]
	v_mfma_f32_16x16x32_bf16 v[14:17], v[146:149], v[208:211], v[14:17]
	v_mfma_f32_16x16x32_bf16 v[14:17], v[150:153], v[212:215], v[14:17]
	v_mfma_f32_16x16x32_bf16 v[6:9], v[154:157], v[208:211], v[6:9]
	v_mfma_f32_16x16x32_bf16 v[6:9], v[158:161], v[212:215], v[6:9]
	v_mfma_f32_16x16x32_bf16 v[58:61], v[162:165], v[184:187], v[58:61]
	v_mfma_f32_16x16x32_bf16 v[58:61], v[166:169], v[188:191], v[58:61]
	v_mfma_f32_16x16x32_bf16 v[50:53], v[170:173], v[184:187], v[50:53]
	v_mfma_f32_16x16x32_bf16 v[50:53], v[180:183], v[188:191], v[50:53]
	v_mfma_f32_16x16x32_bf16 v[42:45], v[162:165], v[192:195], v[42:45]
	v_mfma_f32_16x16x32_bf16 v[42:45], v[166:169], v[196:199], v[42:45]
	v_mfma_f32_16x16x32_bf16 v[34:37], v[170:173], v[192:195], v[34:37]
	v_mfma_f32_16x16x32_bf16 v[34:37], v[180:183], v[196:199], v[34:37]
	v_mfma_f32_16x16x32_bf16 v[26:29], v[162:165], v[200:203], v[26:29]
	v_mfma_f32_16x16x32_bf16 v[26:29], v[166:169], v[204:207], v[26:29]
	v_mfma_f32_16x16x32_bf16 v[18:21], v[170:173], v[200:203], v[18:21]
	v_mfma_f32_16x16x32_bf16 v[18:21], v[180:183], v[204:207], v[18:21]
	v_mfma_f32_16x16x32_bf16 v[10:13], v[162:165], v[208:211], v[10:13]
	v_mfma_f32_16x16x32_bf16 v[10:13], v[166:169], v[212:215], v[10:13]
	v_mfma_f32_16x16x32_bf16 v[2:5], v[170:173], v[208:211], v[2:5]
	v_mfma_f32_16x16x32_bf16 v[2:5], v[180:183], v[212:215], v[2:5]
	s_barrier
	s_setprio 0
	ds_read_b128 v[184:187], v145 offset:32768
	ds_read_b128 v[188:191], v145 offset:33792
	ds_read_b128 v[192:195], v145 offset:34816
	ds_read_b128 v[196:199], v145 offset:35840
	ds_read_b128 v[200:203], v145 offset:36864
	ds_read_b128 v[204:207], v145 offset:37888
	ds_read_b128 v[208:211], v145 offset:38912
	ds_read_b128 v[212:215], v145 offset:39936
	s_add_i32 s54, 0, 0x18000
	s_add_i32 s55, 0, 0x1c000
	v_add_u32_e32 v158, s54, v143
	v_add_u32_e32 v180, s55, v143
	ds_read_b128 v[146:149], v158
	ds_read_b128 v[150:153], v158 offset:1024
	ds_read_b128 v[154:157], v158 offset:2048
	ds_read_b128 v[158:161], v158 offset:3072
	ds_read_b128 v[162:165], v180
	ds_read_b128 v[166:169], v180 offset:1024
	ds_read_b128 v[170:173], v180 offset:2048
	ds_read_b128 v[180:183], v180 offset:3072
	s_add_u32 s18, s34, 0x84000
	s_addc_u32 s19, s35, 0
	s_mov_b32 m0, s46
	v_lshl_add_u64 v[220:221], s[18:19], 0, v[134:135]
	global_load_lds_dwordx4 v[220:221], off
	v_lshl_add_u64 v[220:221], s[18:19], 0, v[132:133]
	s_mov_b32 m0, s47
	s_nop 0
	global_load_lds_dwordx4 v[220:221], off
	s_waitcnt vmcnt(8)
	s_waitcnt lgkmcnt(0)
	s_setprio 1
	s_barrier
	v_mfma_f32_16x16x32_bf16 v[126:129], v[146:149], v[184:187], v[126:129]
	v_mfma_f32_16x16x32_bf16 v[126:129], v[150:153], v[188:191], v[126:129]
	v_mfma_f32_16x16x32_bf16 v[118:121], v[154:157], v[184:187], v[118:121]
	v_mfma_f32_16x16x32_bf16 v[118:121], v[158:161], v[188:191], v[118:121]
	v_mfma_f32_16x16x32_bf16 v[110:113], v[146:149], v[192:195], v[110:113]
	v_mfma_f32_16x16x32_bf16 v[110:113], v[150:153], v[196:199], v[110:113]
	v_mfma_f32_16x16x32_bf16 v[102:105], v[154:157], v[192:195], v[102:105]
	v_mfma_f32_16x16x32_bf16 v[102:105], v[158:161], v[196:199], v[102:105]
	v_mfma_f32_16x16x32_bf16 v[94:97], v[146:149], v[200:203], v[94:97]
	v_mfma_f32_16x16x32_bf16 v[94:97], v[150:153], v[204:207], v[94:97]
	v_mfma_f32_16x16x32_bf16 v[86:89], v[154:157], v[200:203], v[86:89]
	v_mfma_f32_16x16x32_bf16 v[86:89], v[158:161], v[204:207], v[86:89]
	v_mfma_f32_16x16x32_bf16 v[78:81], v[146:149], v[208:211], v[78:81]
	v_mfma_f32_16x16x32_bf16 v[78:81], v[150:153], v[212:215], v[78:81]
	v_mfma_f32_16x16x32_bf16 v[70:73], v[154:157], v[208:211], v[70:73]
	v_mfma_f32_16x16x32_bf16 v[70:73], v[158:161], v[212:215], v[70:73]
	v_mfma_f32_16x16x32_bf16 v[122:125], v[162:165], v[184:187], v[122:125]
	v_mfma_f32_16x16x32_bf16 v[122:125], v[166:169], v[188:191], v[122:125]
	v_mfma_f32_16x16x32_bf16 v[114:117], v[170:173], v[184:187], v[114:117]
	v_mfma_f32_16x16x32_bf16 v[114:117], v[180:183], v[188:191], v[114:117]
	v_mfma_f32_16x16x32_bf16 v[106:109], v[162:165], v[192:195], v[106:109]
	v_mfma_f32_16x16x32_bf16 v[106:109], v[166:169], v[196:199], v[106:109]
	v_mfma_f32_16x16x32_bf16 v[98:101], v[170:173], v[192:195], v[98:101]
	v_mfma_f32_16x16x32_bf16 v[98:101], v[180:183], v[196:199], v[98:101]
	v_mfma_f32_16x16x32_bf16 v[90:93], v[162:165], v[200:203], v[90:93]
	v_mfma_f32_16x16x32_bf16 v[90:93], v[166:169], v[204:207], v[90:93]
	v_mfma_f32_16x16x32_bf16 v[82:85], v[170:173], v[200:203], v[82:85]
	v_mfma_f32_16x16x32_bf16 v[82:85], v[180:183], v[204:207], v[82:85]
	v_mfma_f32_16x16x32_bf16 v[74:77], v[162:165], v[208:211], v[74:77]
	v_mfma_f32_16x16x32_bf16 v[74:77], v[166:169], v[212:215], v[74:77]
	v_mfma_f32_16x16x32_bf16 v[66:69], v[170:173], v[208:211], v[66:69]
	v_mfma_f32_16x16x32_bf16 v[66:69], v[180:183], v[212:215], v[66:69]
	s_barrier
; #define PG8_STAGE(bufoff, gbase, voff) do { _Pragma("unroll") for (int _i = 0; _i < 2; ++_i) \
;         __builtin_amdgcn_global_load_lds((const unsigned*)((const char*)(gbase) + (voff)[_i]), (LAS unsigned*)(lds + (bufoff) + ldsw + _i * 8192), 16, 0, 0); } while (0)
; #define PG8_LDA(dst, b, h) do { _Pragma("unroll") for (int m = 0; m < 4; ++m) _Pragma("unroll") for (int k = 0; k < 2; ++k) dst[m][k] = *(const LAS bf16x8*)(lds + PG8_SA(b, h) + aoff + m * 2048 + k * 1024); } while (0)
; #define PG8_MMA(ai, bj, At, Bt) do { __builtin_amdgcn_s_setprio(1); _Pragma("unroll") for (int m = 0; m < 4; ++m) _Pragma("unroll") for (int n = 0; n < 2; ++n) _Pragma("unroll") for (int k = 0; k < 2; ++k) \
;         acc[ai][bj][m][n] = __builtin_amdgcn_mfma_f32_16x16x32_bf16(Bt[n][k], At[m][k], acc[ai][bj][m][n], 0, 0, 0); __builtin_amdgcn_s_setprio(0); } while (0)
; #define PG8_WAIT_V(n) asm volatile("s_waitcnt vmcnt(" #n ")" ::: "memory")
; #define PG8_WAIT_L(n) asm volatile("s_waitcnt lgkmcnt(" #n ")" ::: "memory")
; #define PG8_BAR __builtin_amdgcn_s_barrier()
; #define PG8_SCHED __builtin_amdgcn_sched_barrier(0)
; template <class Epi, class Sched, int LDA, int LDB, bool ALIGN_EPI = true>
; __device__ __forceinline__ void gemm_phase(LAS unsigned char* lds, const Gemm g, const Sched& S, const Epi& E, int wave) {
;     ...
;             PG8_LDA(At, 1, 1); PG8_STAGE(PG8_SB(1, 0), b3, voffB); PG8_STAGE(PG8_SB(1, 1), b3 + hstepB, voffB); PG8_STAGE(PG8_SA(1, 0), a3, voffA);
;             PG8_WAIT_V(8); PG8_WAIT_L(0); PG8_BAR; PG8_MMA(1, 0, At, B0); PG8_MMA(1, 1, At, B1); PG8_BAR; PG8_SCHED;
;         }
;         if constexpr (ALIGN_EPI) { if (wr == 0) PG8_BAR; }
	s_setprio 0
	s_add_i32 s18, s54, s5
	v_lshl_add_u64 v[140:141], v[140:141], 0, s[6:7]
	s_mov_b32 m0, s18
	ds_read_b128 v[184:187], v145 offset:49152
	ds_read_b128 v[188:191], v145 offset:50176
	ds_read_b128 v[192:195], v145 offset:51200
	ds_read_b128 v[196:199], v145 offset:52224
	ds_read_b128 v[200:203], v145 offset:53248
	ds_read_b128 v[204:207], v145 offset:54272
	ds_read_b128 v[208:211], v145 offset:55296
	ds_read_b128 v[212:215], v145 offset:56320
	global_load_lds_dwordx4 v[140:141], off
	s_add_i32 m0, s18, 0x2000
	s_add_u32 s18, s28, 0x80080
	v_lshl_add_u64 v[140:141], v[174:175], 0, s[6:7]
	s_addc_u32 s19, s29, 0
	s_add_i32 s28, s55, s5
	global_load_lds_dwordx4 v[140:141], off
	v_lshl_add_u64 v[140:141], s[18:19], 0, v[0:1]
	s_mov_b32 m0, s28
	s_nop 0
	global_load_lds_dwordx4 v[140:141], off
	v_lshl_add_u64 v[140:141], s[18:19], 0, v[130:131]
	s_add_i32 m0, s28, 0x2000
	s_nop 0
	global_load_lds_dwordx4 v[140:141], off
	v_lshl_add_u64 v[140:141], v[216:217], 0, s[6:7]
	s_mov_b32 m0, s48
	s_nop 0
	global_load_lds_dwordx4 v[140:141], off
	v_lshl_add_u64 v[140:141], v[218:219], 0, s[6:7]
	s_mov_b32 m0, s49
	s_nop 0
	global_load_lds_dwordx4 v[140:141], off
	s_waitcnt vmcnt(8)
	s_waitcnt lgkmcnt(0)
	s_setprio 1
	s_barrier
	v_mfma_f32_16x16x32_bf16 v[62:65], v[146:149], v[184:187], v[62:65]
	v_mfma_f32_16x16x32_bf16 v[62:65], v[150:153], v[188:191], v[62:65]
	v_mfma_f32_16x16x32_bf16 v[54:57], v[154:157], v[184:187], v[54:57]
	v_mfma_f32_16x16x32_bf16 v[54:57], v[158:161], v[188:191], v[54:57]
	v_mfma_f32_16x16x32_bf16 v[46:49], v[146:149], v[192:195], v[46:49]
	v_mfma_f32_16x16x32_bf16 v[46:49], v[150:153], v[196:199], v[46:49]
	v_mfma_f32_16x16x32_bf16 v[38:41], v[154:157], v[192:195], v[38:41]
	v_mfma_f32_16x16x32_bf16 v[38:41], v[158:161], v[196:199], v[38:41]
	v_mfma_f32_16x16x32_bf16 v[30:33], v[146:149], v[200:203], v[30:33]
	v_mfma_f32_16x16x32_bf16 v[30:33], v[150:153], v[204:207], v[30:33]
	v_mfma_f32_16x16x32_bf16 v[22:25], v[154:157], v[200:203], v[22:25]
	v_mfma_f32_16x16x32_bf16 v[22:25], v[158:161], v[204:207], v[22:25]
	v_mfma_f32_16x16x32_bf16 v[14:17], v[146:149], v[208:211], v[14:17]
	v_mfma_f32_16x16x32_bf16 v[14:17], v[150:153], v[212:215], v[14:17]
	v_mfma_f32_16x16x32_bf16 v[6:9], v[154:157], v[208:211], v[6:9]
	v_mfma_f32_16x16x32_bf16 v[6:9], v[158:161], v[212:215], v[6:9]
	v_mfma_f32_16x16x32_bf16 v[58:61], v[162:165], v[184:187], v[58:61]
	v_mfma_f32_16x16x32_bf16 v[58:61], v[166:169], v[188:191], v[58:61]
	v_mfma_f32_16x16x32_bf16 v[50:53], v[170:173], v[184:187], v[50:53]
	v_mfma_f32_16x16x32_bf16 v[50:53], v[180:183], v[188:191], v[50:53]
	v_mfma_f32_16x16x32_bf16 v[42:45], v[162:165], v[192:195], v[42:45]
	v_mfma_f32_16x16x32_bf16 v[42:45], v[166:169], v[196:199], v[42:45]
	v_mfma_f32_16x16x32_bf16 v[34:37], v[170:173], v[192:195], v[34:37]
	v_mfma_f32_16x16x32_bf16 v[34:37], v[180:183], v[196:199], v[34:37]
	v_mfma_f32_16x16x32_bf16 v[26:29], v[162:165], v[200:203], v[26:29]
	v_mfma_f32_16x16x32_bf16 v[26:29], v[166:169], v[204:207], v[26:29]
	v_mfma_f32_16x16x32_bf16 v[18:21], v[170:173], v[200:203], v[18:21]
	v_mfma_f32_16x16x32_bf16 v[18:21], v[180:183], v[204:207], v[18:21]
	v_mfma_f32_16x16x32_bf16 v[10:13], v[162:165], v[208:211], v[10:13]
	v_mfma_f32_16x16x32_bf16 v[10:13], v[166:169], v[212:215], v[10:13]
	v_mfma_f32_16x16x32_bf16 v[2:5], v[170:173], v[208:211], v[2:5]
	v_mfma_f32_16x16x32_bf16 v[2:5], v[180:183], v[212:215], v[2:5]
	s_barrier
	s_setprio 0
	s_add_i32 s53, s53, 2
	s_add_u32 s44, s44, 0x100
	s_addc_u32 s45, s45, 0
	s_cmp_gt_u32 s53, 29
	s_mov_b64 s[18:19], s[24:25]
	s_cbranch_scc0 .LBB0_485
	v_readlane_b32 s6, v252, 14
	v_readlane_b32 s7, v252, 15
	s_and_b64 vcc, exec, s[6:7]
	s_cbranch_vccz .LBB0_488
	s_barrier

; #define PG8_STAGE(bufoff, gbase, voff) do { _Pragma("unroll") for (int _i = 0; _i < 2; ++_i) \
;         __builtin_amdgcn_global_load_lds((const unsigned*)((const char*)(gbase) + (voff)[_i]), (LAS unsigned*)(lds + (bufoff) + ldsw + _i * 8192), 16, 0, 0); } while (0)
; #define PG8_LDA(dst, b, h) do { _Pragma("unroll") for (int m = 0; m < 4; ++m) _Pragma("unroll") for (int k = 0; k < 2; ++k) dst[m][k] = *(const LAS bf16x8*)(lds + PG8_SA(b, h) + aoff + m * 2048 + k * 1024); } while (0)
; #define PG8_LDB(dst, b, h) do { _Pragma("unroll") for (int n = 0; n < 2; ++n) _Pragma("unroll") for (int k = 0; k < 2; ++k) dst[n][k] = *(const LAS bf16x8*)(lds + PG8_SB(b, h) + boff + n * 2048 + k * 1024); } while (0)
; #define PG8_MMA(ai, bj, At, Bt) do { __builtin_amdgcn_s_setprio(1); _Pragma("unroll") for (int m = 0; m < 4; ++m) _Pragma("unroll") for (int n = 0; n < 2; ++n) _Pragma("unroll") for (int k = 0; k < 2; ++k) \
;         acc[ai][bj][m][n] = __builtin_amdgcn_mfma_f32_16x16x32_bf16(Bt[n][k], At[m][k], acc[ai][bj][m][n], 0, 0, 0); __builtin_amdgcn_s_setprio(0); } while (0)
; #define PG8_WAIT_V(n) asm volatile("s_waitcnt vmcnt(" #n ")" ::: "memory")
; #define PG8_WAIT_L(n) asm volatile("s_waitcnt lgkmcnt(" #n ")" ::: "memory")
; #define PG8_BAR __builtin_amdgcn_s_barrier()
; template <class Epi, class Sched, int LDA, int LDB, bool ALIGN_EPI = true>
; __device__ __forceinline__ void gemm_phase(LAS unsigned char* lds, const Gemm g, const Sched& S, const Epi& E, int wave) {
;     ...
;         for (int t = 0; t < nt; t += 2) {
;             const bool last = (t == nt - 2);
;             const char* a1 = cA + (size_t)(t + 1) * kstep;
;             const char* a2 = last ? nA : cA + (size_t)(t + 2) * kstep; const char* b2 = last ? nB : cB + (size_t)(t + 2) * kstep;
;             const char* a3 = a2 + kstep; const char* b3 = b2 + kstep;
;             PG8_LDB(B0, 0, 0); PG8_LDB(B1, 0, 1); PG8_SCHED; PG8_LDA(At, 0, 0); PG8_STAGE(PG8_SA(1, 1), a1 + hstepA, voffA);
;             PG8_WAIT_V(8); PG8_WAIT_L(0); PG8_BAR; PG8_MMA(0, 0, At, B0); PG8_MMA(0, 1, At, B1); PG8_BAR; PG8_SCHED;
;             PG8_LDA(At, 0, 1); PG8_STAGE(PG8_SB(0, 0), b2, voffB); PG8_STAGE(PG8_SB(0, 1), b2 + hstepB, voffB); PG8_STAGE(PG8_SA(0, 0), a2, voffA);
;             PG8_WAIT_V(8); PG8_WAIT_L(0); PG8_BAR; PG8_MMA(1, 0, At, B0); PG8_MMA(1, 1, At, B1); PG8_BAR; PG8_SCHED;
.LBB0_1893:
	ds_read_b128 v[172:175], v236
	ds_read_b128 v[180:183], v236 offset:1024
	ds_read_b128 v[184:187], v236 offset:2048
	ds_read_b128 v[188:191], v236 offset:3072
	ds_read_b128 v[192:195], v236 offset:4096
	ds_read_b128 v[196:199], v236 offset:5120
	ds_read_b128 v[200:203], v236 offset:6144
	ds_read_b128 v[204:207], v236 offset:7168
	s_add_i32 s79, s46, 2
	s_add_u32 s38, s36, 0x100
	s_addc_u32 s39, s37, 0
	s_add_i32 s82, 0, 0x10000
	s_cmp_eq_u32 s25, s46
	s_cselect_b32 s49, s29, s39
	s_cselect_b32 s48, s28, s38
	s_cselect_b32 s47, s35, s78
	s_cselect_b32 s46, s34, s77
	s_add_i32 s85, 0, 0x14000
	v_add_u32_e32 v152, s82, v249
	v_add_u32_e32 v168, s85, v249
	ds_read_b128 v[130:133], v152
	ds_read_b128 v[134:137], v152 offset:1024
	ds_read_b128 v[148:151], v152 offset:2048
	ds_read_b128 v[152:155], v152 offset:3072
	ds_read_b128 v[156:159], v168
	ds_read_b128 v[160:163], v168 offset:1024
	ds_read_b128 v[164:167], v168 offset:2048
	ds_read_b128 v[168:171], v168 offset:3072
	v_lshl_add_u64 v[208:209], s[36:37], 0, v[144:145]
	s_add_i32 m0, s50, 0xc000
	s_nop 0
	global_load_lds_dwordx4 v[208:209], off
	v_lshl_add_u64 v[208:209], s[36:37], 0, v[146:147]
	s_add_i32 m0, s50, 0xe000
	s_nop 0
	global_load_lds_dwordx4 v[208:209], off
	s_waitcnt vmcnt(8)
	s_waitcnt lgkmcnt(0)
	s_setprio 1
	s_barrier
	v_mfma_f32_16x16x32_bf16 v[126:129], v[130:133], v[172:175], v[126:129]
	v_mfma_f32_16x16x32_bf16 v[126:129], v[134:137], v[180:183], v[126:129]
	v_mfma_f32_16x16x32_bf16 v[122:125], v[148:151], v[172:175], v[122:125]
	v_mfma_f32_16x16x32_bf16 v[122:125], v[152:155], v[180:183], v[122:125]
	v_mfma_f32_16x16x32_bf16 v[110:113], v[130:133], v[184:187], v[110:113]
	v_mfma_f32_16x16x32_bf16 v[110:113], v[134:137], v[188:191], v[110:113]
	v_mfma_f32_16x16x32_bf16 v[106:109], v[148:151], v[184:187], v[106:109]
	v_mfma_f32_16x16x32_bf16 v[106:109], v[152:155], v[188:191], v[106:109]
	v_mfma_f32_16x16x32_bf16 v[94:97], v[130:133], v[192:195], v[94:97]
	v_mfma_f32_16x16x32_bf16 v[94:97], v[134:137], v[196:199], v[94:97]
	v_mfma_f32_16x16x32_bf16 v[90:93], v[148:151], v[192:195], v[90:93]
	v_mfma_f32_16x16x32_bf16 v[90:93], v[152:155], v[196:199], v[90:93]
	v_mfma_f32_16x16x32_bf16 v[78:81], v[130:133], v[200:203], v[78:81]
	v_mfma_f32_16x16x32_bf16 v[78:81], v[134:137], v[204:207], v[78:81]
	v_mfma_f32_16x16x32_bf16 v[74:77], v[148:151], v[200:203], v[74:77]
	v_mfma_f32_16x16x32_bf16 v[74:77], v[152:155], v[204:207], v[74:77]
	v_mfma_f32_16x16x32_bf16 v[118:121], v[156:159], v[172:175], v[118:121]
	v_mfma_f32_16x16x32_bf16 v[118:121], v[160:163], v[180:183], v[118:121]
	v_mfma_f32_16x16x32_bf16 v[114:117], v[164:167], v[172:175], v[114:117]
	v_mfma_f32_16x16x32_bf16 v[114:117], v[168:171], v[180:183], v[114:117]
	v_mfma_f32_16x16x32_bf16 v[102:105], v[156:159], v[184:187], v[102:105]
	v_mfma_f32_16x16x32_bf16 v[102:105], v[160:163], v[188:191], v[102:105]
	v_mfma_f32_16x16x32_bf16 v[98:101], v[164:167], v[184:187], v[98:101]
	v_mfma_f32_16x16x32_bf16 v[98:101], v[168:171], v[188:191], v[98:101]
	v_mfma_f32_16x16x32_bf16 v[86:89], v[156:159], v[192:195], v[86:89]
	v_mfma_f32_16x16x32_bf16 v[86:89], v[160:163], v[196:199], v[86:89]
	v_mfma_f32_16x16x32_bf16 v[82:85], v[164:167], v[192:195], v[82:85]
	v_mfma_f32_16x16x32_bf16 v[82:85], v[168:171], v[196:199], v[82:85]
	v_mfma_f32_16x16x32_bf16 v[70:73], v[156:159], v[200:203], v[70:73]
	v_mfma_f32_16x16x32_bf16 v[70:73], v[160:163], v[204:207], v[70:73]
	v_mfma_f32_16x16x32_bf16 v[66:69], v[164:167], v[200:203], v[66:69]
	v_mfma_f32_16x16x32_bf16 v[66:69], v[168:171], v[204:207], v[66:69]
	s_barrier
	s_setprio 0
	s_add_i32 s36, s82, s2
	v_lshl_add_u64 v[208:209], s[46:47], 0, v[0:1]
	s_mov_b32 m0, s36
	ds_read_b128 v[172:175], v236 offset:16384
	ds_read_b128 v[180:183], v236 offset:17408
	ds_read_b128 v[184:187], v236 offset:18432
	ds_read_b128 v[188:191], v236 offset:19456
	ds_read_b128 v[192:195], v236 offset:20480
	ds_read_b128 v[196:199], v236 offset:21504
	ds_read_b128 v[200:203], v236 offset:22528
	ds_read_b128 v[204:207], v236 offset:23552
	global_load_lds_dwordx4 v[208:209], off
	s_add_i32 m0, s36, 0x2000
	s_add_u32 s36, s46, 0x160000
	v_lshl_add_u64 v[210:211], s[46:47], 0, v[142:143]
	s_addc_u32 s37, s47, 0
	s_add_i32 s82, s85, s2
	global_load_lds_dwordx4 v[210:211], off
	v_lshl_add_u64 v[212:213], s[36:37], 0, v[0:1]
	s_mov_b32 m0, s82
	v_lshl_add_u64 v[214:215], s[48:49], 0, v[140:141]
	global_load_lds_dwordx4 v[212:213], off
	v_lshl_add_u64 v[212:213], s[36:37], 0, v[142:143]
	s_add_i32 m0, s82, 0x2000
	s_nop 0
	global_load_lds_dwordx4 v[212:213], off
	v_lshl_add_u64 v[212:213], s[48:49], 0, v[138:139]
	s_mov_b32 m0, s50
	s_nop 0
	global_load_lds_dwordx4 v[212:213], off
	s_mov_b32 m0, s51
	s_nop 0
	global_load_lds_dwordx4 v[214:215], off
	s_waitcnt vmcnt(8)
	s_waitcnt lgkmcnt(0)
	s_setprio 1
	s_barrier
; #define PG8_STAGE(bufoff, gbase, voff) do { _Pragma("unroll") for (int _i = 0; _i < 2; ++_i) \
;         __builtin_amdgcn_global_load_lds((const unsigned*)((const char*)(gbase) + (voff)[_i]), (LAS unsigned*)(lds + (bufoff) + ldsw + _i * 8192), 16, 0, 0); } while (0)
; #define PG8_LDA(dst, b, h) do { _Pragma("unroll") for (int m = 0; m < 4; ++m) _Pragma("unroll") for (int k = 0; k < 2; ++k) dst[m][k] = *(const LAS bf16x8*)(lds + PG8_SA(b, h) + aoff + m * 2048 + k * 1024); } while (0)
; #define PG8_LDB(dst, b, h) do { _Pragma("unroll") for (int n = 0; n < 2; ++n) _Pragma("unroll") for (int k = 0; k < 2; ++k) dst[n][k] = *(const LAS bf16x8*)(lds + PG8_SB(b, h) + boff + n * 2048 + k * 1024); } while (0)
; #define PG8_MMA(ai, bj, At, Bt) do { __builtin_amdgcn_s_setprio(1); _Pragma("unroll") for (int m = 0; m < 4; ++m) _Pragma("unroll") for (int n = 0; n < 2; ++n) _Pragma("unroll") for (int k = 0; k < 2; ++k) \
;         acc[ai][bj][m][n] = __builtin_amdgcn_mfma_f32_16x16x32_bf16(Bt[n][k], At[m][k], acc[ai][bj][m][n], 0, 0, 0); __builtin_amdgcn_s_setprio(0); } while (0)
; #define PG8_WAIT_V(n) asm volatile("s_waitcnt vmcnt(" #n ")" ::: "memory")
; #define PG8_WAIT_L(n) asm volatile("s_waitcnt lgkmcnt(" #n ")" ::: "memory")
; #define PG8_BAR __builtin_amdgcn_s_barrier()
; #define PG8_SCHED __builtin_amdgcn_sched_barrier(0)
; template <class Epi, class Sched, int LDA, int LDB, bool ALIGN_EPI = true>
; __device__ __forceinline__ void gemm_phase(LAS unsigned char* lds, const Gemm g, const Sched& S, const Epi& E, int wave) {
;     ...
;             PG8_WAIT_V(8); PG8_WAIT_L(0); PG8_BAR; PG8_MMA(1, 0, At, B0); PG8_MMA(1, 1, At, B1); PG8_BAR; PG8_SCHED;
;             PG8_LDB(B0, 1, 0); PG8_LDB(B1, 1, 1); PG8_SCHED; PG8_LDA(At, 1, 0); PG8_STAGE(PG8_SA(0, 1), a2 + hstepA, voffA);
;             PG8_WAIT_V(8); PG8_WAIT_L(0); PG8_BAR; PG8_MMA(0, 0, At, B0); PG8_MMA(0, 1, At, B1); PG8_BAR; PG8_SCHED;
	v_mfma_f32_16x16x32_bf16 v[62:65], v[130:133], v[172:175], v[62:65]
	v_mfma_f32_16x16x32_bf16 v[62:65], v[134:137], v[180:183], v[62:65]
	v_mfma_f32_16x16x32_bf16 v[58:61], v[148:151], v[172:175], v[58:61]
	v_mfma_f32_16x16x32_bf16 v[58:61], v[152:155], v[180:183], v[58:61]
	v_mfma_f32_16x16x32_bf16 v[46:49], v[130:133], v[184:187], v[46:49]
	v_mfma_f32_16x16x32_bf16 v[46:49], v[134:137], v[188:191], v[46:49]
	v_mfma_f32_16x16x32_bf16 v[42:45], v[148:151], v[184:187], v[42:45]
	v_mfma_f32_16x16x32_bf16 v[42:45], v[152:155], v[188:191], v[42:45]
	v_mfma_f32_16x16x32_bf16 v[30:33], v[130:133], v[192:195], v[30:33]
	v_mfma_f32_16x16x32_bf16 v[30:33], v[134:137], v[196:199], v[30:33]
	v_mfma_f32_16x16x32_bf16 v[26:29], v[148:151], v[192:195], v[26:29]
	v_mfma_f32_16x16x32_bf16 v[26:29], v[152:155], v[196:199], v[26:29]
	v_mfma_f32_16x16x32_bf16 v[14:17], v[130:133], v[200:203], v[14:17]
	v_mfma_f32_16x16x32_bf16 v[14:17], v[134:137], v[204:207], v[14:17]
	v_mfma_f32_16x16x32_bf16 v[10:13], v[148:151], v[200:203], v[10:13]
	v_mfma_f32_16x16x32_bf16 v[10:13], v[152:155], v[204:207], v[10:13]
	v_mfma_f32_16x16x32_bf16 v[54:57], v[156:159], v[172:175], v[54:57]
	v_mfma_f32_16x16x32_bf16 v[54:57], v[160:163], v[180:183], v[54:57]
	v_mfma_f32_16x16x32_bf16 v[50:53], v[164:167], v[172:175], v[50:53]
	v_mfma_f32_16x16x32_bf16 v[50:53], v[168:171], v[180:183], v[50:53]
	v_mfma_f32_16x16x32_bf16 v[38:41], v[156:159], v[184:187], v[38:41]
	v_mfma_f32_16x16x32_bf16 v[38:41], v[160:163], v[188:191], v[38:41]
	v_mfma_f32_16x16x32_bf16 v[34:37], v[164:167], v[184:187], v[34:37]
	v_mfma_f32_16x16x32_bf16 v[34:37], v[168:171], v[188:191], v[34:37]
	v_mfma_f32_16x16x32_bf16 v[22:25], v[156:159], v[192:195], v[22:25]
	v_mfma_f32_16x16x32_bf16 v[22:25], v[160:163], v[196:199], v[22:25]
	v_mfma_f32_16x16x32_bf16 v[18:21], v[164:167], v[192:195], v[18:21]
	v_mfma_f32_16x16x32_bf16 v[18:21], v[168:171], v[196:199], v[18:21]
	v_mfma_f32_16x16x32_bf16 v[6:9], v[156:159], v[200:203], v[6:9]
	v_mfma_f32_16x16x32_bf16 v[6:9], v[160:163], v[204:207], v[6:9]
	v_mfma_f32_16x16x32_bf16 v[2:5], v[164:167], v[200:203], v[2:5]
	v_mfma_f32_16x16x32_bf16 v[2:5], v[168:171], v[204:207], v[2:5]
	s_barrier
	s_setprio 0
	ds_read_b128 v[172:175], v236 offset:32768
	ds_read_b128 v[180:183], v236 offset:33792
	ds_read_b128 v[184:187], v236 offset:34816
	ds_read_b128 v[188:191], v236 offset:35840
	ds_read_b128 v[192:195], v236 offset:36864
	ds_read_b128 v[196:199], v236 offset:37888
	ds_read_b128 v[200:203], v236 offset:38912
	ds_read_b128 v[204:207], v236 offset:39936
	s_add_i32 s82, 0, 0x18000
	s_add_i32 s85, 0, 0x1c000
	v_add_u32_e32 v152, s82, v249
	v_add_u32_e32 v168, s85, v249
	ds_read_b128 v[130:133], v152
	ds_read_b128 v[134:137], v152 offset:1024
	ds_read_b128 v[148:151], v152 offset:2048
	ds_read_b128 v[152:155], v152 offset:3072
	ds_read_b128 v[156:159], v168
	ds_read_b128 v[160:163], v168 offset:1024
	ds_read_b128 v[164:167], v168 offset:2048
	ds_read_b128 v[168:171], v168 offset:3072
	s_add_u32 s36, s48, 0x160000
	s_addc_u32 s37, s49, 0
	s_mov_b32 m0, s52
	v_lshl_add_u64 v[216:217], s[36:37], 0, v[138:139]
	global_load_lds_dwordx4 v[216:217], off
	v_lshl_add_u64 v[216:217], s[36:37], 0, v[140:141]
	s_mov_b32 m0, s53
	s_nop 0
	global_load_lds_dwordx4 v[216:217], off
	s_waitcnt vmcnt(8)
	s_waitcnt lgkmcnt(0)
	s_setprio 1
	s_barrier
	v_mfma_f32_16x16x32_bf16 v[126:129], v[130:133], v[172:175], v[126:129]
	v_mfma_f32_16x16x32_bf16 v[126:129], v[134:137], v[180:183], v[126:129]
	v_mfma_f32_16x16x32_bf16 v[122:125], v[148:151], v[172:175], v[122:125]
	v_mfma_f32_16x16x32_bf16 v[122:125], v[152:155], v[180:183], v[122:125]
	v_mfma_f32_16x16x32_bf16 v[110:113], v[130:133], v[184:187], v[110:113]
	v_mfma_f32_16x16x32_bf16 v[110:113], v[134:137], v[188:191], v[110:113]
	v_mfma_f32_16x16x32_bf16 v[106:109], v[148:151], v[184:187], v[106:109]
	v_mfma_f32_16x16x32_bf16 v[106:109], v[152:155], v[188:191], v[106:109]
	v_mfma_f32_16x16x32_bf16 v[94:97], v[130:133], v[192:195], v[94:97]
	v_mfma_f32_16x16x32_bf16 v[94:97], v[134:137], v[196:199], v[94:97]
	v_mfma_f32_16x16x32_bf16 v[90:93], v[148:151], v[192:195], v[90:93]
	v_mfma_f32_16x16x32_bf16 v[90:93], v[152:155], v[196:199], v[90:93]
	v_mfma_f32_16x16x32_bf16 v[78:81], v[130:133], v[200:203], v[78:81]
	v_mfma_f32_16x16x32_bf16 v[78:81], v[134:137], v[204:207], v[78:81]
	v_mfma_f32_16x16x32_bf16 v[74:77], v[148:151], v[200:203], v[74:77]
	v_mfma_f32_16x16x32_bf16 v[74:77], v[152:155], v[204:207], v[74:77]
	v_mfma_f32_16x16x32_bf16 v[118:121], v[156:159], v[172:175], v[118:121]
	v_mfma_f32_16x16x32_bf16 v[118:121], v[160:163], v[180:183], v[118:121]
	v_mfma_f32_16x16x32_bf16 v[114:117], v[164:167], v[172:175], v[114:117]
	v_mfma_f32_16x16x32_bf16 v[114:117], v[168:171], v[180:183], v[114:117]
	v_mfma_f32_16x16x32_bf16 v[102:105], v[156:159], v[184:187], v[102:105]
	v_mfma_f32_16x16x32_bf16 v[102:105], v[160:163], v[188:191], v[102:105]
	v_mfma_f32_16x16x32_bf16 v[98:101], v[164:167], v[184:187], v[98:101]
	v_mfma_f32_16x16x32_bf16 v[98:101], v[168:171], v[188:191], v[98:101]
	v_mfma_f32_16x16x32_bf16 v[86:89], v[156:159], v[192:195], v[86:89]
	v_mfma_f32_16x16x32_bf16 v[86:89], v[160:163], v[196:199], v[86:89]
	v_mfma_f32_16x16x32_bf16 v[82:85], v[164:167], v[192:195], v[82:85]
	v_mfma_f32_16x16x32_bf16 v[82:85], v[168:171], v[196:199], v[82:85]
	v_mfma_f32_16x16x32_bf16 v[70:73], v[156:159], v[200:203], v[70:73]
	v_mfma_f32_16x16x32_bf16 v[70:73], v[160:163], v[204:207], v[70:73]
	v_mfma_f32_16x16x32_bf16 v[66:69], v[164:167], v[200:203], v[66:69]
	v_mfma_f32_16x16x32_bf16 v[66:69], v[168:171], v[204:207], v[66:69]
	s_barrier
; #define PG8_STAGE(bufoff, gbase, voff) do { _Pragma("unroll") for (int _i = 0; _i < 2; ++_i) \
;         __builtin_amdgcn_global_load_lds((const unsigned*)((const char*)(gbase) + (voff)[_i]), (LAS unsigned*)(lds + (bufoff) + ldsw + _i * 8192), 16, 0, 0); } while (0)
; #define PG8_LDA(dst, b, h) do { _Pragma("unroll") for (int m = 0; m < 4; ++m) _Pragma("unroll") for (int k = 0; k < 2; ++k) dst[m][k] = *(const LAS bf16x8*)(lds + PG8_SA(b, h) + aoff + m * 2048 + k * 1024); } while (0)
; #define PG8_MMA(ai, bj, At, Bt) do { __builtin_amdgcn_s_setprio(1); _Pragma("unroll") for (int m = 0; m < 4; ++m) _Pragma("unroll") for (int n = 0; n < 2; ++n) _Pragma("unroll") for (int k = 0; k < 2; ++k) \
;         acc[ai][bj][m][n] = __builtin_amdgcn_mfma_f32_16x16x32_bf16(Bt[n][k], At[m][k], acc[ai][bj][m][n], 0, 0, 0); __builtin_amdgcn_s_setprio(0); } while (0)
; #define PG8_WAIT_V(n) asm volatile("s_waitcnt vmcnt(" #n ")" ::: "memory")
; #define PG8_WAIT_L(n) asm volatile("s_waitcnt lgkmcnt(" #n ")" ::: "memory")
; #define PG8_BAR __builtin_amdgcn_s_barrier()
; #define PG8_SCHED __builtin_amdgcn_sched_barrier(0)
; template <class Epi, class Sched, int LDA, int LDB, bool ALIGN_EPI = true>
; __device__ __forceinline__ void gemm_phase(LAS unsigned char* lds, const Gemm g, const Sched& S, const Epi& E, int wave) {
;     ...
;             PG8_LDA(At, 1, 1); PG8_STAGE(PG8_SB(1, 0), b3, voffB); PG8_STAGE(PG8_SB(1, 1), b3 + hstepB, voffB); PG8_STAGE(PG8_SA(1, 0), a3, voffA);
;             PG8_WAIT_V(8); PG8_WAIT_L(0); PG8_BAR; PG8_MMA(1, 0, At, B0); PG8_MMA(1, 1, At, B1); PG8_BAR; PG8_SCHED;
;         }
;         if constexpr (ALIGN_EPI) { if (wr == 0) PG8_BAR; }
	s_setprio 0
	s_add_i32 s36, s82, s2
	v_lshl_add_u64 v[208:209], v[208:209], 0, s[8:9]
	s_mov_b32 m0, s36
	ds_read_b128 v[172:175], v236 offset:49152
	ds_read_b128 v[180:183], v236 offset:50176
	ds_read_b128 v[184:187], v236 offset:51200
	ds_read_b128 v[188:191], v236 offset:52224
	ds_read_b128 v[192:195], v236 offset:53248
	ds_read_b128 v[196:199], v236 offset:54272
	ds_read_b128 v[200:203], v236 offset:55296
	ds_read_b128 v[204:207], v236 offset:56320
	global_load_lds_dwordx4 v[208:209], off
	s_add_i32 m0, s36, 0x2000
	s_add_u32 s36, s46, 0x160080
	v_lshl_add_u64 v[208:209], v[210:211], 0, s[8:9]
	s_addc_u32 s37, s47, 0
	s_add_i32 s46, s85, s2
	global_load_lds_dwordx4 v[208:209], off
	v_lshl_add_u64 v[208:209], s[36:37], 0, v[0:1]
	s_mov_b32 m0, s46
	s_nop 0
	global_load_lds_dwordx4 v[208:209], off
	v_lshl_add_u64 v[208:209], s[36:37], 0, v[142:143]
	s_add_i32 m0, s46, 0x2000
	s_nop 0
	global_load_lds_dwordx4 v[208:209], off
	v_lshl_add_u64 v[208:209], v[212:213], 0, s[8:9]
	s_mov_b32 m0, s5
	s_nop 0
	global_load_lds_dwordx4 v[208:209], off
	v_lshl_add_u64 v[208:209], v[214:215], 0, s[8:9]
	s_mov_b32 m0, s59
	s_nop 0
	global_load_lds_dwordx4 v[208:209], off
	s_waitcnt vmcnt(8)
	s_waitcnt lgkmcnt(0)
	s_setprio 1
	s_barrier
	v_mfma_f32_16x16x32_bf16 v[62:65], v[130:133], v[172:175], v[62:65]
	v_mfma_f32_16x16x32_bf16 v[62:65], v[134:137], v[180:183], v[62:65]
	v_mfma_f32_16x16x32_bf16 v[58:61], v[148:151], v[172:175], v[58:61]
	v_mfma_f32_16x16x32_bf16 v[58:61], v[152:155], v[180:183], v[58:61]
	v_mfma_f32_16x16x32_bf16 v[46:49], v[130:133], v[184:187], v[46:49]
	v_mfma_f32_16x16x32_bf16 v[46:49], v[134:137], v[188:191], v[46:49]
	v_mfma_f32_16x16x32_bf16 v[42:45], v[148:151], v[184:187], v[42:45]
	v_mfma_f32_16x16x32_bf16 v[42:45], v[152:155], v[188:191], v[42:45]
	v_mfma_f32_16x16x32_bf16 v[30:33], v[130:133], v[192:195], v[30:33]
	v_mfma_f32_16x16x32_bf16 v[30:33], v[134:137], v[196:199], v[30:33]
	v_mfma_f32_16x16x32_bf16 v[26:29], v[148:151], v[192:195], v[26:29]
	v_mfma_f32_16x16x32_bf16 v[26:29], v[152:155], v[196:199], v[26:29]
	v_mfma_f32_16x16x32_bf16 v[14:17], v[130:133], v[200:203], v[14:17]
	v_mfma_f32_16x16x32_bf16 v[14:17], v[134:137], v[204:207], v[14:17]
	v_mfma_f32_16x16x32_bf16 v[10:13], v[148:151], v[200:203], v[10:13]
	v_mfma_f32_16x16x32_bf16 v[10:13], v[152:155], v[204:207], v[10:13]
	v_mfma_f32_16x16x32_bf16 v[54:57], v[156:159], v[172:175], v[54:57]
	v_mfma_f32_16x16x32_bf16 v[54:57], v[160:163], v[180:183], v[54:57]
	v_mfma_f32_16x16x32_bf16 v[50:53], v[164:167], v[172:175], v[50:53]
	v_mfma_f32_16x16x32_bf16 v[50:53], v[168:171], v[180:183], v[50:53]
	v_mfma_f32_16x16x32_bf16 v[38:41], v[156:159], v[184:187], v[38:41]
	v_mfma_f32_16x16x32_bf16 v[38:41], v[160:163], v[188:191], v[38:41]
	v_mfma_f32_16x16x32_bf16 v[34:37], v[164:167], v[184:187], v[34:37]
	v_mfma_f32_16x16x32_bf16 v[34:37], v[168:171], v[188:191], v[34:37]
	v_mfma_f32_16x16x32_bf16 v[22:25], v[156:159], v[192:195], v[22:25]
	v_mfma_f32_16x16x32_bf16 v[22:25], v[160:163], v[196:199], v[22:25]
	v_mfma_f32_16x16x32_bf16 v[18:21], v[164:167], v[192:195], v[18:21]
	v_mfma_f32_16x16x32_bf16 v[18:21], v[168:171], v[196:199], v[18:21]
	v_mfma_f32_16x16x32_bf16 v[6:9], v[156:159], v[200:203], v[6:9]
	v_mfma_f32_16x16x32_bf16 v[6:9], v[160:163], v[204:207], v[6:9]
	v_mfma_f32_16x16x32_bf16 v[2:5], v[164:167], v[200:203], v[2:5]
	v_mfma_f32_16x16x32_bf16 v[2:5], v[168:171], v[204:207], v[2:5]
	s_barrier
	s_setprio 0
	s_add_u32 s77, s77, 0x100
	s_addc_u32 s78, s78, 0
	s_cmp_ge_i32 s79, s75
	s_mov_b64 s[36:37], s[38:39]
	s_mov_b32 s46, s79
	s_cbranch_scc0 .LBB0_1893
	v_readlane_b32 s2, v252, 14
	v_readlane_b32 s3, v252, 15
	s_and_b64 vcc, exec, s[2:3]
	s_cbranch_vccz .LBB0_1896
	s_barrier

; #define PG8_STAGE(bufoff, gbase, voff) do { _Pragma("unroll") for (int _i = 0; _i < 2; ++_i) \
;         __builtin_amdgcn_global_load_lds((const unsigned*)((const char*)(gbase) + (voff)[_i]), (LAS unsigned*)(lds + (bufoff) + ldsw + _i * 8192), 16, 0, 0); } while (0)
; #define PG8_LDA(dst, b, h) do { _Pragma("unroll") for (int m = 0; m < 4; ++m) _Pragma("unroll") for (int k = 0; k < 2; ++k) dst[m][k] = *(const LAS bf16x8*)(lds + PG8_SA(b, h) + aoff + m * 2048 + k * 1024); } while (0)
; #define PG8_LDB(dst, b, h) do { _Pragma("unroll") for (int n = 0; n < 2; ++n) _Pragma("unroll") for (int k = 0; k < 2; ++k) dst[n][k] = *(const LAS bf16x8*)(lds + PG8_SB(b, h) + boff + n * 2048 + k * 1024); } while (0)
; #define PG8_MMA(ai, bj, At, Bt) do { __builtin_amdgcn_s_setprio(1); _Pragma("unroll") for (int m = 0; m < 4; ++m) _Pragma("unroll") for (int n = 0; n < 2; ++n) _Pragma("unroll") for (int k = 0; k < 2; ++k) \
;         acc[ai][bj][m][n] = __builtin_amdgcn_mfma_f32_16x16x32_bf16(Bt[n][k], At[m][k], acc[ai][bj][m][n], 0, 0, 0); __builtin_amdgcn_s_setprio(0); } while (0)
; #define PG8_WAIT_V(n) asm volatile("s_waitcnt vmcnt(" #n ")" ::: "memory")
; #define PG8_WAIT_L(n) asm volatile("s_waitcnt lgkmcnt(" #n ")" ::: "memory")
; #define PG8_BAR __builtin_amdgcn_s_barrier()
; template <class Epi, class Sched, int LDA, int LDB, bool ALIGN_EPI = true>
; __device__ __forceinline__ void gemm_phase(LAS unsigned char* lds, const Gemm g, const Sched& S, const Epi& E, int wave) {
;     ...
;         for (int t = 0; t < nt; t += 2) {
;             const bool last = (t == nt - 2);
;             const char* a1 = cA + (size_t)(t + 1) * kstep;
;             const char* a2 = last ? nA : cA + (size_t)(t + 2) * kstep; const char* b2 = last ? nB : cB + (size_t)(t + 2) * kstep;
;             const char* a3 = a2 + kstep; const char* b3 = b2 + kstep;
;             PG8_LDB(B0, 0, 0); PG8_LDB(B1, 0, 1); PG8_SCHED; PG8_LDA(At, 0, 0); PG8_STAGE(PG8_SA(1, 1), a1 + hstepA, voffA);
;             PG8_WAIT_V(8); PG8_WAIT_L(0); PG8_BAR; PG8_MMA(0, 0, At, B0); PG8_MMA(0, 1, At, B1); PG8_BAR; PG8_SCHED;
;             PG8_LDA(At, 0, 1); PG8_STAGE(PG8_SB(0, 0), b2, voffB); PG8_STAGE(PG8_SB(0, 1), b2 + hstepB, voffB); PG8_STAGE(PG8_SA(0, 0), a2, voffA);
;             PG8_WAIT_V(8); PG8_WAIT_L(0); PG8_BAR; PG8_MMA(1, 0, At, B0); PG8_MMA(1, 1, At, B1); PG8_BAR; PG8_SCHED;
.LBB0_2254:
	ds_read_b128 v[184:187], v163
	ds_read_b128 v[188:191], v163 offset:1024
	ds_read_b128 v[192:195], v163 offset:2048
	ds_read_b128 v[196:199], v163 offset:3072
	ds_read_b128 v[200:203], v163 offset:4096
	ds_read_b128 v[204:207], v163 offset:5120
	ds_read_b128 v[208:211], v163 offset:6144
	ds_read_b128 v[212:215], v163 offset:7168
	s_add_u32 s2, s0, 0x100
	s_addc_u32 s3, s1, 0
	s_add_i32 s64, 0, 0x10000
	s_cmp_eq_u32 s59, 28
	s_cselect_b32 s29, s15, s3
	s_cselect_b32 s28, s14, s2
	v_add_u32_e32 v0, s64, v161
	s_cselect_b32 s25, s13, s58
	s_cselect_b32 s24, s48, s49
	s_add_i32 s65, 0, 0x14000
	ds_read_b128 v[144:147], v0
	ds_read_b128 v[148:151], v0 offset:1024
	ds_read_b128 v[152:155], v0 offset:2048
	ds_read_b128 v[156:159], v0 offset:3072
	v_add_u32_e32 v0, s65, v161
	ds_read_b128 v[164:167], v0
	ds_read_b128 v[168:171], v0 offset:1024
	ds_read_b128 v[172:175], v0 offset:2048
	ds_read_b128 v[180:183], v0 offset:3072
	v_lshl_add_u64 v[216:217], s[0:1], 0, v[140:141]
	s_add_i32 m0, s19, 0xc000
	s_nop 0
	global_load_lds_dwordx4 v[216:217], off
	v_lshl_add_u64 v[216:217], s[0:1], 0, v[142:143]
	s_add_i32 m0, s19, 0xe000
	s_nop 0
	global_load_lds_dwordx4 v[216:217], off
	s_waitcnt vmcnt(8)
	s_waitcnt lgkmcnt(0)
	s_setprio 1
	s_barrier
	v_mfma_f32_16x16x32_bf16 v[126:129], v[144:147], v[184:187], v[126:129]
	v_mfma_f32_16x16x32_bf16 v[126:129], v[148:151], v[188:191], v[126:129]
	v_mfma_f32_16x16x32_bf16 v[122:125], v[152:155], v[184:187], v[122:125]
	v_mfma_f32_16x16x32_bf16 v[122:125], v[156:159], v[188:191], v[122:125]
	v_mfma_f32_16x16x32_bf16 v[118:121], v[144:147], v[192:195], v[118:121]
	v_mfma_f32_16x16x32_bf16 v[118:121], v[148:151], v[196:199], v[118:121]
	v_mfma_f32_16x16x32_bf16 v[114:117], v[152:155], v[192:195], v[114:117]
	v_mfma_f32_16x16x32_bf16 v[114:117], v[156:159], v[196:199], v[114:117]
	v_mfma_f32_16x16x32_bf16 v[110:113], v[144:147], v[200:203], v[110:113]
	v_mfma_f32_16x16x32_bf16 v[110:113], v[148:151], v[204:207], v[110:113]
	v_mfma_f32_16x16x32_bf16 v[106:109], v[152:155], v[200:203], v[106:109]
	v_mfma_f32_16x16x32_bf16 v[106:109], v[156:159], v[204:207], v[106:109]
	v_mfma_f32_16x16x32_bf16 v[102:105], v[144:147], v[208:211], v[102:105]
	v_mfma_f32_16x16x32_bf16 v[102:105], v[148:151], v[212:215], v[102:105]
	v_mfma_f32_16x16x32_bf16 v[98:101], v[152:155], v[208:211], v[98:101]
	v_mfma_f32_16x16x32_bf16 v[98:101], v[156:159], v[212:215], v[98:101]
	v_mfma_f32_16x16x32_bf16 v[62:65], v[164:167], v[184:187], v[62:65]
	v_mfma_f32_16x16x32_bf16 v[62:65], v[168:171], v[188:191], v[62:65]
	v_mfma_f32_16x16x32_bf16 v[58:61], v[172:175], v[184:187], v[58:61]
	v_mfma_f32_16x16x32_bf16 v[58:61], v[180:183], v[188:191], v[58:61]
	v_mfma_f32_16x16x32_bf16 v[54:57], v[164:167], v[192:195], v[54:57]
	v_mfma_f32_16x16x32_bf16 v[54:57], v[168:171], v[196:199], v[54:57]
	v_mfma_f32_16x16x32_bf16 v[50:53], v[172:175], v[192:195], v[50:53]
	v_mfma_f32_16x16x32_bf16 v[50:53], v[180:183], v[196:199], v[50:53]
	v_mfma_f32_16x16x32_bf16 v[46:49], v[164:167], v[200:203], v[46:49]
	v_mfma_f32_16x16x32_bf16 v[46:49], v[168:171], v[204:207], v[46:49]
	v_mfma_f32_16x16x32_bf16 v[42:45], v[172:175], v[200:203], v[42:45]
	v_mfma_f32_16x16x32_bf16 v[42:45], v[180:183], v[204:207], v[42:45]
	v_mfma_f32_16x16x32_bf16 v[38:41], v[164:167], v[208:211], v[38:41]
	v_mfma_f32_16x16x32_bf16 v[38:41], v[168:171], v[212:215], v[38:41]
	v_mfma_f32_16x16x32_bf16 v[34:37], v[172:175], v[208:211], v[34:37]
	v_mfma_f32_16x16x32_bf16 v[34:37], v[180:183], v[212:215], v[34:37]
	s_barrier
	s_setprio 0
	s_add_i32 s0, s64, s61
	v_lshl_add_u64 v[216:217], s[24:25], 0, v[132:133]
	s_mov_b32 m0, s0
	ds_read_b128 v[184:187], v163 offset:16384
	ds_read_b128 v[188:191], v163 offset:17408
	ds_read_b128 v[192:195], v163 offset:18432
	ds_read_b128 v[196:199], v163 offset:19456
	ds_read_b128 v[200:203], v163 offset:20480
	ds_read_b128 v[204:207], v163 offset:21504
	ds_read_b128 v[208:211], v163 offset:22528
	ds_read_b128 v[212:215], v163 offset:23552
	global_load_lds_dwordx4 v[216:217], off
	s_add_i32 m0, s0, 0x2000
	s_add_u32 s0, s24, 0x80000
	v_lshl_add_u64 v[218:219], s[24:25], 0, v[136:137]
	s_addc_u32 s1, s25, 0
	s_add_i32 s64, s65, s61
	global_load_lds_dwordx4 v[218:219], off
	v_lshl_add_u64 v[220:221], s[0:1], 0, v[132:133]
	s_mov_b32 m0, s64
	v_lshl_add_u64 v[222:223], s[28:29], 0, v[134:135]
	global_load_lds_dwordx4 v[220:221], off
	v_lshl_add_u64 v[220:221], s[0:1], 0, v[136:137]
	s_add_i32 m0, s64, 0x2000
	s_nop 0
	global_load_lds_dwordx4 v[220:221], off
	v_lshl_add_u64 v[220:221], s[28:29], 0, v[130:131]
	s_mov_b32 m0, s19
	s_nop 0
	global_load_lds_dwordx4 v[220:221], off
	s_mov_b32 m0, s35
	s_nop 0
	global_load_lds_dwordx4 v[222:223], off
	s_waitcnt vmcnt(8)
	s_waitcnt lgkmcnt(0)
	s_setprio 1
	s_barrier
; #define PG8_STAGE(bufoff, gbase, voff) do { _Pragma("unroll") for (int _i = 0; _i < 2; ++_i) \
;         __builtin_amdgcn_global_load_lds((const unsigned*)((const char*)(gbase) + (voff)[_i]), (LAS unsigned*)(lds + (bufoff) + ldsw + _i * 8192), 16, 0, 0); } while (0)
; #define PG8_LDA(dst, b, h) do { _Pragma("unroll") for (int m = 0; m < 4; ++m) _Pragma("unroll") for (int k = 0; k < 2; ++k) dst[m][k] = *(const LAS bf16x8*)(lds + PG8_SA(b, h) + aoff + m * 2048 + k * 1024); } while (0)
; #define PG8_LDB(dst, b, h) do { _Pragma("unroll") for (int n = 0; n < 2; ++n) _Pragma("unroll") for (int k = 0; k < 2; ++k) dst[n][k] = *(const LAS bf16x8*)(lds + PG8_SB(b, h) + boff + n * 2048 + k * 1024); } while (0)
; #define PG8_MMA(ai, bj, At, Bt) do { __builtin_amdgcn_s_setprio(1); _Pragma("unroll") for (int m = 0; m < 4; ++m) _Pragma("unroll") for (int n = 0; n < 2; ++n) _Pragma("unroll") for (int k = 0; k < 2; ++k) \
;         acc[ai][bj][m][n] = __builtin_amdgcn_mfma_f32_16x16x32_bf16(Bt[n][k], At[m][k], acc[ai][bj][m][n], 0, 0, 0); __builtin_amdgcn_s_setprio(0); } while (0)
; #define PG8_WAIT_V(n) asm volatile("s_waitcnt vmcnt(" #n ")" ::: "memory")
; #define PG8_WAIT_L(n) asm volatile("s_waitcnt lgkmcnt(" #n ")" ::: "memory")
; #define PG8_BAR __builtin_amdgcn_s_barrier()
; #define PG8_SCHED __builtin_amdgcn_sched_barrier(0)
; template <class Epi, class Sched, int LDA, int LDB, bool ALIGN_EPI = true>
; __device__ __forceinline__ void gemm_phase(LAS unsigned char* lds, const Gemm g, const Sched& S, const Epi& E, int wave) {
;     ...
;             PG8_WAIT_V(8); PG8_WAIT_L(0); PG8_BAR; PG8_MMA(1, 0, At, B0); PG8_MMA(1, 1, At, B1); PG8_BAR; PG8_SCHED;
;             PG8_LDB(B0, 1, 0); PG8_LDB(B1, 1, 1); PG8_SCHED; PG8_LDA(At, 1, 0); PG8_STAGE(PG8_SA(0, 1), a2 + hstepA, voffA);
;             PG8_WAIT_V(8); PG8_WAIT_L(0); PG8_BAR; PG8_MMA(0, 0, At, B0); PG8_MMA(0, 1, At, B1); PG8_BAR; PG8_SCHED;
	v_mfma_f32_16x16x32_bf16 v[94:97], v[144:147], v[184:187], v[94:97]
	v_mfma_f32_16x16x32_bf16 v[94:97], v[148:151], v[188:191], v[94:97]
	v_mfma_f32_16x16x32_bf16 v[90:93], v[152:155], v[184:187], v[90:93]
	v_mfma_f32_16x16x32_bf16 v[90:93], v[156:159], v[188:191], v[90:93]
	v_mfma_f32_16x16x32_bf16 v[86:89], v[144:147], v[192:195], v[86:89]
	v_mfma_f32_16x16x32_bf16 v[86:89], v[148:151], v[196:199], v[86:89]
	v_mfma_f32_16x16x32_bf16 v[82:85], v[152:155], v[192:195], v[82:85]
	v_mfma_f32_16x16x32_bf16 v[82:85], v[156:159], v[196:199], v[82:85]
	v_mfma_f32_16x16x32_bf16 v[78:81], v[144:147], v[200:203], v[78:81]
	v_mfma_f32_16x16x32_bf16 v[78:81], v[148:151], v[204:207], v[78:81]
	v_mfma_f32_16x16x32_bf16 v[74:77], v[152:155], v[200:203], v[74:77]
	v_mfma_f32_16x16x32_bf16 v[74:77], v[156:159], v[204:207], v[74:77]
	v_mfma_f32_16x16x32_bf16 v[70:73], v[144:147], v[208:211], v[70:73]
	v_mfma_f32_16x16x32_bf16 v[70:73], v[148:151], v[212:215], v[70:73]
	v_mfma_f32_16x16x32_bf16 v[66:69], v[152:155], v[208:211], v[66:69]
	v_mfma_f32_16x16x32_bf16 v[66:69], v[156:159], v[212:215], v[66:69]
	v_mfma_f32_16x16x32_bf16 v[30:33], v[164:167], v[184:187], v[30:33]
	v_mfma_f32_16x16x32_bf16 v[30:33], v[168:171], v[188:191], v[30:33]
	v_mfma_f32_16x16x32_bf16 v[26:29], v[172:175], v[184:187], v[26:29]
	v_mfma_f32_16x16x32_bf16 v[26:29], v[180:183], v[188:191], v[26:29]
	v_mfma_f32_16x16x32_bf16 v[22:25], v[164:167], v[192:195], v[22:25]
	v_mfma_f32_16x16x32_bf16 v[22:25], v[168:171], v[196:199], v[22:25]
	v_mfma_f32_16x16x32_bf16 v[18:21], v[172:175], v[192:195], v[18:21]
	v_mfma_f32_16x16x32_bf16 v[18:21], v[180:183], v[196:199], v[18:21]
	v_mfma_f32_16x16x32_bf16 v[14:17], v[164:167], v[200:203], v[14:17]
	v_mfma_f32_16x16x32_bf16 v[14:17], v[168:171], v[204:207], v[14:17]
	v_mfma_f32_16x16x32_bf16 v[10:13], v[172:175], v[200:203], v[10:13]
	v_mfma_f32_16x16x32_bf16 v[10:13], v[180:183], v[204:207], v[10:13]
	v_mfma_f32_16x16x32_bf16 v[6:9], v[164:167], v[208:211], v[6:9]
	v_mfma_f32_16x16x32_bf16 v[6:9], v[168:171], v[212:215], v[6:9]
	v_mfma_f32_16x16x32_bf16 v[2:5], v[172:175], v[208:211], v[2:5]
	v_mfma_f32_16x16x32_bf16 v[2:5], v[180:183], v[212:215], v[2:5]
	s_barrier
	s_setprio 0
	ds_read_b128 v[184:187], v163 offset:32768
	ds_read_b128 v[188:191], v163 offset:33792
	ds_read_b128 v[192:195], v163 offset:34816
	ds_read_b128 v[196:199], v163 offset:35840
	ds_read_b128 v[200:203], v163 offset:36864
	ds_read_b128 v[204:207], v163 offset:37888
	ds_read_b128 v[208:211], v163 offset:38912
	ds_read_b128 v[212:215], v163 offset:39936
	s_add_i32 s64, 0, 0x18000
	v_add_u32_e32 v0, s64, v161
	s_add_i32 s65, 0, 0x1c000
	ds_read_b128 v[144:147], v0
	ds_read_b128 v[148:151], v0 offset:1024
	ds_read_b128 v[152:155], v0 offset:2048
	ds_read_b128 v[156:159], v0 offset:3072
	v_add_u32_e32 v0, s65, v161
	ds_read_b128 v[164:167], v0
	ds_read_b128 v[168:171], v0 offset:1024
	ds_read_b128 v[172:175], v0 offset:2048
	ds_read_b128 v[180:183], v0 offset:3072
	s_add_u32 s0, s28, 0x84000
	s_addc_u32 s1, s29, 0
	s_mov_b32 m0, s36
	v_lshl_add_u64 v[224:225], s[0:1], 0, v[130:131]
	global_load_lds_dwordx4 v[224:225], off
	v_lshl_add_u64 v[224:225], s[0:1], 0, v[134:135]
	s_mov_b32 m0, s37
	s_nop 0
	global_load_lds_dwordx4 v[224:225], off
	s_waitcnt vmcnt(8)
	s_waitcnt lgkmcnt(0)
	s_setprio 1
	s_barrier
	v_mfma_f32_16x16x32_bf16 v[126:129], v[144:147], v[184:187], v[126:129]
	v_mfma_f32_16x16x32_bf16 v[126:129], v[148:151], v[188:191], v[126:129]
	v_mfma_f32_16x16x32_bf16 v[122:125], v[152:155], v[184:187], v[122:125]
	v_mfma_f32_16x16x32_bf16 v[122:125], v[156:159], v[188:191], v[122:125]
	v_mfma_f32_16x16x32_bf16 v[118:121], v[144:147], v[192:195], v[118:121]
	v_mfma_f32_16x16x32_bf16 v[118:121], v[148:151], v[196:199], v[118:121]
	v_mfma_f32_16x16x32_bf16 v[114:117], v[152:155], v[192:195], v[114:117]
	v_mfma_f32_16x16x32_bf16 v[114:117], v[156:159], v[196:199], v[114:117]
	v_mfma_f32_16x16x32_bf16 v[110:113], v[144:147], v[200:203], v[110:113]
	v_mfma_f32_16x16x32_bf16 v[110:113], v[148:151], v[204:207], v[110:113]
	v_mfma_f32_16x16x32_bf16 v[106:109], v[152:155], v[200:203], v[106:109]
	v_mfma_f32_16x16x32_bf16 v[106:109], v[156:159], v[204:207], v[106:109]
	v_mfma_f32_16x16x32_bf16 v[102:105], v[144:147], v[208:211], v[102:105]
	v_mfma_f32_16x16x32_bf16 v[102:105], v[148:151], v[212:215], v[102:105]
	v_mfma_f32_16x16x32_bf16 v[98:101], v[152:155], v[208:211], v[98:101]
	v_mfma_f32_16x16x32_bf16 v[98:101], v[156:159], v[212:215], v[98:101]
	v_mfma_f32_16x16x32_bf16 v[62:65], v[164:167], v[184:187], v[62:65]
	v_mfma_f32_16x16x32_bf16 v[62:65], v[168:171], v[188:191], v[62:65]
	v_mfma_f32_16x16x32_bf16 v[58:61], v[172:175], v[184:187], v[58:61]
	v_mfma_f32_16x16x32_bf16 v[58:61], v[180:183], v[188:191], v[58:61]
	v_mfma_f32_16x16x32_bf16 v[54:57], v[164:167], v[192:195], v[54:57]
	v_mfma_f32_16x16x32_bf16 v[54:57], v[168:171], v[196:199], v[54:57]
	v_mfma_f32_16x16x32_bf16 v[50:53], v[172:175], v[192:195], v[50:53]
	v_mfma_f32_16x16x32_bf16 v[50:53], v[180:183], v[196:199], v[50:53]
	v_mfma_f32_16x16x32_bf16 v[46:49], v[164:167], v[200:203], v[46:49]
	v_mfma_f32_16x16x32_bf16 v[46:49], v[168:171], v[204:207], v[46:49]
	v_mfma_f32_16x16x32_bf16 v[42:45], v[172:175], v[200:203], v[42:45]
	v_mfma_f32_16x16x32_bf16 v[42:45], v[180:183], v[204:207], v[42:45]
	v_mfma_f32_16x16x32_bf16 v[38:41], v[164:167], v[208:211], v[38:41]
	v_mfma_f32_16x16x32_bf16 v[38:41], v[168:171], v[212:215], v[38:41]
	v_mfma_f32_16x16x32_bf16 v[34:37], v[172:175], v[208:211], v[34:37]
	v_mfma_f32_16x16x32_bf16 v[34:37], v[180:183], v[212:215], v[34:37]
	s_barrier
; #define PG8_STAGE(bufoff, gbase, voff) do { _Pragma("unroll") for (int _i = 0; _i < 2; ++_i) \
;         __builtin_amdgcn_global_load_lds((const unsigned*)((const char*)(gbase) + (voff)[_i]), (LAS unsigned*)(lds + (bufoff) + ldsw + _i * 8192), 16, 0, 0); } while (0)
; #define PG8_LDA(dst, b, h) do { _Pragma("unroll") for (int m = 0; m < 4; ++m) _Pragma("unroll") for (int k = 0; k < 2; ++k) dst[m][k] = *(const LAS bf16x8*)(lds + PG8_SA(b, h) + aoff + m * 2048 + k * 1024); } while (0)
; #define PG8_MMA(ai, bj, At, Bt) do { __builtin_amdgcn_s_setprio(1); _Pragma("unroll") for (int m = 0; m < 4; ++m) _Pragma("unroll") for (int n = 0; n < 2; ++n) _Pragma("unroll") for (int k = 0; k < 2; ++k) \
;         acc[ai][bj][m][n] = __builtin_amdgcn_mfma_f32_16x16x32_bf16(Bt[n][k], At[m][k], acc[ai][bj][m][n], 0, 0, 0); __builtin_amdgcn_s_setprio(0); } while (0)
; #define PG8_WAIT_V(n) asm volatile("s_waitcnt vmcnt(" #n ")" ::: "memory")
; #define PG8_WAIT_L(n) asm volatile("s_waitcnt lgkmcnt(" #n ")" ::: "memory")
; #define PG8_BAR __builtin_amdgcn_s_barrier()
; #define PG8_SCHED __builtin_amdgcn_sched_barrier(0)
; template <class Epi, class Sched, int LDA, int LDB, bool ALIGN_EPI = true>
; __device__ __forceinline__ void gemm_phase(LAS unsigned char* lds, const Gemm g, const Sched& S, const Epi& E, int wave) {
;     ...
;             PG8_LDA(At, 1, 1); PG8_STAGE(PG8_SB(1, 0), b3, voffB); PG8_STAGE(PG8_SB(1, 1), b3 + hstepB, voffB); PG8_STAGE(PG8_SA(1, 0), a3, voffA);
;             PG8_WAIT_V(8); PG8_WAIT_L(0); PG8_BAR; PG8_MMA(1, 0, At, B0); PG8_MMA(1, 1, At, B1); PG8_BAR; PG8_SCHED;
;         }
;         if constexpr (ALIGN_EPI) { if (wr == 0) PG8_BAR; }
	s_setprio 0
	s_add_i32 s0, s64, s61
	v_lshl_add_u64 v[216:217], v[216:217], 0, s[70:71]
	s_mov_b32 m0, s0
	ds_read_b128 v[184:187], v163 offset:49152
	ds_read_b128 v[188:191], v163 offset:50176
	ds_read_b128 v[192:195], v163 offset:51200
	ds_read_b128 v[196:199], v163 offset:52224
	ds_read_b128 v[200:203], v163 offset:53248
	ds_read_b128 v[204:207], v163 offset:54272
	ds_read_b128 v[208:211], v163 offset:55296
	ds_read_b128 v[212:215], v163 offset:56320
	global_load_lds_dwordx4 v[216:217], off
	s_add_i32 m0, s0, 0x2000
	s_add_u32 s0, s24, 0x80080
	v_lshl_add_u64 v[216:217], v[218:219], 0, s[70:71]
	s_addc_u32 s1, s25, 0
	s_add_i32 s24, s65, s61
	global_load_lds_dwordx4 v[216:217], off
	v_lshl_add_u64 v[216:217], s[0:1], 0, v[132:133]
	s_mov_b32 m0, s24
	s_nop 0
	global_load_lds_dwordx4 v[216:217], off
	v_lshl_add_u64 v[216:217], s[0:1], 0, v[136:137]
	s_add_i32 m0, s24, 0x2000
	s_nop 0
	global_load_lds_dwordx4 v[216:217], off
	v_lshl_add_u64 v[216:217], v[220:221], 0, s[70:71]
	s_mov_b32 m0, s38
	s_nop 0
	global_load_lds_dwordx4 v[216:217], off
	v_lshl_add_u64 v[216:217], v[222:223], 0, s[70:71]
	s_mov_b32 m0, s39
	s_nop 0
	global_load_lds_dwordx4 v[216:217], off
	s_waitcnt vmcnt(8)
	s_waitcnt lgkmcnt(0)
	s_setprio 1
	s_barrier
	v_mfma_f32_16x16x32_bf16 v[94:97], v[144:147], v[184:187], v[94:97]
	v_mfma_f32_16x16x32_bf16 v[94:97], v[148:151], v[188:191], v[94:97]
	v_mfma_f32_16x16x32_bf16 v[90:93], v[152:155], v[184:187], v[90:93]
	v_mfma_f32_16x16x32_bf16 v[90:93], v[156:159], v[188:191], v[90:93]
	v_mfma_f32_16x16x32_bf16 v[86:89], v[144:147], v[192:195], v[86:89]
	v_mfma_f32_16x16x32_bf16 v[86:89], v[148:151], v[196:199], v[86:89]
	v_mfma_f32_16x16x32_bf16 v[82:85], v[152:155], v[192:195], v[82:85]
	v_mfma_f32_16x16x32_bf16 v[82:85], v[156:159], v[196:199], v[82:85]
	v_mfma_f32_16x16x32_bf16 v[78:81], v[144:147], v[200:203], v[78:81]
	v_mfma_f32_16x16x32_bf16 v[78:81], v[148:151], v[204:207], v[78:81]
	v_mfma_f32_16x16x32_bf16 v[74:77], v[152:155], v[200:203], v[74:77]
	v_mfma_f32_16x16x32_bf16 v[74:77], v[156:159], v[204:207], v[74:77]
	v_mfma_f32_16x16x32_bf16 v[70:73], v[144:147], v[208:211], v[70:73]
	v_mfma_f32_16x16x32_bf16 v[70:73], v[148:151], v[212:215], v[70:73]
	v_mfma_f32_16x16x32_bf16 v[66:69], v[152:155], v[208:211], v[66:69]
	v_mfma_f32_16x16x32_bf16 v[66:69], v[156:159], v[212:215], v[66:69]
	v_mfma_f32_16x16x32_bf16 v[30:33], v[164:167], v[184:187], v[30:33]
	v_mfma_f32_16x16x32_bf16 v[30:33], v[168:171], v[188:191], v[30:33]
	v_mfma_f32_16x16x32_bf16 v[26:29], v[172:175], v[184:187], v[26:29]
	v_mfma_f32_16x16x32_bf16 v[26:29], v[180:183], v[188:191], v[26:29]
	v_mfma_f32_16x16x32_bf16 v[22:25], v[164:167], v[192:195], v[22:25]
	v_mfma_f32_16x16x32_bf16 v[22:25], v[168:171], v[196:199], v[22:25]
	v_mfma_f32_16x16x32_bf16 v[18:21], v[172:175], v[192:195], v[18:21]
	v_mfma_f32_16x16x32_bf16 v[18:21], v[180:183], v[196:199], v[18:21]
	v_mfma_f32_16x16x32_bf16 v[14:17], v[164:167], v[200:203], v[14:17]
	v_mfma_f32_16x16x32_bf16 v[14:17], v[168:171], v[204:207], v[14:17]
	v_mfma_f32_16x16x32_bf16 v[10:13], v[172:175], v[200:203], v[10:13]
	v_mfma_f32_16x16x32_bf16 v[10:13], v[180:183], v[204:207], v[10:13]
	v_mfma_f32_16x16x32_bf16 v[6:9], v[164:167], v[208:211], v[6:9]
	v_mfma_f32_16x16x32_bf16 v[6:9], v[168:171], v[212:215], v[6:9]
	v_mfma_f32_16x16x32_bf16 v[2:5], v[172:175], v[208:211], v[2:5]
	v_mfma_f32_16x16x32_bf16 v[2:5], v[180:183], v[212:215], v[2:5]
	s_barrier
	s_setprio 0
	s_add_i32 s59, s59, 2
	s_add_u32 s49, s49, 0x100
	s_addc_u32 s58, s58, 0
	s_cmp_gt_u32 s59, 29
	s_mov_b64 s[0:1], s[2:3]
	s_cbranch_scc0 .LBB0_2254
	v_readlane_b32 s0, v252, 14
	v_readlane_b32 s1, v252, 15
	s_and_b64 vcc, exec, s[0:1]
	s_cbranch_vccz .LBB0_2257
	s_barrier

; #define PG8_STAGE(bufoff, gbase, voff) do { _Pragma("unroll") for (int _i = 0; _i < 2; ++_i) \
;         __builtin_amdgcn_global_load_lds((const unsigned*)((const char*)(gbase) + (voff)[_i]), (LAS unsigned*)(lds + (bufoff) + ldsw + _i * 8192), 16, 0, 0); } while (0)
; #define PG8_LDA(dst, b, h) do { _Pragma("unroll") for (int m = 0; m < 4; ++m) _Pragma("unroll") for (int k = 0; k < 2; ++k) dst[m][k] = *(const LAS bf16x8*)(lds + PG8_SA(b, h) + aoff + m * 2048 + k * 1024); } while (0)
; #define PG8_LDB(dst, b, h) do { _Pragma("unroll") for (int n = 0; n < 2; ++n) _Pragma("unroll") for (int k = 0; k < 2; ++k) dst[n][k] = *(const LAS bf16x8*)(lds + PG8_SB(b, h) + boff + n * 2048 + k * 1024); } while (0)
; #define PG8_MMA(ai, bj, At, Bt) do { __builtin_amdgcn_s_setprio(1); _Pragma("unroll") for (int m = 0; m < 4; ++m) _Pragma("unroll") for (int n = 0; n < 2; ++n) _Pragma("unroll") for (int k = 0; k < 2; ++k) \
;         acc[ai][bj][m][n] = __builtin_amdgcn_mfma_f32_16x16x32_bf16(Bt[n][k], At[m][k], acc[ai][bj][m][n], 0, 0, 0); __builtin_amdgcn_s_setprio(0); } while (0)
; #define PG8_WAIT_V(n) asm volatile("s_waitcnt vmcnt(" #n ")" ::: "memory")
; #define PG8_WAIT_L(n) asm volatile("s_waitcnt lgkmcnt(" #n ")" ::: "memory")
; #define PG8_BAR __builtin_amdgcn_s_barrier()
; template <class Epi, class Sched, int LDA, int LDB, bool ALIGN_EPI = true>
; __device__ __forceinline__ void gemm_phase(LAS unsigned char* lds, const Gemm g, const Sched& S, const Epi& E, int wave) {
;     ...
;         for (int t = 0; t < nt; t += 2) {
;             const bool last = (t == nt - 2);
;             const char* a1 = cA + (size_t)(t + 1) * kstep;
;             const char* a2 = last ? nA : cA + (size_t)(t + 2) * kstep; const char* b2 = last ? nB : cB + (size_t)(t + 2) * kstep;
;             const char* a3 = a2 + kstep; const char* b3 = b2 + kstep;
;             PG8_LDB(B0, 0, 0); PG8_LDB(B1, 0, 1); PG8_SCHED; PG8_LDA(At, 0, 0); PG8_STAGE(PG8_SA(1, 1), a1 + hstepA, voffA);
;             PG8_WAIT_V(8); PG8_WAIT_L(0); PG8_BAR; PG8_MMA(0, 0, At, B0); PG8_MMA(0, 1, At, B1); PG8_BAR; PG8_SCHED;
;             PG8_LDA(At, 0, 1); PG8_STAGE(PG8_SB(0, 0), b2, voffB); PG8_STAGE(PG8_SB(0, 1), b2 + hstepB, voffB); PG8_STAGE(PG8_SA(0, 0), a2, voffA);
;             PG8_WAIT_V(8); PG8_WAIT_L(0); PG8_BAR; PG8_MMA(1, 0, At, B0); PG8_MMA(1, 1, At, B1); PG8_BAR; PG8_SCHED;
.LBB0_2415:
	ds_read_b128 v[184:187], v145
	ds_read_b128 v[188:191], v145 offset:1024
	ds_read_b128 v[192:195], v145 offset:2048
	ds_read_b128 v[196:199], v145 offset:3072
	ds_read_b128 v[200:203], v145 offset:4096
	ds_read_b128 v[204:207], v145 offset:5120
	ds_read_b128 v[208:211], v145 offset:6144
	ds_read_b128 v[212:215], v145 offset:7168
	s_add_u32 s12, s10, 0xfff80080
	s_addc_u32 s13, s11, -1
	s_add_i32 s39, 0, 0x10000
	s_cmp_eq_u32 s38, 28
	s_cselect_b32 s15, s1, s13
	s_cselect_b32 s14, s3, s12
	v_add_u32_e32 v140, s39, v143
	s_cselect_b32 s13, s7, s37
	s_cselect_b32 s12, s6, s36
	s_add_i32 s46, 0, 0x14000
	ds_read_b128 v[146:149], v140
	ds_read_b128 v[150:153], v140 offset:1024
	ds_read_b128 v[154:157], v140 offset:2048
	ds_read_b128 v[158:161], v140 offset:3072
	v_add_u32_e32 v140, s46, v143
	ds_read_b128 v[162:165], v140
	ds_read_b128 v[166:169], v140 offset:1024
	ds_read_b128 v[170:173], v140 offset:2048
	ds_read_b128 v[180:183], v140 offset:3072
	v_lshl_add_u64 v[140:141], s[10:11], 0, v[136:137]
	s_add_i32 m0, s18, 0xc000
	s_nop 0
	global_load_lds_dwordx4 v[140:141], off
	v_lshl_add_u64 v[140:141], s[10:11], 0, v[138:139]
	s_add_i32 m0, s18, 0xe000
	s_nop 0
	global_load_lds_dwordx4 v[140:141], off
	s_waitcnt vmcnt(8)
	s_waitcnt lgkmcnt(0)
	s_setprio 1
	s_barrier
	v_mfma_f32_16x16x32_bf16 v[126:129], v[146:149], v[184:187], v[126:129]
	v_mfma_f32_16x16x32_bf16 v[126:129], v[150:153], v[188:191], v[126:129]
	v_mfma_f32_16x16x32_bf16 v[122:125], v[154:157], v[184:187], v[122:125]
	v_mfma_f32_16x16x32_bf16 v[122:125], v[158:161], v[188:191], v[122:125]
	v_mfma_f32_16x16x32_bf16 v[114:117], v[146:149], v[192:195], v[114:117]
	v_mfma_f32_16x16x32_bf16 v[114:117], v[150:153], v[196:199], v[114:117]
	v_mfma_f32_16x16x32_bf16 v[106:109], v[154:157], v[192:195], v[106:109]
	v_mfma_f32_16x16x32_bf16 v[106:109], v[158:161], v[196:199], v[106:109]
	v_mfma_f32_16x16x32_bf16 v[98:101], v[146:149], v[200:203], v[98:101]
	v_mfma_f32_16x16x32_bf16 v[98:101], v[150:153], v[204:207], v[98:101]
	v_mfma_f32_16x16x32_bf16 v[90:93], v[154:157], v[200:203], v[90:93]
	v_mfma_f32_16x16x32_bf16 v[90:93], v[158:161], v[204:207], v[90:93]
	v_mfma_f32_16x16x32_bf16 v[82:85], v[146:149], v[208:211], v[82:85]
	v_mfma_f32_16x16x32_bf16 v[82:85], v[150:153], v[212:215], v[82:85]
	v_mfma_f32_16x16x32_bf16 v[74:77], v[154:157], v[208:211], v[74:77]
	v_mfma_f32_16x16x32_bf16 v[74:77], v[158:161], v[212:215], v[74:77]
	v_mfma_f32_16x16x32_bf16 v[118:121], v[162:165], v[184:187], v[118:121]
	v_mfma_f32_16x16x32_bf16 v[118:121], v[166:169], v[188:191], v[118:121]
	v_mfma_f32_16x16x32_bf16 v[110:113], v[170:173], v[184:187], v[110:113]
	v_mfma_f32_16x16x32_bf16 v[110:113], v[180:183], v[188:191], v[110:113]
	v_mfma_f32_16x16x32_bf16 v[102:105], v[162:165], v[192:195], v[102:105]
	v_mfma_f32_16x16x32_bf16 v[102:105], v[166:169], v[196:199], v[102:105]
	v_mfma_f32_16x16x32_bf16 v[94:97], v[170:173], v[192:195], v[94:97]
	v_mfma_f32_16x16x32_bf16 v[94:97], v[180:183], v[196:199], v[94:97]
	v_mfma_f32_16x16x32_bf16 v[86:89], v[162:165], v[200:203], v[86:89]
	v_mfma_f32_16x16x32_bf16 v[86:89], v[166:169], v[204:207], v[86:89]
	v_mfma_f32_16x16x32_bf16 v[78:81], v[170:173], v[200:203], v[78:81]
	v_mfma_f32_16x16x32_bf16 v[78:81], v[180:183], v[204:207], v[78:81]
	v_mfma_f32_16x16x32_bf16 v[70:73], v[162:165], v[208:211], v[70:73]
	v_mfma_f32_16x16x32_bf16 v[70:73], v[166:169], v[212:215], v[70:73]
	v_mfma_f32_16x16x32_bf16 v[66:69], v[170:173], v[208:211], v[66:69]
	v_mfma_f32_16x16x32_bf16 v[66:69], v[180:183], v[212:215], v[66:69]
	s_barrier
	s_setprio 0
	s_add_i32 s39, s39, s47
	v_lshl_add_u64 v[140:141], s[12:13], 0, v[0:1]
	s_mov_b32 m0, s39
	ds_read_b128 v[184:187], v145 offset:16384
	ds_read_b128 v[188:191], v145 offset:17408
	ds_read_b128 v[192:195], v145 offset:18432
	ds_read_b128 v[196:199], v145 offset:19456
	ds_read_b128 v[200:203], v145 offset:20480
	ds_read_b128 v[204:207], v145 offset:21504
	ds_read_b128 v[208:211], v145 offset:22528
	ds_read_b128 v[212:215], v145 offset:23552
	global_load_lds_dwordx4 v[140:141], off
	s_add_i32 m0, s39, 0x2000
	s_add_u32 s44, s12, 0x84000
	v_lshl_add_u64 v[174:175], s[12:13], 0, v[134:135]
	s_addc_u32 s45, s13, 0
	s_add_i32 s39, s46, s47
	global_load_lds_dwordx4 v[174:175], off
	v_lshl_add_u64 v[216:217], s[44:45], 0, v[0:1]
	s_mov_b32 m0, s39
	v_lshl_add_u64 v[218:219], s[14:15], 0, v[132:133]
	global_load_lds_dwordx4 v[216:217], off
	v_lshl_add_u64 v[216:217], s[44:45], 0, v[134:135]
	s_add_i32 m0, s39, 0x2000
	s_nop 0
	global_load_lds_dwordx4 v[216:217], off
	v_lshl_add_u64 v[216:217], s[14:15], 0, v[130:131]
	s_mov_b32 m0, s18
	s_nop 0
	global_load_lds_dwordx4 v[216:217], off
	s_mov_b32 m0, s19
	s_nop 0
	global_load_lds_dwordx4 v[218:219], off
	s_waitcnt vmcnt(8)
	s_waitcnt lgkmcnt(0)
	s_setprio 1
	s_barrier
; #define PG8_STAGE(bufoff, gbase, voff) do { _Pragma("unroll") for (int _i = 0; _i < 2; ++_i) \
;         __builtin_amdgcn_global_load_lds((const unsigned*)((const char*)(gbase) + (voff)[_i]), (LAS unsigned*)(lds + (bufoff) + ldsw + _i * 8192), 16, 0, 0); } while (0)
; #define PG8_LDA(dst, b, h) do { _Pragma("unroll") for (int m = 0; m < 4; ++m) _Pragma("unroll") for (int k = 0; k < 2; ++k) dst[m][k] = *(const LAS bf16x8*)(lds + PG8_SA(b, h) + aoff + m * 2048 + k * 1024); } while (0)
; #define PG8_LDB(dst, b, h) do { _Pragma("unroll") for (int n = 0; n < 2; ++n) _Pragma("unroll") for (int k = 0; k < 2; ++k) dst[n][k] = *(const LAS bf16x8*)(lds + PG8_SB(b, h) + boff + n * 2048 + k * 1024); } while (0)
; #define PG8_MMA(ai, bj, At, Bt) do { __builtin_amdgcn_s_setprio(1); _Pragma("unroll") for (int m = 0; m < 4; ++m) _Pragma("unroll") for (int n = 0; n < 2; ++n) _Pragma("unroll") for (int k = 0; k < 2; ++k) \
;         acc[ai][bj][m][n] = __builtin_amdgcn_mfma_f32_16x16x32_bf16(Bt[n][k], At[m][k], acc[ai][bj][m][n], 0, 0, 0); __builtin_amdgcn_s_setprio(0); } while (0)
; #define PG8_WAIT_V(n) asm volatile("s_waitcnt vmcnt(" #n ")" ::: "memory")
; #define PG8_WAIT_L(n) asm volatile("s_waitcnt lgkmcnt(" #n ")" ::: "memory")
; #define PG8_BAR __builtin_amdgcn_s_barrier()
; #define PG8_SCHED __builtin_amdgcn_sched_barrier(0)
; template <class Epi, class Sched, int LDA, int LDB, bool ALIGN_EPI = true>
; __device__ __forceinline__ void gemm_phase(LAS unsigned char* lds, const Gemm g, const Sched& S, const Epi& E, int wave) {
;     ...
;             PG8_WAIT_V(8); PG8_WAIT_L(0); PG8_BAR; PG8_MMA(1, 0, At, B0); PG8_MMA(1, 1, At, B1); PG8_BAR; PG8_SCHED;
;             PG8_LDB(B0, 1, 0); PG8_LDB(B1, 1, 1); PG8_SCHED; PG8_LDA(At, 1, 0); PG8_STAGE(PG8_SA(0, 1), a2 + hstepA, voffA);
;             PG8_WAIT_V(8); PG8_WAIT_L(0); PG8_BAR; PG8_MMA(0, 0, At, B0); PG8_MMA(0, 1, At, B1); PG8_BAR; PG8_SCHED;
	v_mfma_f32_16x16x32_bf16 v[62:65], v[146:149], v[184:187], v[62:65]
	v_mfma_f32_16x16x32_bf16 v[62:65], v[150:153], v[188:191], v[62:65]
	v_mfma_f32_16x16x32_bf16 v[58:61], v[154:157], v[184:187], v[58:61]
	v_mfma_f32_16x16x32_bf16 v[58:61], v[158:161], v[188:191], v[58:61]
	v_mfma_f32_16x16x32_bf16 v[50:53], v[146:149], v[192:195], v[50:53]
	v_mfma_f32_16x16x32_bf16 v[50:53], v[150:153], v[196:199], v[50:53]
	v_mfma_f32_16x16x32_bf16 v[42:45], v[154:157], v[192:195], v[42:45]
	v_mfma_f32_16x16x32_bf16 v[42:45], v[158:161], v[196:199], v[42:45]
	v_mfma_f32_16x16x32_bf16 v[34:37], v[146:149], v[200:203], v[34:37]
	v_mfma_f32_16x16x32_bf16 v[34:37], v[150:153], v[204:207], v[34:37]
	v_mfma_f32_16x16x32_bf16 v[26:29], v[154:157], v[200:203], v[26:29]
	v_mfma_f32_16x16x32_bf16 v[26:29], v[158:161], v[204:207], v[26:29]
	v_mfma_f32_16x16x32_bf16 v[18:21], v[146:149], v[208:211], v[18:21]
	v_mfma_f32_16x16x32_bf16 v[18:21], v[150:153], v[212:215], v[18:21]
	v_mfma_f32_16x16x32_bf16 v[10:13], v[154:157], v[208:211], v[10:13]
	v_mfma_f32_16x16x32_bf16 v[10:13], v[158:161], v[212:215], v[10:13]
	v_mfma_f32_16x16x32_bf16 v[54:57], v[162:165], v[184:187], v[54:57]
	v_mfma_f32_16x16x32_bf16 v[54:57], v[166:169], v[188:191], v[54:57]
	v_mfma_f32_16x16x32_bf16 v[46:49], v[170:173], v[184:187], v[46:49]
	v_mfma_f32_16x16x32_bf16 v[46:49], v[180:183], v[188:191], v[46:49]
	v_mfma_f32_16x16x32_bf16 v[38:41], v[162:165], v[192:195], v[38:41]
	v_mfma_f32_16x16x32_bf16 v[38:41], v[166:169], v[196:199], v[38:41]
	v_mfma_f32_16x16x32_bf16 v[30:33], v[170:173], v[192:195], v[30:33]
	v_mfma_f32_16x16x32_bf16 v[30:33], v[180:183], v[196:199], v[30:33]
	v_mfma_f32_16x16x32_bf16 v[22:25], v[162:165], v[200:203], v[22:25]
	v_mfma_f32_16x16x32_bf16 v[22:25], v[166:169], v[204:207], v[22:25]
	v_mfma_f32_16x16x32_bf16 v[14:17], v[170:173], v[200:203], v[14:17]
	v_mfma_f32_16x16x32_bf16 v[14:17], v[180:183], v[204:207], v[14:17]
	v_mfma_f32_16x16x32_bf16 v[6:9], v[162:165], v[208:211], v[6:9]
	v_mfma_f32_16x16x32_bf16 v[6:9], v[166:169], v[212:215], v[6:9]
	v_mfma_f32_16x16x32_bf16 v[2:5], v[170:173], v[208:211], v[2:5]
	v_mfma_f32_16x16x32_bf16 v[2:5], v[180:183], v[212:215], v[2:5]
	s_barrier
	s_setprio 0
	ds_read_b128 v[184:187], v145 offset:32768
	ds_read_b128 v[188:191], v145 offset:33792
	ds_read_b128 v[192:195], v145 offset:34816
	ds_read_b128 v[196:199], v145 offset:35840
	ds_read_b128 v[200:203], v145 offset:36864
	ds_read_b128 v[204:207], v145 offset:37888
	ds_read_b128 v[208:211], v145 offset:38912
	ds_read_b128 v[212:215], v145 offset:39936
	s_add_i32 s39, 0, 0x18000
	s_add_i32 s44, 0, 0x1c000
	v_add_u32_e32 v158, s39, v143
	v_add_u32_e32 v180, s44, v143
	ds_read_b128 v[146:149], v158
	ds_read_b128 v[150:153], v158 offset:1024
	ds_read_b128 v[154:157], v158 offset:2048
	ds_read_b128 v[158:161], v158 offset:3072
	ds_read_b128 v[162:165], v180
	ds_read_b128 v[166:169], v180 offset:1024
	ds_read_b128 v[170:173], v180 offset:2048
	ds_read_b128 v[180:183], v180 offset:3072
	s_add_u32 s14, s14, 0x80000
	s_addc_u32 s15, s15, 0
	s_mov_b32 m0, s24
	v_lshl_add_u64 v[220:221], s[14:15], 0, v[130:131]
	global_load_lds_dwordx4 v[220:221], off
	v_lshl_add_u64 v[220:221], s[14:15], 0, v[132:133]
	s_mov_b32 m0, s25
	s_nop 0
	global_load_lds_dwordx4 v[220:221], off
	s_waitcnt vmcnt(8)
	s_waitcnt lgkmcnt(0)
	s_setprio 1
	s_barrier
	v_mfma_f32_16x16x32_bf16 v[126:129], v[146:149], v[184:187], v[126:129]
	v_mfma_f32_16x16x32_bf16 v[126:129], v[150:153], v[188:191], v[126:129]
	v_mfma_f32_16x16x32_bf16 v[122:125], v[154:157], v[184:187], v[122:125]
	v_mfma_f32_16x16x32_bf16 v[122:125], v[158:161], v[188:191], v[122:125]
	v_mfma_f32_16x16x32_bf16 v[114:117], v[146:149], v[192:195], v[114:117]
	v_mfma_f32_16x16x32_bf16 v[114:117], v[150:153], v[196:199], v[114:117]
	v_mfma_f32_16x16x32_bf16 v[106:109], v[154:157], v[192:195], v[106:109]
	v_mfma_f32_16x16x32_bf16 v[106:109], v[158:161], v[196:199], v[106:109]
	v_mfma_f32_16x16x32_bf16 v[98:101], v[146:149], v[200:203], v[98:101]
	v_mfma_f32_16x16x32_bf16 v[98:101], v[150:153], v[204:207], v[98:101]
	v_mfma_f32_16x16x32_bf16 v[90:93], v[154:157], v[200:203], v[90:93]
	v_mfma_f32_16x16x32_bf16 v[90:93], v[158:161], v[204:207], v[90:93]
	v_mfma_f32_16x16x32_bf16 v[82:85], v[146:149], v[208:211], v[82:85]
	v_mfma_f32_16x16x32_bf16 v[82:85], v[150:153], v[212:215], v[82:85]
	v_mfma_f32_16x16x32_bf16 v[74:77], v[154:157], v[208:211], v[74:77]
	v_mfma_f32_16x16x32_bf16 v[74:77], v[158:161], v[212:215], v[74:77]
	v_mfma_f32_16x16x32_bf16 v[118:121], v[162:165], v[184:187], v[118:121]
	v_mfma_f32_16x16x32_bf16 v[118:121], v[166:169], v[188:191], v[118:121]
	v_mfma_f32_16x16x32_bf16 v[110:113], v[170:173], v[184:187], v[110:113]
	v_mfma_f32_16x16x32_bf16 v[110:113], v[180:183], v[188:191], v[110:113]
	v_mfma_f32_16x16x32_bf16 v[102:105], v[162:165], v[192:195], v[102:105]
	v_mfma_f32_16x16x32_bf16 v[102:105], v[166:169], v[196:199], v[102:105]
	v_mfma_f32_16x16x32_bf16 v[94:97], v[170:173], v[192:195], v[94:97]
	v_mfma_f32_16x16x32_bf16 v[94:97], v[180:183], v[196:199], v[94:97]
	v_mfma_f32_16x16x32_bf16 v[86:89], v[162:165], v[200:203], v[86:89]
	v_mfma_f32_16x16x32_bf16 v[86:89], v[166:169], v[204:207], v[86:89]
	v_mfma_f32_16x16x32_bf16 v[78:81], v[170:173], v[200:203], v[78:81]
	v_mfma_f32_16x16x32_bf16 v[78:81], v[180:183], v[204:207], v[78:81]
	v_mfma_f32_16x16x32_bf16 v[70:73], v[162:165], v[208:211], v[70:73]
	v_mfma_f32_16x16x32_bf16 v[70:73], v[166:169], v[212:215], v[70:73]
	v_mfma_f32_16x16x32_bf16 v[66:69], v[170:173], v[208:211], v[66:69]
	v_mfma_f32_16x16x32_bf16 v[66:69], v[180:183], v[212:215], v[66:69]
	s_barrier
; #define PG8_STAGE(bufoff, gbase, voff) do { _Pragma("unroll") for (int _i = 0; _i < 2; ++_i) \
;         __builtin_amdgcn_global_load_lds((const unsigned*)((const char*)(gbase) + (voff)[_i]), (LAS unsigned*)(lds + (bufoff) + ldsw + _i * 8192), 16, 0, 0); } while (0)
; #define PG8_LDA(dst, b, h) do { _Pragma("unroll") for (int m = 0; m < 4; ++m) _Pragma("unroll") for (int k = 0; k < 2; ++k) dst[m][k] = *(const LAS bf16x8*)(lds + PG8_SA(b, h) + aoff + m * 2048 + k * 1024); } while (0)
; #define PG8_MMA(ai, bj, At, Bt) do { __builtin_amdgcn_s_setprio(1); _Pragma("unroll") for (int m = 0; m < 4; ++m) _Pragma("unroll") for (int n = 0; n < 2; ++n) _Pragma("unroll") for (int k = 0; k < 2; ++k) \
;         acc[ai][bj][m][n] = __builtin_amdgcn_mfma_f32_16x16x32_bf16(Bt[n][k], At[m][k], acc[ai][bj][m][n], 0, 0, 0); __builtin_amdgcn_s_setprio(0); } while (0)
; #define PG8_WAIT_V(n) asm volatile("s_waitcnt vmcnt(" #n ")" ::: "memory")
; #define PG8_WAIT_L(n) asm volatile("s_waitcnt lgkmcnt(" #n ")" ::: "memory")
; #define PG8_BAR __builtin_amdgcn_s_barrier()
; #define PG8_SCHED __builtin_amdgcn_sched_barrier(0)
; template <class Epi, class Sched, int LDA, int LDB, bool ALIGN_EPI = true>
; __device__ __forceinline__ void gemm_phase(LAS unsigned char* lds, const Gemm g, const Sched& S, const Epi& E, int wave) {
;     ...
;             PG8_LDA(At, 1, 1); PG8_STAGE(PG8_SB(1, 0), b3, voffB); PG8_STAGE(PG8_SB(1, 1), b3 + hstepB, voffB); PG8_STAGE(PG8_SA(1, 0), a3, voffA);
;             PG8_WAIT_V(8); PG8_WAIT_L(0); PG8_BAR; PG8_MMA(1, 0, At, B0); PG8_MMA(1, 1, At, B1); PG8_BAR; PG8_SCHED;
;         }
;         if constexpr (ALIGN_EPI) { if (wr == 0) PG8_BAR; }
	s_setprio 0
	s_add_i32 s14, s39, s47
	v_lshl_add_u64 v[140:141], v[140:141], 0, s[48:49]
	s_mov_b32 m0, s14
	ds_read_b128 v[184:187], v145 offset:49152
	ds_read_b128 v[188:191], v145 offset:50176
	ds_read_b128 v[192:195], v145 offset:51200
	ds_read_b128 v[196:199], v145 offset:52224
	ds_read_b128 v[200:203], v145 offset:53248
	ds_read_b128 v[204:207], v145 offset:54272
	ds_read_b128 v[208:211], v145 offset:55296
	ds_read_b128 v[212:215], v145 offset:56320
	global_load_lds_dwordx4 v[140:141], off
	s_add_i32 m0, s14, 0x2000
	s_add_u32 s12, s12, 0x84080
	v_lshl_add_u64 v[140:141], v[174:175], 0, s[48:49]
	s_addc_u32 s13, s13, 0
	s_add_i32 s14, s44, s47
	global_load_lds_dwordx4 v[140:141], off
	v_lshl_add_u64 v[140:141], s[12:13], 0, v[0:1]
	s_mov_b32 m0, s14
	s_nop 0
	global_load_lds_dwordx4 v[140:141], off
	v_lshl_add_u64 v[140:141], s[12:13], 0, v[134:135]
	s_add_i32 m0, s14, 0x2000
	s_nop 0
	global_load_lds_dwordx4 v[140:141], off
	v_lshl_add_u64 v[140:141], v[216:217], 0, s[48:49]
	s_mov_b32 m0, s26
	s_nop 0
	global_load_lds_dwordx4 v[140:141], off
	v_lshl_add_u64 v[140:141], v[218:219], 0, s[48:49]
	s_mov_b32 m0, s27
	s_nop 0
	global_load_lds_dwordx4 v[140:141], off
	s_waitcnt vmcnt(8)
	s_waitcnt lgkmcnt(0)
	s_setprio 1
	s_barrier
	v_mfma_f32_16x16x32_bf16 v[62:65], v[146:149], v[184:187], v[62:65]
	v_mfma_f32_16x16x32_bf16 v[62:65], v[150:153], v[188:191], v[62:65]
	v_mfma_f32_16x16x32_bf16 v[58:61], v[154:157], v[184:187], v[58:61]
	v_mfma_f32_16x16x32_bf16 v[58:61], v[158:161], v[188:191], v[58:61]
	v_mfma_f32_16x16x32_bf16 v[50:53], v[146:149], v[192:195], v[50:53]
	v_mfma_f32_16x16x32_bf16 v[50:53], v[150:153], v[196:199], v[50:53]
	v_mfma_f32_16x16x32_bf16 v[42:45], v[154:157], v[192:195], v[42:45]
	v_mfma_f32_16x16x32_bf16 v[42:45], v[158:161], v[196:199], v[42:45]
	v_mfma_f32_16x16x32_bf16 v[34:37], v[146:149], v[200:203], v[34:37]
	v_mfma_f32_16x16x32_bf16 v[34:37], v[150:153], v[204:207], v[34:37]
	v_mfma_f32_16x16x32_bf16 v[26:29], v[154:157], v[200:203], v[26:29]
	v_mfma_f32_16x16x32_bf16 v[26:29], v[158:161], v[204:207], v[26:29]
	v_mfma_f32_16x16x32_bf16 v[18:21], v[146:149], v[208:211], v[18:21]
	v_mfma_f32_16x16x32_bf16 v[18:21], v[150:153], v[212:215], v[18:21]
	v_mfma_f32_16x16x32_bf16 v[10:13], v[154:157], v[208:211], v[10:13]
	v_mfma_f32_16x16x32_bf16 v[10:13], v[158:161], v[212:215], v[10:13]
	v_mfma_f32_16x16x32_bf16 v[54:57], v[162:165], v[184:187], v[54:57]
	v_mfma_f32_16x16x32_bf16 v[54:57], v[166:169], v[188:191], v[54:57]
	v_mfma_f32_16x16x32_bf16 v[46:49], v[170:173], v[184:187], v[46:49]
	v_mfma_f32_16x16x32_bf16 v[46:49], v[180:183], v[188:191], v[46:49]
	v_mfma_f32_16x16x32_bf16 v[38:41], v[162:165], v[192:195], v[38:41]
	v_mfma_f32_16x16x32_bf16 v[38:41], v[166:169], v[196:199], v[38:41]
	v_mfma_f32_16x16x32_bf16 v[30:33], v[170:173], v[192:195], v[30:33]
	v_mfma_f32_16x16x32_bf16 v[30:33], v[180:183], v[196:199], v[30:33]
	v_mfma_f32_16x16x32_bf16 v[22:25], v[162:165], v[200:203], v[22:25]
	v_mfma_f32_16x16x32_bf16 v[22:25], v[166:169], v[204:207], v[22:25]
	v_mfma_f32_16x16x32_bf16 v[14:17], v[170:173], v[200:203], v[14:17]
	v_mfma_f32_16x16x32_bf16 v[14:17], v[180:183], v[204:207], v[14:17]
	v_mfma_f32_16x16x32_bf16 v[6:9], v[162:165], v[208:211], v[6:9]
	v_mfma_f32_16x16x32_bf16 v[6:9], v[166:169], v[212:215], v[6:9]
	v_mfma_f32_16x16x32_bf16 v[2:5], v[170:173], v[208:211], v[2:5]
	v_mfma_f32_16x16x32_bf16 v[2:5], v[180:183], v[212:215], v[2:5]
	s_barrier
	s_setprio 0
	s_add_i32 s38, s38, 2
	s_add_u32 s10, s10, 0x100
	s_addc_u32 s11, s11, 0
	s_add_u32 s36, s36, 0x100
	s_addc_u32 s37, s37, 0
	s_cmp_gt_u32 s38, 29
	s_cbranch_scc0 .LBB0_2415
	v_readlane_b32 s10, v252, 14
	v_readlane_b32 s11, v252, 15
	s_and_b64 vcc, exec, s[10:11]
	s_cbranch_vccz .LBB0_2418
	s_barrier

; #define PG8_STAGE(bufoff, gbase, voff) do { _Pragma("unroll") for (int _i = 0; _i < 2; ++_i) \
;         __builtin_amdgcn_global_load_lds((const unsigned*)((const char*)(gbase) + (voff)[_i]), (LAS unsigned*)(lds + (bufoff) + ldsw + _i * 8192), 16, 0, 0); } while (0)
; #define PG8_LDA(dst, b, h) do { _Pragma("unroll") for (int m = 0; m < 4; ++m) _Pragma("unroll") for (int k = 0; k < 2; ++k) dst[m][k] = *(const LAS bf16x8*)(lds + PG8_SA(b, h) + aoff + m * 2048 + k * 1024); } while (0)
; #define PG8_LDB(dst, b, h) do { _Pragma("unroll") for (int n = 0; n < 2; ++n) _Pragma("unroll") for (int k = 0; k < 2; ++k) dst[n][k] = *(const LAS bf16x8*)(lds + PG8_SB(b, h) + boff + n * 2048 + k * 1024); } while (0)
; #define PG8_MMA(ai, bj, At, Bt) do { __builtin_amdgcn_s_setprio(1); _Pragma("unroll") for (int m = 0; m < 4; ++m) _Pragma("unroll") for (int n = 0; n < 2; ++n) _Pragma("unroll") for (int k = 0; k < 2; ++k) \
;         acc[ai][bj][m][n] = __builtin_amdgcn_mfma_f32_16x16x32_bf16(Bt[n][k], At[m][k], acc[ai][bj][m][n], 0, 0, 0); __builtin_amdgcn_s_setprio(0); } while (0)
; #define PG8_WAIT_V(n) asm volatile("s_waitcnt vmcnt(" #n ")" ::: "memory")
; #define PG8_WAIT_L(n) asm volatile("s_waitcnt lgkmcnt(" #n ")" ::: "memory")
; #define PG8_BAR __builtin_amdgcn_s_barrier()
; template <class Epi, class Sched, int LDA, int LDB, bool ALIGN_EPI = true>
; __device__ __forceinline__ void gemm_phase(LAS unsigned char* lds, const Gemm g, const Sched& S, const Epi& E, int wave) {
;     ...
;         for (int t = 0; t < nt; t += 2) {
;             const bool last = (t == nt - 2);
;             const char* a1 = cA + (size_t)(t + 1) * kstep;
;             const char* a2 = last ? nA : cA + (size_t)(t + 2) * kstep; const char* b2 = last ? nB : cB + (size_t)(t + 2) * kstep;
;             const char* a3 = a2 + kstep; const char* b3 = b2 + kstep;
;             PG8_LDB(B0, 0, 0); PG8_LDB(B1, 0, 1); PG8_SCHED; PG8_LDA(At, 0, 0); PG8_STAGE(PG8_SA(1, 1), a1 + hstepA, voffA);
;             PG8_WAIT_V(8); PG8_WAIT_L(0); PG8_BAR; PG8_MMA(0, 0, At, B0); PG8_MMA(0, 1, At, B1); PG8_BAR; PG8_SCHED;
;             PG8_LDA(At, 0, 1); PG8_STAGE(PG8_SB(0, 0), b2, voffB); PG8_STAGE(PG8_SB(0, 1), b2 + hstepB, voffB); PG8_STAGE(PG8_SA(0, 0), a2, voffA);
;             PG8_WAIT_V(8); PG8_WAIT_L(0); PG8_BAR; PG8_MMA(1, 0, At, B0); PG8_MMA(1, 1, At, B1); PG8_BAR; PG8_SCHED;
.LBB0_2513:
	ds_read_b128 v[184:187], v145
	ds_read_b128 v[188:191], v145 offset:1024
	ds_read_b128 v[192:195], v145 offset:2048
	ds_read_b128 v[196:199], v145 offset:3072
	ds_read_b128 v[200:203], v145 offset:4096
	ds_read_b128 v[204:207], v145 offset:5120
	ds_read_b128 v[208:211], v145 offset:6144
	ds_read_b128 v[212:215], v145 offset:7168
	s_add_u32 s14, s12, 0xfff80080
	s_addc_u32 s15, s13, -1
	s_add_i32 s44, 0, 0x10000
	s_cmp_eq_u32 s39, 28
	s_cselect_b32 s17, s1, s15
	s_cselect_b32 s16, s3, s14
	v_add_u32_e32 v140, s44, v143
	s_cselect_b32 s15, s9, s38
	s_cselect_b32 s14, s8, s37
	s_add_i32 s46, 0, 0x14000
	ds_read_b128 v[146:149], v140
	ds_read_b128 v[150:153], v140 offset:1024
	ds_read_b128 v[154:157], v140 offset:2048
	ds_read_b128 v[158:161], v140 offset:3072
	v_add_u32_e32 v140, s46, v143
	ds_read_b128 v[162:165], v140
	ds_read_b128 v[166:169], v140 offset:1024
	ds_read_b128 v[170:173], v140 offset:2048
	ds_read_b128 v[180:183], v140 offset:3072
	v_lshl_add_u64 v[140:141], s[12:13], 0, v[136:137]
	s_add_i32 m0, s24, 0xc000
	s_nop 0
	global_load_lds_dwordx4 v[140:141], off
	v_lshl_add_u64 v[140:141], s[12:13], 0, v[138:139]
	s_add_i32 m0, s24, 0xe000
	s_nop 0
	global_load_lds_dwordx4 v[140:141], off
	s_waitcnt vmcnt(8)
	s_waitcnt lgkmcnt(0)
	s_setprio 1
	s_barrier
	v_mfma_f32_16x16x32_bf16 v[126:129], v[146:149], v[184:187], v[126:129]
	v_mfma_f32_16x16x32_bf16 v[126:129], v[150:153], v[188:191], v[126:129]
	v_mfma_f32_16x16x32_bf16 v[122:125], v[154:157], v[184:187], v[122:125]
	v_mfma_f32_16x16x32_bf16 v[122:125], v[158:161], v[188:191], v[122:125]
	v_mfma_f32_16x16x32_bf16 v[114:117], v[146:149], v[192:195], v[114:117]
	v_mfma_f32_16x16x32_bf16 v[114:117], v[150:153], v[196:199], v[114:117]
	v_mfma_f32_16x16x32_bf16 v[106:109], v[154:157], v[192:195], v[106:109]
	v_mfma_f32_16x16x32_bf16 v[106:109], v[158:161], v[196:199], v[106:109]
	v_mfma_f32_16x16x32_bf16 v[98:101], v[146:149], v[200:203], v[98:101]
	v_mfma_f32_16x16x32_bf16 v[98:101], v[150:153], v[204:207], v[98:101]
	v_mfma_f32_16x16x32_bf16 v[90:93], v[154:157], v[200:203], v[90:93]
	v_mfma_f32_16x16x32_bf16 v[90:93], v[158:161], v[204:207], v[90:93]
	v_mfma_f32_16x16x32_bf16 v[82:85], v[146:149], v[208:211], v[82:85]
	v_mfma_f32_16x16x32_bf16 v[82:85], v[150:153], v[212:215], v[82:85]
	v_mfma_f32_16x16x32_bf16 v[74:77], v[154:157], v[208:211], v[74:77]
	v_mfma_f32_16x16x32_bf16 v[74:77], v[158:161], v[212:215], v[74:77]
	v_mfma_f32_16x16x32_bf16 v[118:121], v[162:165], v[184:187], v[118:121]
	v_mfma_f32_16x16x32_bf16 v[118:121], v[166:169], v[188:191], v[118:121]
	v_mfma_f32_16x16x32_bf16 v[110:113], v[170:173], v[184:187], v[110:113]
	v_mfma_f32_16x16x32_bf16 v[110:113], v[180:183], v[188:191], v[110:113]
	v_mfma_f32_16x16x32_bf16 v[102:105], v[162:165], v[192:195], v[102:105]
	v_mfma_f32_16x16x32_bf16 v[102:105], v[166:169], v[196:199], v[102:105]
	v_mfma_f32_16x16x32_bf16 v[94:97], v[170:173], v[192:195], v[94:97]
	v_mfma_f32_16x16x32_bf16 v[94:97], v[180:183], v[196:199], v[94:97]
	v_mfma_f32_16x16x32_bf16 v[86:89], v[162:165], v[200:203], v[86:89]
	v_mfma_f32_16x16x32_bf16 v[86:89], v[166:169], v[204:207], v[86:89]
	v_mfma_f32_16x16x32_bf16 v[78:81], v[170:173], v[200:203], v[78:81]
	v_mfma_f32_16x16x32_bf16 v[78:81], v[180:183], v[204:207], v[78:81]
	v_mfma_f32_16x16x32_bf16 v[70:73], v[162:165], v[208:211], v[70:73]
	v_mfma_f32_16x16x32_bf16 v[70:73], v[166:169], v[212:215], v[70:73]
	v_mfma_f32_16x16x32_bf16 v[66:69], v[170:173], v[208:211], v[66:69]
	v_mfma_f32_16x16x32_bf16 v[66:69], v[180:183], v[212:215], v[66:69]
	s_barrier
	s_setprio 0
	s_add_i32 s44, s44, s47
	v_lshl_add_u64 v[140:141], s[14:15], 0, v[0:1]
	s_mov_b32 m0, s44
	ds_read_b128 v[184:187], v145 offset:16384
	ds_read_b128 v[188:191], v145 offset:17408
	ds_read_b128 v[192:195], v145 offset:18432
	ds_read_b128 v[196:199], v145 offset:19456
	ds_read_b128 v[200:203], v145 offset:20480
	ds_read_b128 v[204:207], v145 offset:21504
	ds_read_b128 v[208:211], v145 offset:22528
	ds_read_b128 v[212:215], v145 offset:23552
	global_load_lds_dwordx4 v[140:141], off
	s_add_i32 m0, s44, 0x2000
	s_add_u32 s44, s14, 0x84000
	v_lshl_add_u64 v[174:175], s[14:15], 0, v[134:135]
	s_addc_u32 s45, s15, 0
	s_add_i32 s46, s46, s47
	global_load_lds_dwordx4 v[174:175], off
	v_lshl_add_u64 v[216:217], s[44:45], 0, v[0:1]
	s_mov_b32 m0, s46
	v_lshl_add_u64 v[218:219], s[16:17], 0, v[132:133]
	global_load_lds_dwordx4 v[216:217], off
	v_lshl_add_u64 v[216:217], s[44:45], 0, v[134:135]
	s_add_i32 m0, s46, 0x2000
	s_nop 0
	global_load_lds_dwordx4 v[216:217], off
	v_lshl_add_u64 v[216:217], s[16:17], 0, v[130:131]
	s_mov_b32 m0, s24
	s_nop 0
	global_load_lds_dwordx4 v[216:217], off
	s_mov_b32 m0, s25
	s_nop 0
	global_load_lds_dwordx4 v[218:219], off
	s_waitcnt vmcnt(8)
	s_waitcnt lgkmcnt(0)
	s_setprio 1
	s_barrier
; #define PG8_STAGE(bufoff, gbase, voff) do { _Pragma("unroll") for (int _i = 0; _i < 2; ++_i) \
;         __builtin_amdgcn_global_load_lds((const unsigned*)((const char*)(gbase) + (voff)[_i]), (LAS unsigned*)(lds + (bufoff) + ldsw + _i * 8192), 16, 0, 0); } while (0)
; #define PG8_LDA(dst, b, h) do { _Pragma("unroll") for (int m = 0; m < 4; ++m) _Pragma("unroll") for (int k = 0; k < 2; ++k) dst[m][k] = *(const LAS bf16x8*)(lds + PG8_SA(b, h) + aoff + m * 2048 + k * 1024); } while (0)
; #define PG8_LDB(dst, b, h) do { _Pragma("unroll") for (int n = 0; n < 2; ++n) _Pragma("unroll") for (int k = 0; k < 2; ++k) dst[n][k] = *(const LAS bf16x8*)(lds + PG8_SB(b, h) + boff + n * 2048 + k * 1024); } while (0)
; #define PG8_MMA(ai, bj, At, Bt) do { __builtin_amdgcn_s_setprio(1); _Pragma("unroll") for (int m = 0; m < 4; ++m) _Pragma("unroll") for (int n = 0; n < 2; ++n) _Pragma("unroll") for (int k = 0; k < 2; ++k) \
;         acc[ai][bj][m][n] = __builtin_amdgcn_mfma_f32_16x16x32_bf16(Bt[n][k], At[m][k], acc[ai][bj][m][n], 0, 0, 0); __builtin_amdgcn_s_setprio(0); } while (0)
; #define PG8_WAIT_V(n) asm volatile("s_waitcnt vmcnt(" #n ")" ::: "memory")
; #define PG8_WAIT_L(n) asm volatile("s_waitcnt lgkmcnt(" #n ")" ::: "memory")
; #define PG8_BAR __builtin_amdgcn_s_barrier()
; #define PG8_SCHED __builtin_amdgcn_sched_barrier(0)
; template <class Epi, class Sched, int LDA, int LDB, bool ALIGN_EPI = true>
; __device__ __forceinline__ void gemm_phase(LAS unsigned char* lds, const Gemm g, const Sched& S, const Epi& E, int wave) {
;     ...
;             PG8_WAIT_V(8); PG8_WAIT_L(0); PG8_BAR; PG8_MMA(1, 0, At, B0); PG8_MMA(1, 1, At, B1); PG8_BAR; PG8_SCHED;
;             PG8_LDB(B0, 1, 0); PG8_LDB(B1, 1, 1); PG8_SCHED; PG8_LDA(At, 1, 0); PG8_STAGE(PG8_SA(0, 1), a2 + hstepA, voffA);
;             PG8_WAIT_V(8); PG8_WAIT_L(0); PG8_BAR; PG8_MMA(0, 0, At, B0); PG8_MMA(0, 1, At, B1); PG8_BAR; PG8_SCHED;
	v_mfma_f32_16x16x32_bf16 v[62:65], v[146:149], v[184:187], v[62:65]
	v_mfma_f32_16x16x32_bf16 v[62:65], v[150:153], v[188:191], v[62:65]
	v_mfma_f32_16x16x32_bf16 v[58:61], v[154:157], v[184:187], v[58:61]
	v_mfma_f32_16x16x32_bf16 v[58:61], v[158:161], v[188:191], v[58:61]
	v_mfma_f32_16x16x32_bf16 v[50:53], v[146:149], v[192:195], v[50:53]
	v_mfma_f32_16x16x32_bf16 v[50:53], v[150:153], v[196:199], v[50:53]
	v_mfma_f32_16x16x32_bf16 v[42:45], v[154:157], v[192:195], v[42:45]
	v_mfma_f32_16x16x32_bf16 v[42:45], v[158:161], v[196:199], v[42:45]
	v_mfma_f32_16x16x32_bf16 v[34:37], v[146:149], v[200:203], v[34:37]
	v_mfma_f32_16x16x32_bf16 v[34:37], v[150:153], v[204:207], v[34:37]
	v_mfma_f32_16x16x32_bf16 v[26:29], v[154:157], v[200:203], v[26:29]
	v_mfma_f32_16x16x32_bf16 v[26:29], v[158:161], v[204:207], v[26:29]
	v_mfma_f32_16x16x32_bf16 v[18:21], v[146:149], v[208:211], v[18:21]
	v_mfma_f32_16x16x32_bf16 v[18:21], v[150:153], v[212:215], v[18:21]
	v_mfma_f32_16x16x32_bf16 v[10:13], v[154:157], v[208:211], v[10:13]
	v_mfma_f32_16x16x32_bf16 v[10:13], v[158:161], v[212:215], v[10:13]
	v_mfma_f32_16x16x32_bf16 v[54:57], v[162:165], v[184:187], v[54:57]
	v_mfma_f32_16x16x32_bf16 v[54:57], v[166:169], v[188:191], v[54:57]
	v_mfma_f32_16x16x32_bf16 v[46:49], v[170:173], v[184:187], v[46:49]
	v_mfma_f32_16x16x32_bf16 v[46:49], v[180:183], v[188:191], v[46:49]
	v_mfma_f32_16x16x32_bf16 v[38:41], v[162:165], v[192:195], v[38:41]
	v_mfma_f32_16x16x32_bf16 v[38:41], v[166:169], v[196:199], v[38:41]
	v_mfma_f32_16x16x32_bf16 v[30:33], v[170:173], v[192:195], v[30:33]
	v_mfma_f32_16x16x32_bf16 v[30:33], v[180:183], v[196:199], v[30:33]
	v_mfma_f32_16x16x32_bf16 v[22:25], v[162:165], v[200:203], v[22:25]
	v_mfma_f32_16x16x32_bf16 v[22:25], v[166:169], v[204:207], v[22:25]
	v_mfma_f32_16x16x32_bf16 v[14:17], v[170:173], v[200:203], v[14:17]
	v_mfma_f32_16x16x32_bf16 v[14:17], v[180:183], v[204:207], v[14:17]
	v_mfma_f32_16x16x32_bf16 v[6:9], v[162:165], v[208:211], v[6:9]
	v_mfma_f32_16x16x32_bf16 v[6:9], v[166:169], v[212:215], v[6:9]
	v_mfma_f32_16x16x32_bf16 v[2:5], v[170:173], v[208:211], v[2:5]
	v_mfma_f32_16x16x32_bf16 v[2:5], v[180:183], v[212:215], v[2:5]
	s_barrier
	s_setprio 0
	ds_read_b128 v[184:187], v145 offset:32768
	ds_read_b128 v[188:191], v145 offset:33792
	ds_read_b128 v[192:195], v145 offset:34816
	ds_read_b128 v[196:199], v145 offset:35840
	ds_read_b128 v[200:203], v145 offset:36864
	ds_read_b128 v[204:207], v145 offset:37888
	ds_read_b128 v[208:211], v145 offset:38912
	ds_read_b128 v[212:215], v145 offset:39936
	s_add_i32 s44, 0, 0x18000
	s_add_i32 s45, 0, 0x1c000
	v_add_u32_e32 v158, s44, v143
	v_add_u32_e32 v180, s45, v143
	ds_read_b128 v[146:149], v158
	ds_read_b128 v[150:153], v158 offset:1024
	ds_read_b128 v[154:157], v158 offset:2048
	ds_read_b128 v[158:161], v158 offset:3072
	ds_read_b128 v[162:165], v180
	ds_read_b128 v[166:169], v180 offset:1024
	ds_read_b128 v[170:173], v180 offset:2048
	ds_read_b128 v[180:183], v180 offset:3072
	s_add_u32 s16, s16, 0x80000
	s_addc_u32 s17, s17, 0
	s_mov_b32 m0, s26
	v_lshl_add_u64 v[220:221], s[16:17], 0, v[130:131]
	global_load_lds_dwordx4 v[220:221], off
	v_lshl_add_u64 v[220:221], s[16:17], 0, v[132:133]
	s_mov_b32 m0, s27
	s_nop 0
	global_load_lds_dwordx4 v[220:221], off
	s_waitcnt vmcnt(8)
	s_waitcnt lgkmcnt(0)
	s_setprio 1
	s_barrier
	v_mfma_f32_16x16x32_bf16 v[126:129], v[146:149], v[184:187], v[126:129]
	v_mfma_f32_16x16x32_bf16 v[126:129], v[150:153], v[188:191], v[126:129]
	v_mfma_f32_16x16x32_bf16 v[122:125], v[154:157], v[184:187], v[122:125]
	v_mfma_f32_16x16x32_bf16 v[122:125], v[158:161], v[188:191], v[122:125]
	v_mfma_f32_16x16x32_bf16 v[114:117], v[146:149], v[192:195], v[114:117]
	v_mfma_f32_16x16x32_bf16 v[114:117], v[150:153], v[196:199], v[114:117]
	v_mfma_f32_16x16x32_bf16 v[106:109], v[154:157], v[192:195], v[106:109]
	v_mfma_f32_16x16x32_bf16 v[106:109], v[158:161], v[196:199], v[106:109]
	v_mfma_f32_16x16x32_bf16 v[98:101], v[146:149], v[200:203], v[98:101]
	v_mfma_f32_16x16x32_bf16 v[98:101], v[150:153], v[204:207], v[98:101]
	v_mfma_f32_16x16x32_bf16 v[90:93], v[154:157], v[200:203], v[90:93]
	v_mfma_f32_16x16x32_bf16 v[90:93], v[158:161], v[204:207], v[90:93]
	v_mfma_f32_16x16x32_bf16 v[82:85], v[146:149], v[208:211], v[82:85]
	v_mfma_f32_16x16x32_bf16 v[82:85], v[150:153], v[212:215], v[82:85]
	v_mfma_f32_16x16x32_bf16 v[74:77], v[154:157], v[208:211], v[74:77]
	v_mfma_f32_16x16x32_bf16 v[74:77], v[158:161], v[212:215], v[74:77]
	v_mfma_f32_16x16x32_bf16 v[118:121], v[162:165], v[184:187], v[118:121]
	v_mfma_f32_16x16x32_bf16 v[118:121], v[166:169], v[188:191], v[118:121]
	v_mfma_f32_16x16x32_bf16 v[110:113], v[170:173], v[184:187], v[110:113]
	v_mfma_f32_16x16x32_bf16 v[110:113], v[180:183], v[188:191], v[110:113]
	v_mfma_f32_16x16x32_bf16 v[102:105], v[162:165], v[192:195], v[102:105]
	v_mfma_f32_16x16x32_bf16 v[102:105], v[166:169], v[196:199], v[102:105]
	v_mfma_f32_16x16x32_bf16 v[94:97], v[170:173], v[192:195], v[94:97]
	v_mfma_f32_16x16x32_bf16 v[94:97], v[180:183], v[196:199], v[94:97]
	v_mfma_f32_16x16x32_bf16 v[86:89], v[162:165], v[200:203], v[86:89]
	v_mfma_f32_16x16x32_bf16 v[86:89], v[166:169], v[204:207], v[86:89]
	v_mfma_f32_16x16x32_bf16 v[78:81], v[170:173], v[200:203], v[78:81]
	v_mfma_f32_16x16x32_bf16 v[78:81], v[180:183], v[204:207], v[78:81]
	v_mfma_f32_16x16x32_bf16 v[70:73], v[162:165], v[208:211], v[70:73]
	v_mfma_f32_16x16x32_bf16 v[70:73], v[166:169], v[212:215], v[70:73]
	v_mfma_f32_16x16x32_bf16 v[66:69], v[170:173], v[208:211], v[66:69]
	v_mfma_f32_16x16x32_bf16 v[66:69], v[180:183], v[212:215], v[66:69]
	s_barrier
; #define PG8_STAGE(bufoff, gbase, voff) do { _Pragma("unroll") for (int _i = 0; _i < 2; ++_i) \
;         __builtin_amdgcn_global_load_lds((const unsigned*)((const char*)(gbase) + (voff)[_i]), (LAS unsigned*)(lds + (bufoff) + ldsw + _i * 8192), 16, 0, 0); } while (0)
; #define PG8_LDA(dst, b, h) do { _Pragma("unroll") for (int m = 0; m < 4; ++m) _Pragma("unroll") for (int k = 0; k < 2; ++k) dst[m][k] = *(const LAS bf16x8*)(lds + PG8_SA(b, h) + aoff + m * 2048 + k * 1024); } while (0)
; #define PG8_MMA(ai, bj, At, Bt) do { __builtin_amdgcn_s_setprio(1); _Pragma("unroll") for (int m = 0; m < 4; ++m) _Pragma("unroll") for (int n = 0; n < 2; ++n) _Pragma("unroll") for (int k = 0; k < 2; ++k) \
;         acc[ai][bj][m][n] = __builtin_amdgcn_mfma_f32_16x16x32_bf16(Bt[n][k], At[m][k], acc[ai][bj][m][n], 0, 0, 0); __builtin_amdgcn_s_setprio(0); } while (0)
; #define PG8_WAIT_V(n) asm volatile("s_waitcnt vmcnt(" #n ")" ::: "memory")
; #define PG8_WAIT_L(n) asm volatile("s_waitcnt lgkmcnt(" #n ")" ::: "memory")
; #define PG8_BAR __builtin_amdgcn_s_barrier()
; #define PG8_SCHED __builtin_amdgcn_sched_barrier(0)
; template <class Epi, class Sched, int LDA, int LDB, bool ALIGN_EPI = true>
; __device__ __forceinline__ void gemm_phase(LAS unsigned char* lds, const Gemm g, const Sched& S, const Epi& E, int wave) {
;     ...
;             PG8_LDA(At, 1, 1); PG8_STAGE(PG8_SB(1, 0), b3, voffB); PG8_STAGE(PG8_SB(1, 1), b3 + hstepB, voffB); PG8_STAGE(PG8_SA(1, 0), a3, voffA);
;             PG8_WAIT_V(8); PG8_WAIT_L(0); PG8_BAR; PG8_MMA(1, 0, At, B0); PG8_MMA(1, 1, At, B1); PG8_BAR; PG8_SCHED;
;         }
;         if constexpr (ALIGN_EPI) { if (wr == 0) PG8_BAR; }
	s_setprio 0
	s_add_i32 s16, s44, s47
	v_lshl_add_u64 v[140:141], v[140:141], 0, s[72:73]
	s_mov_b32 m0, s16
	ds_read_b128 v[184:187], v145 offset:49152
	ds_read_b128 v[188:191], v145 offset:50176
	ds_read_b128 v[192:195], v145 offset:51200
	ds_read_b128 v[196:199], v145 offset:52224
	ds_read_b128 v[200:203], v145 offset:53248
	ds_read_b128 v[204:207], v145 offset:54272
	ds_read_b128 v[208:211], v145 offset:55296
	ds_read_b128 v[212:215], v145 offset:56320
	global_load_lds_dwordx4 v[140:141], off
	s_add_i32 m0, s16, 0x2000
	s_add_u32 s14, s14, 0x84080
	v_lshl_add_u64 v[140:141], v[174:175], 0, s[72:73]
	s_addc_u32 s15, s15, 0
	s_add_i32 s16, s45, s47
	global_load_lds_dwordx4 v[140:141], off
	v_lshl_add_u64 v[140:141], s[14:15], 0, v[0:1]
	s_mov_b32 m0, s16
	s_nop 0
	global_load_lds_dwordx4 v[140:141], off
	v_lshl_add_u64 v[140:141], s[14:15], 0, v[134:135]
	s_add_i32 m0, s16, 0x2000
	s_nop 0
	global_load_lds_dwordx4 v[140:141], off
	v_lshl_add_u64 v[140:141], v[216:217], 0, s[72:73]
	s_mov_b32 m0, s28
	s_nop 0
	global_load_lds_dwordx4 v[140:141], off
	v_lshl_add_u64 v[140:141], v[218:219], 0, s[72:73]
	s_mov_b32 m0, s29
	s_nop 0
	global_load_lds_dwordx4 v[140:141], off
	s_waitcnt vmcnt(8)
	s_waitcnt lgkmcnt(0)
	s_setprio 1
	s_barrier
	v_mfma_f32_16x16x32_bf16 v[62:65], v[146:149], v[184:187], v[62:65]
	v_mfma_f32_16x16x32_bf16 v[62:65], v[150:153], v[188:191], v[62:65]
	v_mfma_f32_16x16x32_bf16 v[58:61], v[154:157], v[184:187], v[58:61]
	v_mfma_f32_16x16x32_bf16 v[58:61], v[158:161], v[188:191], v[58:61]
	v_mfma_f32_16x16x32_bf16 v[50:53], v[146:149], v[192:195], v[50:53]
	v_mfma_f32_16x16x32_bf16 v[50:53], v[150:153], v[196:199], v[50:53]
	v_mfma_f32_16x16x32_bf16 v[42:45], v[154:157], v[192:195], v[42:45]
	v_mfma_f32_16x16x32_bf16 v[42:45], v[158:161], v[196:199], v[42:45]
	v_mfma_f32_16x16x32_bf16 v[34:37], v[146:149], v[200:203], v[34:37]
	v_mfma_f32_16x16x32_bf16 v[34:37], v[150:153], v[204:207], v[34:37]
	v_mfma_f32_16x16x32_bf16 v[26:29], v[154:157], v[200:203], v[26:29]
	v_mfma_f32_16x16x32_bf16 v[26:29], v[158:161], v[204:207], v[26:29]
	v_mfma_f32_16x16x32_bf16 v[18:21], v[146:149], v[208:211], v[18:21]
	v_mfma_f32_16x16x32_bf16 v[18:21], v[150:153], v[212:215], v[18:21]
	v_mfma_f32_16x16x32_bf16 v[10:13], v[154:157], v[208:211], v[10:13]
	v_mfma_f32_16x16x32_bf16 v[10:13], v[158:161], v[212:215], v[10:13]
	v_mfma_f32_16x16x32_bf16 v[54:57], v[162:165], v[184:187], v[54:57]
	v_mfma_f32_16x16x32_bf16 v[54:57], v[166:169], v[188:191], v[54:57]
	v_mfma_f32_16x16x32_bf16 v[46:49], v[170:173], v[184:187], v[46:49]
	v_mfma_f32_16x16x32_bf16 v[46:49], v[180:183], v[188:191], v[46:49]
	v_mfma_f32_16x16x32_bf16 v[38:41], v[162:165], v[192:195], v[38:41]
	v_mfma_f32_16x16x32_bf16 v[38:41], v[166:169], v[196:199], v[38:41]
	v_mfma_f32_16x16x32_bf16 v[30:33], v[170:173], v[192:195], v[30:33]
	v_mfma_f32_16x16x32_bf16 v[30:33], v[180:183], v[196:199], v[30:33]
	v_mfma_f32_16x16x32_bf16 v[22:25], v[162:165], v[200:203], v[22:25]
	v_mfma_f32_16x16x32_bf16 v[22:25], v[166:169], v[204:207], v[22:25]
	v_mfma_f32_16x16x32_bf16 v[14:17], v[170:173], v[200:203], v[14:17]
	v_mfma_f32_16x16x32_bf16 v[14:17], v[180:183], v[204:207], v[14:17]
	v_mfma_f32_16x16x32_bf16 v[6:9], v[162:165], v[208:211], v[6:9]
	v_mfma_f32_16x16x32_bf16 v[6:9], v[166:169], v[212:215], v[6:9]
	v_mfma_f32_16x16x32_bf16 v[2:5], v[170:173], v[208:211], v[2:5]
	v_mfma_f32_16x16x32_bf16 v[2:5], v[180:183], v[212:215], v[2:5]
	s_barrier
	s_setprio 0
	s_add_i32 s39, s39, 2
	s_add_u32 s12, s12, 0x100
	s_addc_u32 s13, s13, 0
	s_add_u32 s37, s37, 0x100
	s_addc_u32 s38, s38, 0
	s_cmp_gt_u32 s39, 29
	s_cbranch_scc0 .LBB0_2513
	v_readlane_b32 s12, v252, 14
	v_readlane_b32 s13, v252, 15
	s_and_b64 vcc, exec, s[12:13]
	s_cbranch_vccz .LBB0_2516
	s_barrier

; #define PG8_STAGE(bufoff, gbase, voff) do { _Pragma("unroll") for (int _i = 0; _i < 2; ++_i) \
;         __builtin_amdgcn_global_load_lds((const unsigned*)((const char*)(gbase) + (voff)[_i]), (LAS unsigned*)(lds + (bufoff) + ldsw + _i * 8192), 16, 0, 0); } while (0)
; #define PG8_LDA(dst, b, h) do { _Pragma("unroll") for (int m = 0; m < 4; ++m) _Pragma("unroll") for (int k = 0; k < 2; ++k) dst[m][k] = *(const LAS bf16x8*)(lds + PG8_SA(b, h) + aoff + m * 2048 + k * 1024); } while (0)
; #define PG8_LDB(dst, b, h) do { _Pragma("unroll") for (int n = 0; n < 2; ++n) _Pragma("unroll") for (int k = 0; k < 2; ++k) dst[n][k] = *(const LAS bf16x8*)(lds + PG8_SB(b, h) + boff + n * 2048 + k * 1024); } while (0)
; #define PG8_MMA(ai, bj, At, Bt) do { __builtin_amdgcn_s_setprio(1); _Pragma("unroll") for (int m = 0; m < 4; ++m) _Pragma("unroll") for (int n = 0; n < 2; ++n) _Pragma("unroll") for (int k = 0; k < 2; ++k) \
;         acc[ai][bj][m][n] = __builtin_amdgcn_mfma_f32_16x16x32_bf16(Bt[n][k], At[m][k], acc[ai][bj][m][n], 0, 0, 0); __builtin_amdgcn_s_setprio(0); } while (0)
; #define PG8_WAIT_V(n) asm volatile("s_waitcnt vmcnt(" #n ")" ::: "memory")
; #define PG8_WAIT_L(n) asm volatile("s_waitcnt lgkmcnt(" #n ")" ::: "memory")
; #define PG8_BAR __builtin_amdgcn_s_barrier()
; template <class Epi, class Sched, int LDA, int LDB, bool ALIGN_EPI = true>
; __device__ __forceinline__ void gemm_phase(LAS unsigned char* lds, const Gemm g, const Sched& S, const Epi& E, int wave) {
;     ...
;         for (int t = 0; t < nt; t += 2) {
;             const bool last = (t == nt - 2);
;             const char* a1 = cA + (size_t)(t + 1) * kstep;
;             const char* a2 = last ? nA : cA + (size_t)(t + 2) * kstep; const char* b2 = last ? nB : cB + (size_t)(t + 2) * kstep;
;             const char* a3 = a2 + kstep; const char* b3 = b2 + kstep;
;             PG8_LDB(B0, 0, 0); PG8_LDB(B1, 0, 1); PG8_SCHED; PG8_LDA(At, 0, 0); PG8_STAGE(PG8_SA(1, 1), a1 + hstepA, voffA);
;             PG8_WAIT_V(8); PG8_WAIT_L(0); PG8_BAR; PG8_MMA(0, 0, At, B0); PG8_MMA(0, 1, At, B1); PG8_BAR; PG8_SCHED;
;             PG8_LDA(At, 0, 1); PG8_STAGE(PG8_SB(0, 0), b2, voffB); PG8_STAGE(PG8_SB(0, 1), b2 + hstepB, voffB); PG8_STAGE(PG8_SA(0, 0), a2, voffA);
;             PG8_WAIT_V(8); PG8_WAIT_L(0); PG8_BAR; PG8_MMA(1, 0, At, B0); PG8_MMA(1, 1, At, B1); PG8_BAR; PG8_SCHED;
.LBB0_2551:
	ds_read_b128 v[188:191], v156
	ds_read_b128 v[192:195], v156 offset:1024
	ds_read_b128 v[196:199], v156 offset:2048
	ds_read_b128 v[200:203], v156 offset:3072
	ds_read_b128 v[204:207], v156 offset:4096
	ds_read_b128 v[208:211], v156 offset:5120
	ds_read_b128 v[212:215], v156 offset:6144
	ds_read_b128 v[216:219], v156 offset:7168
	s_add_u32 s2, s0, 0x100
	s_addc_u32 s3, s1, 0
	s_add_i32 s50, 0, 0x10000
	s_cmp_eq_u32 s49, 8
	s_cselect_b32 s17, s11, s3
	s_cselect_b32 s16, s10, s2
	v_add_u32_e32 v0, s50, v154
	s_cselect_b32 s15, s13, s47
	s_cselect_b32 s14, s12, s46
	s_add_i32 s51, 0, 0x14000
	ds_read_b128 v[130:133], v0
	ds_read_b128 v[148:151], v0 offset:1024
	ds_read_b128 v[158:161], v0 offset:2048
	ds_read_b128 v[162:165], v0 offset:3072
	v_add_u32_e32 v0, s51, v154
	ds_read_b128 v[166:169], v0
	ds_read_b128 v[170:173], v0 offset:1024
	ds_read_b128 v[180:183], v0 offset:2048
	ds_read_b128 v[184:187], v0 offset:3072
	v_lshl_add_u64 v[152:153], s[0:1], 0, v[144:145]
	s_add_i32 m0, s28, 0xc000
	s_nop 0
	global_load_lds_dwordx4 v[152:153], off
	v_lshl_add_u64 v[152:153], s[0:1], 0, v[146:147]
	s_add_i32 m0, s28, 0xe000
	s_nop 0
	global_load_lds_dwordx4 v[152:153], off
	s_waitcnt vmcnt(8)
	s_waitcnt lgkmcnt(0)
	s_setprio 1
	s_barrier
	v_mfma_f32_16x16x32_bf16 v[126:129], v[130:133], v[188:191], v[126:129]
	v_mfma_f32_16x16x32_bf16 v[126:129], v[148:151], v[192:195], v[126:129]
	v_mfma_f32_16x16x32_bf16 v[122:125], v[158:161], v[188:191], v[122:125]
	v_mfma_f32_16x16x32_bf16 v[122:125], v[162:165], v[192:195], v[122:125]
	v_mfma_f32_16x16x32_bf16 v[118:121], v[130:133], v[196:199], v[118:121]
	v_mfma_f32_16x16x32_bf16 v[118:121], v[148:151], v[200:203], v[118:121]
	v_mfma_f32_16x16x32_bf16 v[114:117], v[158:161], v[196:199], v[114:117]
	v_mfma_f32_16x16x32_bf16 v[114:117], v[162:165], v[200:203], v[114:117]
	v_mfma_f32_16x16x32_bf16 v[110:113], v[130:133], v[204:207], v[110:113]
	v_mfma_f32_16x16x32_bf16 v[110:113], v[148:151], v[208:211], v[110:113]
	v_mfma_f32_16x16x32_bf16 v[106:109], v[158:161], v[204:207], v[106:109]
	v_mfma_f32_16x16x32_bf16 v[106:109], v[162:165], v[208:211], v[106:109]
	v_mfma_f32_16x16x32_bf16 v[102:105], v[130:133], v[212:215], v[102:105]
	v_mfma_f32_16x16x32_bf16 v[102:105], v[148:151], v[216:219], v[102:105]
	v_mfma_f32_16x16x32_bf16 v[98:101], v[158:161], v[212:215], v[98:101]
	v_mfma_f32_16x16x32_bf16 v[98:101], v[162:165], v[216:219], v[98:101]
	v_mfma_f32_16x16x32_bf16 v[62:65], v[166:169], v[188:191], v[62:65]
	v_mfma_f32_16x16x32_bf16 v[62:65], v[170:173], v[192:195], v[62:65]
	v_mfma_f32_16x16x32_bf16 v[58:61], v[180:183], v[188:191], v[58:61]
	v_mfma_f32_16x16x32_bf16 v[58:61], v[184:187], v[192:195], v[58:61]
	v_mfma_f32_16x16x32_bf16 v[54:57], v[166:169], v[196:199], v[54:57]
	v_mfma_f32_16x16x32_bf16 v[54:57], v[170:173], v[200:203], v[54:57]
	v_mfma_f32_16x16x32_bf16 v[50:53], v[180:183], v[196:199], v[50:53]
	v_mfma_f32_16x16x32_bf16 v[50:53], v[184:187], v[200:203], v[50:53]
	v_mfma_f32_16x16x32_bf16 v[46:49], v[166:169], v[204:207], v[46:49]
	v_mfma_f32_16x16x32_bf16 v[46:49], v[170:173], v[208:211], v[46:49]
	v_mfma_f32_16x16x32_bf16 v[42:45], v[180:183], v[204:207], v[42:45]
	v_mfma_f32_16x16x32_bf16 v[42:45], v[184:187], v[208:211], v[42:45]
	v_mfma_f32_16x16x32_bf16 v[38:41], v[166:169], v[212:215], v[38:41]
	v_mfma_f32_16x16x32_bf16 v[38:41], v[170:173], v[216:219], v[38:41]
	v_mfma_f32_16x16x32_bf16 v[34:37], v[180:183], v[212:215], v[34:37]
	v_mfma_f32_16x16x32_bf16 v[34:37], v[184:187], v[216:219], v[34:37]
	s_barrier
	s_setprio 0
	s_add_i32 s0, s50, s54
	v_lshl_add_u64 v[152:153], s[14:15], 0, v[136:137]
	s_mov_b32 m0, s0
	ds_read_b128 v[188:191], v156 offset:16384
	ds_read_b128 v[192:195], v156 offset:17408
	ds_read_b128 v[196:199], v156 offset:18432
	ds_read_b128 v[200:203], v156 offset:19456
	ds_read_b128 v[204:207], v156 offset:20480
	ds_read_b128 v[208:211], v156 offset:21504
	ds_read_b128 v[212:215], v156 offset:22528
	ds_read_b128 v[216:219], v156 offset:23552
	global_load_lds_dwordx4 v[152:153], off
	s_add_i32 m0, s0, 0x2000
	s_add_u32 s0, s14, 0x30000
	v_lshl_add_u64 v[174:175], s[14:15], 0, v[140:141]
	s_addc_u32 s1, s15, 0
	s_add_i32 s50, s51, s54
	global_load_lds_dwordx4 v[174:175], off
	v_lshl_add_u64 v[220:221], s[0:1], 0, v[136:137]
	s_mov_b32 m0, s50
	v_lshl_add_u64 v[222:223], s[16:17], 0, v[138:139]
	global_load_lds_dwordx4 v[220:221], off
	v_lshl_add_u64 v[220:221], s[0:1], 0, v[140:141]
	s_add_i32 m0, s50, 0x2000
	s_nop 0
	global_load_lds_dwordx4 v[220:221], off
	v_lshl_add_u64 v[220:221], s[16:17], 0, v[134:135]
	s_mov_b32 m0, s28
	s_nop 0
	global_load_lds_dwordx4 v[220:221], off
	s_mov_b32 m0, s29
	s_nop 0
	global_load_lds_dwordx4 v[222:223], off
	s_waitcnt vmcnt(8)
	s_waitcnt lgkmcnt(0)
	s_setprio 1
	s_barrier
; #define PG8_STAGE(bufoff, gbase, voff) do { _Pragma("unroll") for (int _i = 0; _i < 2; ++_i) \
;         __builtin_amdgcn_global_load_lds((const unsigned*)((const char*)(gbase) + (voff)[_i]), (LAS unsigned*)(lds + (bufoff) + ldsw + _i * 8192), 16, 0, 0); } while (0)
; #define PG8_LDA(dst, b, h) do { _Pragma("unroll") for (int m = 0; m < 4; ++m) _Pragma("unroll") for (int k = 0; k < 2; ++k) dst[m][k] = *(const LAS bf16x8*)(lds + PG8_SA(b, h) + aoff + m * 2048 + k * 1024); } while (0)
; #define PG8_LDB(dst, b, h) do { _Pragma("unroll") for (int n = 0; n < 2; ++n) _Pragma("unroll") for (int k = 0; k < 2; ++k) dst[n][k] = *(const LAS bf16x8*)(lds + PG8_SB(b, h) + boff + n * 2048 + k * 1024); } while (0)
; #define PG8_MMA(ai, bj, At, Bt) do { __builtin_amdgcn_s_setprio(1); _Pragma("unroll") for (int m = 0; m < 4; ++m) _Pragma("unroll") for (int n = 0; n < 2; ++n) _Pragma("unroll") for (int k = 0; k < 2; ++k) \
;         acc[ai][bj][m][n] = __builtin_amdgcn_mfma_f32_16x16x32_bf16(Bt[n][k], At[m][k], acc[ai][bj][m][n], 0, 0, 0); __builtin_amdgcn_s_setprio(0); } while (0)
; #define PG8_WAIT_V(n) asm volatile("s_waitcnt vmcnt(" #n ")" ::: "memory")
; #define PG8_WAIT_L(n) asm volatile("s_waitcnt lgkmcnt(" #n ")" ::: "memory")
; #define PG8_BAR __builtin_amdgcn_s_barrier()
; #define PG8_SCHED __builtin_amdgcn_sched_barrier(0)
; template <class Epi, class Sched, int LDA, int LDB, bool ALIGN_EPI = true>
; __device__ __forceinline__ void gemm_phase(LAS unsigned char* lds, const Gemm g, const Sched& S, const Epi& E, int wave) {
;     ...
;             PG8_WAIT_V(8); PG8_WAIT_L(0); PG8_BAR; PG8_MMA(1, 0, At, B0); PG8_MMA(1, 1, At, B1); PG8_BAR; PG8_SCHED;
;             PG8_LDB(B0, 1, 0); PG8_LDB(B1, 1, 1); PG8_SCHED; PG8_LDA(At, 1, 0); PG8_STAGE(PG8_SA(0, 1), a2 + hstepA, voffA);
;             PG8_WAIT_V(8); PG8_WAIT_L(0); PG8_BAR; PG8_MMA(0, 0, At, B0); PG8_MMA(0, 1, At, B1); PG8_BAR; PG8_SCHED;
	v_mfma_f32_16x16x32_bf16 v[94:97], v[130:133], v[188:191], v[94:97]
	v_mfma_f32_16x16x32_bf16 v[94:97], v[148:151], v[192:195], v[94:97]
	v_mfma_f32_16x16x32_bf16 v[90:93], v[158:161], v[188:191], v[90:93]
	v_mfma_f32_16x16x32_bf16 v[90:93], v[162:165], v[192:195], v[90:93]
	v_mfma_f32_16x16x32_bf16 v[86:89], v[130:133], v[196:199], v[86:89]
	v_mfma_f32_16x16x32_bf16 v[86:89], v[148:151], v[200:203], v[86:89]
	v_mfma_f32_16x16x32_bf16 v[82:85], v[158:161], v[196:199], v[82:85]
	v_mfma_f32_16x16x32_bf16 v[82:85], v[162:165], v[200:203], v[82:85]
	v_mfma_f32_16x16x32_bf16 v[78:81], v[130:133], v[204:207], v[78:81]
	v_mfma_f32_16x16x32_bf16 v[78:81], v[148:151], v[208:211], v[78:81]
	v_mfma_f32_16x16x32_bf16 v[74:77], v[158:161], v[204:207], v[74:77]
	v_mfma_f32_16x16x32_bf16 v[74:77], v[162:165], v[208:211], v[74:77]
	v_mfma_f32_16x16x32_bf16 v[70:73], v[130:133], v[212:215], v[70:73]
	v_mfma_f32_16x16x32_bf16 v[70:73], v[148:151], v[216:219], v[70:73]
	v_mfma_f32_16x16x32_bf16 v[66:69], v[158:161], v[212:215], v[66:69]
	v_mfma_f32_16x16x32_bf16 v[66:69], v[162:165], v[216:219], v[66:69]
	v_mfma_f32_16x16x32_bf16 v[30:33], v[166:169], v[188:191], v[30:33]
	v_mfma_f32_16x16x32_bf16 v[30:33], v[170:173], v[192:195], v[30:33]
	v_mfma_f32_16x16x32_bf16 v[26:29], v[180:183], v[188:191], v[26:29]
	v_mfma_f32_16x16x32_bf16 v[26:29], v[184:187], v[192:195], v[26:29]
	v_mfma_f32_16x16x32_bf16 v[22:25], v[166:169], v[196:199], v[22:25]
	v_mfma_f32_16x16x32_bf16 v[22:25], v[170:173], v[200:203], v[22:25]
	v_mfma_f32_16x16x32_bf16 v[18:21], v[180:183], v[196:199], v[18:21]
	v_mfma_f32_16x16x32_bf16 v[18:21], v[184:187], v[200:203], v[18:21]
	v_mfma_f32_16x16x32_bf16 v[14:17], v[166:169], v[204:207], v[14:17]
	v_mfma_f32_16x16x32_bf16 v[14:17], v[170:173], v[208:211], v[14:17]
	v_mfma_f32_16x16x32_bf16 v[10:13], v[180:183], v[204:207], v[10:13]
	v_mfma_f32_16x16x32_bf16 v[10:13], v[184:187], v[208:211], v[10:13]
	v_mfma_f32_16x16x32_bf16 v[6:9], v[166:169], v[212:215], v[6:9]
	v_mfma_f32_16x16x32_bf16 v[6:9], v[170:173], v[216:219], v[6:9]
	v_mfma_f32_16x16x32_bf16 v[2:5], v[180:183], v[212:215], v[2:5]
	v_mfma_f32_16x16x32_bf16 v[2:5], v[184:187], v[216:219], v[2:5]
	s_barrier
	s_setprio 0
	ds_read_b128 v[188:191], v156 offset:32768
	ds_read_b128 v[192:195], v156 offset:33792
	ds_read_b128 v[196:199], v156 offset:34816
	ds_read_b128 v[200:203], v156 offset:35840
	ds_read_b128 v[204:207], v156 offset:36864
	ds_read_b128 v[208:211], v156 offset:37888
	ds_read_b128 v[212:215], v156 offset:38912
	ds_read_b128 v[216:219], v156 offset:39936
	s_add_i32 s50, 0, 0x18000
	v_add_u32_e32 v0, s50, v154
	s_add_i32 s51, 0, 0x1c000
	ds_read_b128 v[130:133], v0
	ds_read_b128 v[148:151], v0 offset:1024
	ds_read_b128 v[158:161], v0 offset:2048
	ds_read_b128 v[162:165], v0 offset:3072
	v_add_u32_e32 v0, s51, v154
	ds_read_b128 v[166:169], v0
	ds_read_b128 v[170:173], v0 offset:1024
	ds_read_b128 v[180:183], v0 offset:2048
	ds_read_b128 v[184:187], v0 offset:3072
	s_add_u32 s0, s16, 0x30000
	s_addc_u32 s1, s17, 0
	s_mov_b32 m0, s34
	v_lshl_add_u64 v[224:225], s[0:1], 0, v[134:135]
	global_load_lds_dwordx4 v[224:225], off
	v_lshl_add_u64 v[224:225], s[0:1], 0, v[138:139]
	s_mov_b32 m0, s35
	s_nop 0
	global_load_lds_dwordx4 v[224:225], off
	s_waitcnt vmcnt(8)
	s_waitcnt lgkmcnt(0)
	s_setprio 1
	s_barrier
	v_mfma_f32_16x16x32_bf16 v[126:129], v[130:133], v[188:191], v[126:129]
	v_mfma_f32_16x16x32_bf16 v[126:129], v[148:151], v[192:195], v[126:129]
	v_mfma_f32_16x16x32_bf16 v[122:125], v[158:161], v[188:191], v[122:125]
	v_mfma_f32_16x16x32_bf16 v[122:125], v[162:165], v[192:195], v[122:125]
	v_mfma_f32_16x16x32_bf16 v[118:121], v[130:133], v[196:199], v[118:121]
	v_mfma_f32_16x16x32_bf16 v[118:121], v[148:151], v[200:203], v[118:121]
	v_mfma_f32_16x16x32_bf16 v[114:117], v[158:161], v[196:199], v[114:117]
	v_mfma_f32_16x16x32_bf16 v[114:117], v[162:165], v[200:203], v[114:117]
	v_mfma_f32_16x16x32_bf16 v[110:113], v[130:133], v[204:207], v[110:113]
	v_mfma_f32_16x16x32_bf16 v[110:113], v[148:151], v[208:211], v[110:113]
	v_mfma_f32_16x16x32_bf16 v[106:109], v[158:161], v[204:207], v[106:109]
	v_mfma_f32_16x16x32_bf16 v[106:109], v[162:165], v[208:211], v[106:109]
	v_mfma_f32_16x16x32_bf16 v[102:105], v[130:133], v[212:215], v[102:105]
	v_mfma_f32_16x16x32_bf16 v[102:105], v[148:151], v[216:219], v[102:105]
	v_mfma_f32_16x16x32_bf16 v[98:101], v[158:161], v[212:215], v[98:101]
	v_mfma_f32_16x16x32_bf16 v[98:101], v[162:165], v[216:219], v[98:101]
	v_mfma_f32_16x16x32_bf16 v[62:65], v[166:169], v[188:191], v[62:65]
	v_mfma_f32_16x16x32_bf16 v[62:65], v[170:173], v[192:195], v[62:65]
	v_mfma_f32_16x16x32_bf16 v[58:61], v[180:183], v[188:191], v[58:61]
	v_mfma_f32_16x16x32_bf16 v[58:61], v[184:187], v[192:195], v[58:61]
	v_mfma_f32_16x16x32_bf16 v[54:57], v[166:169], v[196:199], v[54:57]
	v_mfma_f32_16x16x32_bf16 v[54:57], v[170:173], v[200:203], v[54:57]
	v_mfma_f32_16x16x32_bf16 v[50:53], v[180:183], v[196:199], v[50:53]
	v_mfma_f32_16x16x32_bf16 v[50:53], v[184:187], v[200:203], v[50:53]
	v_mfma_f32_16x16x32_bf16 v[46:49], v[166:169], v[204:207], v[46:49]
	v_mfma_f32_16x16x32_bf16 v[46:49], v[170:173], v[208:211], v[46:49]
	v_mfma_f32_16x16x32_bf16 v[42:45], v[180:183], v[204:207], v[42:45]
	v_mfma_f32_16x16x32_bf16 v[42:45], v[184:187], v[208:211], v[42:45]
	v_mfma_f32_16x16x32_bf16 v[38:41], v[166:169], v[212:215], v[38:41]
	v_mfma_f32_16x16x32_bf16 v[38:41], v[170:173], v[216:219], v[38:41]
	v_mfma_f32_16x16x32_bf16 v[34:37], v[180:183], v[212:215], v[34:37]
	v_mfma_f32_16x16x32_bf16 v[34:37], v[184:187], v[216:219], v[34:37]
	s_barrier
; #define PG8_STAGE(bufoff, gbase, voff) do { _Pragma("unroll") for (int _i = 0; _i < 2; ++_i) \
;         __builtin_amdgcn_global_load_lds((const unsigned*)((const char*)(gbase) + (voff)[_i]), (LAS unsigned*)(lds + (bufoff) + ldsw + _i * 8192), 16, 0, 0); } while (0)
; #define PG8_LDA(dst, b, h) do { _Pragma("unroll") for (int m = 0; m < 4; ++m) _Pragma("unroll") for (int k = 0; k < 2; ++k) dst[m][k] = *(const LAS bf16x8*)(lds + PG8_SA(b, h) + aoff + m * 2048 + k * 1024); } while (0)
; #define PG8_MMA(ai, bj, At, Bt) do { __builtin_amdgcn_s_setprio(1); _Pragma("unroll") for (int m = 0; m < 4; ++m) _Pragma("unroll") for (int n = 0; n < 2; ++n) _Pragma("unroll") for (int k = 0; k < 2; ++k) \
;         acc[ai][bj][m][n] = __builtin_amdgcn_mfma_f32_16x16x32_bf16(Bt[n][k], At[m][k], acc[ai][bj][m][n], 0, 0, 0); __builtin_amdgcn_s_setprio(0); } while (0)
; #define PG8_WAIT_V(n) asm volatile("s_waitcnt vmcnt(" #n ")" ::: "memory")
; #define PG8_WAIT_L(n) asm volatile("s_waitcnt lgkmcnt(" #n ")" ::: "memory")
; #define PG8_BAR __builtin_amdgcn_s_barrier()
; #define PG8_SCHED __builtin_amdgcn_sched_barrier(0)
; template <class Epi, class Sched, int LDA, int LDB, bool ALIGN_EPI = true>
; __device__ __forceinline__ void gemm_phase(LAS unsigned char* lds, const Gemm g, const Sched& S, const Epi& E, int wave) {
;     ...
;             PG8_LDA(At, 1, 1); PG8_STAGE(PG8_SB(1, 0), b3, voffB); PG8_STAGE(PG8_SB(1, 1), b3 + hstepB, voffB); PG8_STAGE(PG8_SA(1, 0), a3, voffA);
;             PG8_WAIT_V(8); PG8_WAIT_L(0); PG8_BAR; PG8_MMA(1, 0, At, B0); PG8_MMA(1, 1, At, B1); PG8_BAR; PG8_SCHED;
;         }
;         if constexpr (ALIGN_EPI) { if (wr == 0) PG8_BAR; }
	s_setprio 0
	s_add_i32 s0, s50, s54
	v_lshl_add_u64 v[152:153], v[152:153], 0, s[72:73]
	s_mov_b32 m0, s0
	ds_read_b128 v[188:191], v156 offset:49152
	ds_read_b128 v[192:195], v156 offset:50176
	ds_read_b128 v[196:199], v156 offset:51200
	ds_read_b128 v[200:203], v156 offset:52224
	ds_read_b128 v[204:207], v156 offset:53248
	ds_read_b128 v[208:211], v156 offset:54272
	ds_read_b128 v[212:215], v156 offset:55296
	ds_read_b128 v[216:219], v156 offset:56320
	global_load_lds_dwordx4 v[152:153], off
	s_add_i32 m0, s0, 0x2000
	s_add_u32 s0, s14, 0x30080
	v_lshl_add_u64 v[152:153], v[174:175], 0, s[72:73]
	s_addc_u32 s1, s15, 0
	s_add_i32 s14, s51, s54
	global_load_lds_dwordx4 v[152:153], off
	v_lshl_add_u64 v[152:153], s[0:1], 0, v[136:137]
	s_mov_b32 m0, s14
	s_nop 0
	global_load_lds_dwordx4 v[152:153], off
	v_lshl_add_u64 v[152:153], s[0:1], 0, v[140:141]
	s_add_i32 m0, s14, 0x2000
	s_nop 0
	global_load_lds_dwordx4 v[152:153], off
	v_lshl_add_u64 v[152:153], v[220:221], 0, s[72:73]
	s_mov_b32 m0, s36
	s_nop 0
	global_load_lds_dwordx4 v[152:153], off
	v_lshl_add_u64 v[152:153], v[222:223], 0, s[72:73]
	s_mov_b32 m0, s37
	s_nop 0
	global_load_lds_dwordx4 v[152:153], off
	s_waitcnt vmcnt(8)
	s_waitcnt lgkmcnt(0)
	s_setprio 1
	s_barrier
	v_mfma_f32_16x16x32_bf16 v[94:97], v[130:133], v[188:191], v[94:97]
	v_mfma_f32_16x16x32_bf16 v[94:97], v[148:151], v[192:195], v[94:97]
	v_mfma_f32_16x16x32_bf16 v[90:93], v[158:161], v[188:191], v[90:93]
	v_mfma_f32_16x16x32_bf16 v[90:93], v[162:165], v[192:195], v[90:93]
	v_mfma_f32_16x16x32_bf16 v[86:89], v[130:133], v[196:199], v[86:89]
	v_mfma_f32_16x16x32_bf16 v[86:89], v[148:151], v[200:203], v[86:89]
	v_mfma_f32_16x16x32_bf16 v[82:85], v[158:161], v[196:199], v[82:85]
	v_mfma_f32_16x16x32_bf16 v[82:85], v[162:165], v[200:203], v[82:85]
	v_mfma_f32_16x16x32_bf16 v[78:81], v[130:133], v[204:207], v[78:81]
	v_mfma_f32_16x16x32_bf16 v[78:81], v[148:151], v[208:211], v[78:81]
	v_mfma_f32_16x16x32_bf16 v[74:77], v[158:161], v[204:207], v[74:77]
	v_mfma_f32_16x16x32_bf16 v[74:77], v[162:165], v[208:211], v[74:77]
	v_mfma_f32_16x16x32_bf16 v[70:73], v[130:133], v[212:215], v[70:73]
	v_mfma_f32_16x16x32_bf16 v[70:73], v[148:151], v[216:219], v[70:73]
	v_mfma_f32_16x16x32_bf16 v[66:69], v[158:161], v[212:215], v[66:69]
	v_mfma_f32_16x16x32_bf16 v[66:69], v[162:165], v[216:219], v[66:69]
	v_mfma_f32_16x16x32_bf16 v[30:33], v[166:169], v[188:191], v[30:33]
	v_mfma_f32_16x16x32_bf16 v[30:33], v[170:173], v[192:195], v[30:33]
	v_mfma_f32_16x16x32_bf16 v[26:29], v[180:183], v[188:191], v[26:29]
	v_mfma_f32_16x16x32_bf16 v[26:29], v[184:187], v[192:195], v[26:29]
	v_mfma_f32_16x16x32_bf16 v[22:25], v[166:169], v[196:199], v[22:25]
	v_mfma_f32_16x16x32_bf16 v[22:25], v[170:173], v[200:203], v[22:25]
	v_mfma_f32_16x16x32_bf16 v[18:21], v[180:183], v[196:199], v[18:21]
	v_mfma_f32_16x16x32_bf16 v[18:21], v[184:187], v[200:203], v[18:21]
	v_mfma_f32_16x16x32_bf16 v[14:17], v[166:169], v[204:207], v[14:17]
	v_mfma_f32_16x16x32_bf16 v[14:17], v[170:173], v[208:211], v[14:17]
	v_mfma_f32_16x16x32_bf16 v[10:13], v[180:183], v[204:207], v[10:13]
	v_mfma_f32_16x16x32_bf16 v[10:13], v[184:187], v[208:211], v[10:13]
	v_mfma_f32_16x16x32_bf16 v[6:9], v[166:169], v[212:215], v[6:9]
	v_mfma_f32_16x16x32_bf16 v[6:9], v[170:173], v[216:219], v[6:9]
	v_mfma_f32_16x16x32_bf16 v[2:5], v[180:183], v[212:215], v[2:5]
	v_mfma_f32_16x16x32_bf16 v[2:5], v[184:187], v[216:219], v[2:5]
	s_barrier
	s_setprio 0
	s_add_i32 s49, s49, 2
	s_add_u32 s46, s46, 0x100
	s_addc_u32 s47, s47, 0
	s_cmp_gt_u32 s49, 9
	s_mov_b64 s[0:1], s[2:3]
	s_cbranch_scc0 .LBB0_2551
	v_readlane_b32 s0, v252, 14
	v_readlane_b32 s1, v252, 15
	s_and_b64 vcc, exec, s[0:1]
	s_cbranch_vccz .LBB0_2554
	s_barrier

; #define PG8_STAGE(bufoff, gbase, voff) do { _Pragma("unroll") for (int _i = 0; _i < 2; ++_i) \
;         __builtin_amdgcn_global_load_lds((const unsigned*)((const char*)(gbase) + (voff)[_i]), (LAS unsigned*)(lds + (bufoff) + ldsw + _i * 8192), 16, 0, 0); } while (0)
; #define PG8_LDA(dst, b, h) do { _Pragma("unroll") for (int m = 0; m < 4; ++m) _Pragma("unroll") for (int k = 0; k < 2; ++k) dst[m][k] = *(const LAS bf16x8*)(lds + PG8_SA(b, h) + aoff + m * 2048 + k * 1024); } while (0)
; #define PG8_LDB(dst, b, h) do { _Pragma("unroll") for (int n = 0; n < 2; ++n) _Pragma("unroll") for (int k = 0; k < 2; ++k) dst[n][k] = *(const LAS bf16x8*)(lds + PG8_SB(b, h) + boff + n * 2048 + k * 1024); } while (0)
; #define PG8_MMA(ai, bj, At, Bt) do { __builtin_amdgcn_s_setprio(1); _Pragma("unroll") for (int m = 0; m < 4; ++m) _Pragma("unroll") for (int n = 0; n < 2; ++n) _Pragma("unroll") for (int k = 0; k < 2; ++k) \
;         acc[ai][bj][m][n] = __builtin_amdgcn_mfma_f32_16x16x32_bf16(Bt[n][k], At[m][k], acc[ai][bj][m][n], 0, 0, 0); __builtin_amdgcn_s_setprio(0); } while (0)
; #define PG8_WAIT_V(n) asm volatile("s_waitcnt vmcnt(" #n ")" ::: "memory")
; #define PG8_WAIT_L(n) asm volatile("s_waitcnt lgkmcnt(" #n ")" ::: "memory")
; #define PG8_BAR __builtin_amdgcn_s_barrier()
; template <class Epi, class Sched, int LDA, int LDB, bool ALIGN_EPI = true>
; __device__ __forceinline__ void gemm_phase(LAS unsigned char* lds, const Gemm g, const Sched& S, const Epi& E, int wave) {
;     ...
;         for (int t = 0; t < nt; t += 2) {
;             const bool last = (t == nt - 2);
;             const char* a1 = cA + (size_t)(t + 1) * kstep;
;             const char* a2 = last ? nA : cA + (size_t)(t + 2) * kstep; const char* b2 = last ? nB : cB + (size_t)(t + 2) * kstep;
;             const char* a3 = a2 + kstep; const char* b3 = b2 + kstep;
;             PG8_LDB(B0, 0, 0); PG8_LDB(B1, 0, 1); PG8_SCHED; PG8_LDA(At, 0, 0); PG8_STAGE(PG8_SA(1, 1), a1 + hstepA, voffA);
;             PG8_WAIT_V(8); PG8_WAIT_L(0); PG8_BAR; PG8_MMA(0, 0, At, B0); PG8_MMA(0, 1, At, B1); PG8_BAR; PG8_SCHED;
;             PG8_LDA(At, 0, 1); PG8_STAGE(PG8_SB(0, 0), b2, voffB); PG8_STAGE(PG8_SB(0, 1), b2 + hstepB, voffB); PG8_STAGE(PG8_SA(0, 0), a2, voffA);
;             PG8_WAIT_V(8); PG8_WAIT_L(0); PG8_BAR; PG8_MMA(1, 0, At, B0); PG8_MMA(1, 1, At, B1); PG8_BAR; PG8_SCHED;
.LBB0_2619:
	ds_read_b128 v[184:187], v151
	ds_read_b128 v[188:191], v151 offset:1024
	ds_read_b128 v[192:195], v151 offset:2048
	ds_read_b128 v[196:199], v151 offset:3072
	ds_read_b128 v[200:203], v151 offset:4096
	ds_read_b128 v[204:207], v151 offset:5120
	ds_read_b128 v[208:211], v151 offset:6144
	ds_read_b128 v[212:215], v151 offset:7168
	s_add_u32 s16, s14, 0xfffe0080
	s_addc_u32 s17, s15, -1
	s_add_i32 s53, 0, 0x10000
	s_cmp_eq_u32 s52, 4
	s_cselect_b32 s19, s7, s17
	s_cselect_b32 s18, s13, s16
	v_add_u32_e32 v0, s53, v150
	s_cselect_b32 s17, s3, s51
	s_cselect_b32 s16, s44, s45
	s_add_i32 s58, 0, 0x14000
	ds_read_b128 v[144:147], v0
	ds_read_b128 v[152:155], v0 offset:1024
	ds_read_b128 v[156:159], v0 offset:2048
	ds_read_b128 v[160:163], v0 offset:3072
	v_add_u32_e32 v0, s58, v150
	ds_read_b128 v[164:167], v0
	ds_read_b128 v[168:171], v0 offset:1024
	ds_read_b128 v[172:175], v0 offset:2048
	ds_read_b128 v[180:183], v0 offset:3072
	v_lshl_add_u64 v[148:149], s[14:15], 0, v[140:141]
	s_add_i32 m0, s36, 0xc000
	s_nop 0
	global_load_lds_dwordx4 v[148:149], off
	v_lshl_add_u64 v[148:149], s[14:15], 0, v[142:143]
	s_add_i32 m0, s36, 0xe000
	s_nop 0
	global_load_lds_dwordx4 v[148:149], off
	s_waitcnt vmcnt(8)
	s_waitcnt lgkmcnt(0)
	s_setprio 1
	s_barrier
	v_mfma_f32_16x16x32_bf16 v[126:129], v[144:147], v[184:187], v[126:129]
	v_mfma_f32_16x16x32_bf16 v[126:129], v[152:155], v[188:191], v[126:129]
	v_mfma_f32_16x16x32_bf16 v[122:125], v[156:159], v[184:187], v[122:125]
	v_mfma_f32_16x16x32_bf16 v[122:125], v[160:163], v[188:191], v[122:125]
	v_mfma_f32_16x16x32_bf16 v[118:121], v[144:147], v[192:195], v[118:121]
	v_mfma_f32_16x16x32_bf16 v[118:121], v[152:155], v[196:199], v[118:121]
	v_mfma_f32_16x16x32_bf16 v[114:117], v[156:159], v[192:195], v[114:117]
	v_mfma_f32_16x16x32_bf16 v[114:117], v[160:163], v[196:199], v[114:117]
	v_mfma_f32_16x16x32_bf16 v[110:113], v[144:147], v[200:203], v[110:113]
	v_mfma_f32_16x16x32_bf16 v[110:113], v[152:155], v[204:207], v[110:113]
	v_mfma_f32_16x16x32_bf16 v[106:109], v[156:159], v[200:203], v[106:109]
	v_mfma_f32_16x16x32_bf16 v[106:109], v[160:163], v[204:207], v[106:109]
	v_mfma_f32_16x16x32_bf16 v[102:105], v[144:147], v[208:211], v[102:105]
	v_mfma_f32_16x16x32_bf16 v[102:105], v[152:155], v[212:215], v[102:105]
	v_mfma_f32_16x16x32_bf16 v[98:101], v[156:159], v[208:211], v[98:101]
	v_mfma_f32_16x16x32_bf16 v[98:101], v[160:163], v[212:215], v[98:101]
	v_mfma_f32_16x16x32_bf16 v[62:65], v[164:167], v[184:187], v[62:65]
	v_mfma_f32_16x16x32_bf16 v[62:65], v[168:171], v[188:191], v[62:65]
	v_mfma_f32_16x16x32_bf16 v[58:61], v[172:175], v[184:187], v[58:61]
	v_mfma_f32_16x16x32_bf16 v[58:61], v[180:183], v[188:191], v[58:61]
	v_mfma_f32_16x16x32_bf16 v[54:57], v[164:167], v[192:195], v[54:57]
	v_mfma_f32_16x16x32_bf16 v[54:57], v[168:171], v[196:199], v[54:57]
	v_mfma_f32_16x16x32_bf16 v[50:53], v[172:175], v[192:195], v[50:53]
	v_mfma_f32_16x16x32_bf16 v[50:53], v[180:183], v[196:199], v[50:53]
	v_mfma_f32_16x16x32_bf16 v[46:49], v[164:167], v[200:203], v[46:49]
	v_mfma_f32_16x16x32_bf16 v[46:49], v[168:171], v[204:207], v[46:49]
	v_mfma_f32_16x16x32_bf16 v[42:45], v[172:175], v[200:203], v[42:45]
	v_mfma_f32_16x16x32_bf16 v[42:45], v[180:183], v[204:207], v[42:45]
	v_mfma_f32_16x16x32_bf16 v[38:41], v[164:167], v[208:211], v[38:41]
	v_mfma_f32_16x16x32_bf16 v[38:41], v[168:171], v[212:215], v[38:41]
	v_mfma_f32_16x16x32_bf16 v[34:37], v[172:175], v[208:211], v[34:37]
	v_mfma_f32_16x16x32_bf16 v[34:37], v[180:183], v[212:215], v[34:37]
	s_barrier
	s_setprio 0
	s_add_i32 s53, s53, s59
	v_lshl_add_u64 v[148:149], s[16:17], 0, v[132:133]
	s_mov_b32 m0, s53
	ds_read_b128 v[184:187], v151 offset:16384
	ds_read_b128 v[188:191], v151 offset:17408
	ds_read_b128 v[192:195], v151 offset:18432
	ds_read_b128 v[196:199], v151 offset:19456
	ds_read_b128 v[200:203], v151 offset:20480
	ds_read_b128 v[204:207], v151 offset:21504
	ds_read_b128 v[208:211], v151 offset:22528
	ds_read_b128 v[212:215], v151 offset:23552
	global_load_lds_dwordx4 v[148:149], off
	s_add_i32 m0, s53, 0x2000
	s_add_u32 s54, s16, 0x20000
	v_lshl_add_u64 v[216:217], s[16:17], 0, v[136:137]
	s_addc_u32 s55, s17, 0
	s_add_i32 s53, s58, s59
	global_load_lds_dwordx4 v[216:217], off
	v_lshl_add_u64 v[218:219], s[54:55], 0, v[132:133]
	s_mov_b32 m0, s53
	v_lshl_add_u64 v[220:221], s[18:19], 0, v[134:135]
	global_load_lds_dwordx4 v[218:219], off
	v_lshl_add_u64 v[218:219], s[54:55], 0, v[136:137]
	s_add_i32 m0, s53, 0x2000
	s_nop 0
	global_load_lds_dwordx4 v[218:219], off
	v_lshl_add_u64 v[218:219], s[18:19], 0, v[130:131]
	s_mov_b32 m0, s36
	s_nop 0
	global_load_lds_dwordx4 v[218:219], off
	s_mov_b32 m0, s37
	s_nop 0
	global_load_lds_dwordx4 v[220:221], off
	s_waitcnt vmcnt(8)
	s_waitcnt lgkmcnt(0)
	s_setprio 1
	s_barrier
; #define PG8_STAGE(bufoff, gbase, voff) do { _Pragma("unroll") for (int _i = 0; _i < 2; ++_i) \
;         __builtin_amdgcn_global_load_lds((const unsigned*)((const char*)(gbase) + (voff)[_i]), (LAS unsigned*)(lds + (bufoff) + ldsw + _i * 8192), 16, 0, 0); } while (0)
; #define PG8_LDA(dst, b, h) do { _Pragma("unroll") for (int m = 0; m < 4; ++m) _Pragma("unroll") for (int k = 0; k < 2; ++k) dst[m][k] = *(const LAS bf16x8*)(lds + PG8_SA(b, h) + aoff + m * 2048 + k * 1024); } while (0)
; #define PG8_LDB(dst, b, h) do { _Pragma("unroll") for (int n = 0; n < 2; ++n) _Pragma("unroll") for (int k = 0; k < 2; ++k) dst[n][k] = *(const LAS bf16x8*)(lds + PG8_SB(b, h) + boff + n * 2048 + k * 1024); } while (0)
; #define PG8_MMA(ai, bj, At, Bt) do { __builtin_amdgcn_s_setprio(1); _Pragma("unroll") for (int m = 0; m < 4; ++m) _Pragma("unroll") for (int n = 0; n < 2; ++n) _Pragma("unroll") for (int k = 0; k < 2; ++k) \
;         acc[ai][bj][m][n] = __builtin_amdgcn_mfma_f32_16x16x32_bf16(Bt[n][k], At[m][k], acc[ai][bj][m][n], 0, 0, 0); __builtin_amdgcn_s_setprio(0); } while (0)
; #define PG8_WAIT_V(n) asm volatile("s_waitcnt vmcnt(" #n ")" ::: "memory")
; #define PG8_WAIT_L(n) asm volatile("s_waitcnt lgkmcnt(" #n ")" ::: "memory")
; #define PG8_BAR __builtin_amdgcn_s_barrier()
; #define PG8_SCHED __builtin_amdgcn_sched_barrier(0)
; template <class Epi, class Sched, int LDA, int LDB, bool ALIGN_EPI = true>
; __device__ __forceinline__ void gemm_phase(LAS unsigned char* lds, const Gemm g, const Sched& S, const Epi& E, int wave) {
;     ...
;             PG8_WAIT_V(8); PG8_WAIT_L(0); PG8_BAR; PG8_MMA(1, 0, At, B0); PG8_MMA(1, 1, At, B1); PG8_BAR; PG8_SCHED;
;             PG8_LDB(B0, 1, 0); PG8_LDB(B1, 1, 1); PG8_SCHED; PG8_LDA(At, 1, 0); PG8_STAGE(PG8_SA(0, 1), a2 + hstepA, voffA);
;             PG8_WAIT_V(8); PG8_WAIT_L(0); PG8_BAR; PG8_MMA(0, 0, At, B0); PG8_MMA(0, 1, At, B1); PG8_BAR; PG8_SCHED;
	v_mfma_f32_16x16x32_bf16 v[94:97], v[144:147], v[184:187], v[94:97]
	v_mfma_f32_16x16x32_bf16 v[94:97], v[152:155], v[188:191], v[94:97]
	v_mfma_f32_16x16x32_bf16 v[90:93], v[156:159], v[184:187], v[90:93]
	v_mfma_f32_16x16x32_bf16 v[90:93], v[160:163], v[188:191], v[90:93]
	v_mfma_f32_16x16x32_bf16 v[86:89], v[144:147], v[192:195], v[86:89]
	v_mfma_f32_16x16x32_bf16 v[86:89], v[152:155], v[196:199], v[86:89]
	v_mfma_f32_16x16x32_bf16 v[82:85], v[156:159], v[192:195], v[82:85]
	v_mfma_f32_16x16x32_bf16 v[82:85], v[160:163], v[196:199], v[82:85]
	v_mfma_f32_16x16x32_bf16 v[78:81], v[144:147], v[200:203], v[78:81]
	v_mfma_f32_16x16x32_bf16 v[78:81], v[152:155], v[204:207], v[78:81]
	v_mfma_f32_16x16x32_bf16 v[74:77], v[156:159], v[200:203], v[74:77]
	v_mfma_f32_16x16x32_bf16 v[74:77], v[160:163], v[204:207], v[74:77]
	v_mfma_f32_16x16x32_bf16 v[70:73], v[144:147], v[208:211], v[70:73]
	v_mfma_f32_16x16x32_bf16 v[70:73], v[152:155], v[212:215], v[70:73]
	v_mfma_f32_16x16x32_bf16 v[66:69], v[156:159], v[208:211], v[66:69]
	v_mfma_f32_16x16x32_bf16 v[66:69], v[160:163], v[212:215], v[66:69]
	v_mfma_f32_16x16x32_bf16 v[30:33], v[164:167], v[184:187], v[30:33]
	v_mfma_f32_16x16x32_bf16 v[30:33], v[168:171], v[188:191], v[30:33]
	v_mfma_f32_16x16x32_bf16 v[26:29], v[172:175], v[184:187], v[26:29]
	v_mfma_f32_16x16x32_bf16 v[26:29], v[180:183], v[188:191], v[26:29]
	v_mfma_f32_16x16x32_bf16 v[22:25], v[164:167], v[192:195], v[22:25]
	v_mfma_f32_16x16x32_bf16 v[22:25], v[168:171], v[196:199], v[22:25]
	v_mfma_f32_16x16x32_bf16 v[18:21], v[172:175], v[192:195], v[18:21]
	v_mfma_f32_16x16x32_bf16 v[18:21], v[180:183], v[196:199], v[18:21]
	v_mfma_f32_16x16x32_bf16 v[14:17], v[164:167], v[200:203], v[14:17]
	v_mfma_f32_16x16x32_bf16 v[14:17], v[168:171], v[204:207], v[14:17]
	v_mfma_f32_16x16x32_bf16 v[10:13], v[172:175], v[200:203], v[10:13]
	v_mfma_f32_16x16x32_bf16 v[10:13], v[180:183], v[204:207], v[10:13]
	v_mfma_f32_16x16x32_bf16 v[6:9], v[164:167], v[208:211], v[6:9]
	v_mfma_f32_16x16x32_bf16 v[6:9], v[168:171], v[212:215], v[6:9]
	v_mfma_f32_16x16x32_bf16 v[2:5], v[172:175], v[208:211], v[2:5]
	v_mfma_f32_16x16x32_bf16 v[2:5], v[180:183], v[212:215], v[2:5]
	s_barrier
	s_setprio 0
	ds_read_b128 v[184:187], v151 offset:32768
	ds_read_b128 v[188:191], v151 offset:33792
	ds_read_b128 v[192:195], v151 offset:34816
	ds_read_b128 v[196:199], v151 offset:35840
	ds_read_b128 v[200:203], v151 offset:36864
	ds_read_b128 v[204:207], v151 offset:37888
	ds_read_b128 v[208:211], v151 offset:38912
	ds_read_b128 v[212:215], v151 offset:39936
	s_add_i32 s53, 0, 0x18000
	v_add_u32_e32 v0, s53, v150
	s_add_i32 s54, 0, 0x1c000
	ds_read_b128 v[144:147], v0
	ds_read_b128 v[152:155], v0 offset:1024
	ds_read_b128 v[156:159], v0 offset:2048
	ds_read_b128 v[160:163], v0 offset:3072
	v_add_u32_e32 v0, s54, v150
	ds_read_b128 v[164:167], v0
	ds_read_b128 v[168:171], v0 offset:1024
	ds_read_b128 v[172:175], v0 offset:2048
	ds_read_b128 v[180:183], v0 offset:3072
	s_add_u32 s18, s18, 0x20000
	s_addc_u32 s19, s19, 0
	s_mov_b32 m0, s38
	v_lshl_add_u64 v[222:223], s[18:19], 0, v[130:131]
	global_load_lds_dwordx4 v[222:223], off
	v_lshl_add_u64 v[222:223], s[18:19], 0, v[134:135]
	s_mov_b32 m0, s39
	s_nop 0
	global_load_lds_dwordx4 v[222:223], off
	s_waitcnt vmcnt(8)
	s_waitcnt lgkmcnt(0)
	s_setprio 1
	s_barrier
	v_mfma_f32_16x16x32_bf16 v[126:129], v[144:147], v[184:187], v[126:129]
	v_mfma_f32_16x16x32_bf16 v[126:129], v[152:155], v[188:191], v[126:129]
	v_mfma_f32_16x16x32_bf16 v[122:125], v[156:159], v[184:187], v[122:125]
	v_mfma_f32_16x16x32_bf16 v[122:125], v[160:163], v[188:191], v[122:125]
	v_mfma_f32_16x16x32_bf16 v[118:121], v[144:147], v[192:195], v[118:121]
	v_mfma_f32_16x16x32_bf16 v[118:121], v[152:155], v[196:199], v[118:121]
	v_mfma_f32_16x16x32_bf16 v[114:117], v[156:159], v[192:195], v[114:117]
	v_mfma_f32_16x16x32_bf16 v[114:117], v[160:163], v[196:199], v[114:117]
	v_mfma_f32_16x16x32_bf16 v[110:113], v[144:147], v[200:203], v[110:113]
	v_mfma_f32_16x16x32_bf16 v[110:113], v[152:155], v[204:207], v[110:113]
	v_mfma_f32_16x16x32_bf16 v[106:109], v[156:159], v[200:203], v[106:109]
	v_mfma_f32_16x16x32_bf16 v[106:109], v[160:163], v[204:207], v[106:109]
	v_mfma_f32_16x16x32_bf16 v[102:105], v[144:147], v[208:211], v[102:105]
	v_mfma_f32_16x16x32_bf16 v[102:105], v[152:155], v[212:215], v[102:105]
	v_mfma_f32_16x16x32_bf16 v[98:101], v[156:159], v[208:211], v[98:101]
	v_mfma_f32_16x16x32_bf16 v[98:101], v[160:163], v[212:215], v[98:101]
	v_mfma_f32_16x16x32_bf16 v[62:65], v[164:167], v[184:187], v[62:65]
	v_mfma_f32_16x16x32_bf16 v[62:65], v[168:171], v[188:191], v[62:65]
	v_mfma_f32_16x16x32_bf16 v[58:61], v[172:175], v[184:187], v[58:61]
	v_mfma_f32_16x16x32_bf16 v[58:61], v[180:183], v[188:191], v[58:61]
	v_mfma_f32_16x16x32_bf16 v[54:57], v[164:167], v[192:195], v[54:57]
	v_mfma_f32_16x16x32_bf16 v[54:57], v[168:171], v[196:199], v[54:57]
	v_mfma_f32_16x16x32_bf16 v[50:53], v[172:175], v[192:195], v[50:53]
	v_mfma_f32_16x16x32_bf16 v[50:53], v[180:183], v[196:199], v[50:53]
	v_mfma_f32_16x16x32_bf16 v[46:49], v[164:167], v[200:203], v[46:49]
	v_mfma_f32_16x16x32_bf16 v[46:49], v[168:171], v[204:207], v[46:49]
	v_mfma_f32_16x16x32_bf16 v[42:45], v[172:175], v[200:203], v[42:45]
	v_mfma_f32_16x16x32_bf16 v[42:45], v[180:183], v[204:207], v[42:45]
	v_mfma_f32_16x16x32_bf16 v[38:41], v[164:167], v[208:211], v[38:41]
	v_mfma_f32_16x16x32_bf16 v[38:41], v[168:171], v[212:215], v[38:41]
	v_mfma_f32_16x16x32_bf16 v[34:37], v[172:175], v[208:211], v[34:37]
	v_mfma_f32_16x16x32_bf16 v[34:37], v[180:183], v[212:215], v[34:37]
	s_barrier
; #define PG8_STAGE(bufoff, gbase, voff) do { _Pragma("unroll") for (int _i = 0; _i < 2; ++_i) \
;         __builtin_amdgcn_global_load_lds((const unsigned*)((const char*)(gbase) + (voff)[_i]), (LAS unsigned*)(lds + (bufoff) + ldsw + _i * 8192), 16, 0, 0); } while (0)
; #define PG8_LDA(dst, b, h) do { _Pragma("unroll") for (int m = 0; m < 4; ++m) _Pragma("unroll") for (int k = 0; k < 2; ++k) dst[m][k] = *(const LAS bf16x8*)(lds + PG8_SA(b, h) + aoff + m * 2048 + k * 1024); } while (0)
; #define PG8_MMA(ai, bj, At, Bt) do { __builtin_amdgcn_s_setprio(1); _Pragma("unroll") for (int m = 0; m < 4; ++m) _Pragma("unroll") for (int n = 0; n < 2; ++n) _Pragma("unroll") for (int k = 0; k < 2; ++k) \
;         acc[ai][bj][m][n] = __builtin_amdgcn_mfma_f32_16x16x32_bf16(Bt[n][k], At[m][k], acc[ai][bj][m][n], 0, 0, 0); __builtin_amdgcn_s_setprio(0); } while (0)
; #define PG8_WAIT_V(n) asm volatile("s_waitcnt vmcnt(" #n ")" ::: "memory")
; #define PG8_WAIT_L(n) asm volatile("s_waitcnt lgkmcnt(" #n ")" ::: "memory")
; #define PG8_BAR __builtin_amdgcn_s_barrier()
; #define PG8_SCHED __builtin_amdgcn_sched_barrier(0)
; template <class Epi, class Sched, int LDA, int LDB, bool ALIGN_EPI = true>
; __device__ __forceinline__ void gemm_phase(LAS unsigned char* lds, const Gemm g, const Sched& S, const Epi& E, int wave) {
;     ...
;             PG8_LDA(At, 1, 1); PG8_STAGE(PG8_SB(1, 0), b3, voffB); PG8_STAGE(PG8_SB(1, 1), b3 + hstepB, voffB); PG8_STAGE(PG8_SA(1, 0), a3, voffA);
;             PG8_WAIT_V(8); PG8_WAIT_L(0); PG8_BAR; PG8_MMA(1, 0, At, B0); PG8_MMA(1, 1, At, B1); PG8_BAR; PG8_SCHED;
;         }
;         if constexpr (ALIGN_EPI) { if (wr == 0) PG8_BAR; }
	s_setprio 0
	s_add_i32 s18, s53, s59
	v_lshl_add_u64 v[148:149], v[148:149], 0, s[70:71]
	s_mov_b32 m0, s18
	ds_read_b128 v[184:187], v151 offset:49152
	ds_read_b128 v[188:191], v151 offset:50176
	ds_read_b128 v[192:195], v151 offset:51200
	ds_read_b128 v[196:199], v151 offset:52224
	ds_read_b128 v[200:203], v151 offset:53248
	ds_read_b128 v[204:207], v151 offset:54272
	ds_read_b128 v[208:211], v151 offset:55296
	ds_read_b128 v[212:215], v151 offset:56320
	global_load_lds_dwordx4 v[148:149], off
	s_add_i32 m0, s18, 0x2000
	s_add_u32 s16, s16, 0x20080
	v_lshl_add_u64 v[148:149], v[216:217], 0, s[70:71]
	s_addc_u32 s17, s17, 0
	s_add_i32 s18, s54, s59
	global_load_lds_dwordx4 v[148:149], off
	v_lshl_add_u64 v[148:149], s[16:17], 0, v[132:133]
	s_mov_b32 m0, s18
	s_nop 0
	global_load_lds_dwordx4 v[148:149], off
	v_lshl_add_u64 v[148:149], s[16:17], 0, v[136:137]
	s_add_i32 m0, s18, 0x2000
	s_nop 0
	global_load_lds_dwordx4 v[148:149], off
	v_lshl_add_u64 v[148:149], v[218:219], 0, s[70:71]
	s_mov_b32 m0, s46
	s_nop 0
	global_load_lds_dwordx4 v[148:149], off
	v_lshl_add_u64 v[148:149], v[220:221], 0, s[70:71]
	s_mov_b32 m0, s47
	s_nop 0
	global_load_lds_dwordx4 v[148:149], off
	s_waitcnt vmcnt(8)
	s_waitcnt lgkmcnt(0)
	s_setprio 1
	s_barrier
	v_mfma_f32_16x16x32_bf16 v[94:97], v[144:147], v[184:187], v[94:97]
	v_mfma_f32_16x16x32_bf16 v[94:97], v[152:155], v[188:191], v[94:97]
	v_mfma_f32_16x16x32_bf16 v[90:93], v[156:159], v[184:187], v[90:93]
	v_mfma_f32_16x16x32_bf16 v[90:93], v[160:163], v[188:191], v[90:93]
	v_mfma_f32_16x16x32_bf16 v[86:89], v[144:147], v[192:195], v[86:89]
	v_mfma_f32_16x16x32_bf16 v[86:89], v[152:155], v[196:199], v[86:89]
	v_mfma_f32_16x16x32_bf16 v[82:85], v[156:159], v[192:195], v[82:85]
	v_mfma_f32_16x16x32_bf16 v[82:85], v[160:163], v[196:199], v[82:85]
	v_mfma_f32_16x16x32_bf16 v[78:81], v[144:147], v[200:203], v[78:81]
	v_mfma_f32_16x16x32_bf16 v[78:81], v[152:155], v[204:207], v[78:81]
	v_mfma_f32_16x16x32_bf16 v[74:77], v[156:159], v[200:203], v[74:77]
	v_mfma_f32_16x16x32_bf16 v[74:77], v[160:163], v[204:207], v[74:77]
	v_mfma_f32_16x16x32_bf16 v[70:73], v[144:147], v[208:211], v[70:73]
	v_mfma_f32_16x16x32_bf16 v[70:73], v[152:155], v[212:215], v[70:73]
	v_mfma_f32_16x16x32_bf16 v[66:69], v[156:159], v[208:211], v[66:69]
	v_mfma_f32_16x16x32_bf16 v[66:69], v[160:163], v[212:215], v[66:69]
	v_mfma_f32_16x16x32_bf16 v[30:33], v[164:167], v[184:187], v[30:33]
	v_mfma_f32_16x16x32_bf16 v[30:33], v[168:171], v[188:191], v[30:33]
	v_mfma_f32_16x16x32_bf16 v[26:29], v[172:175], v[184:187], v[26:29]
	v_mfma_f32_16x16x32_bf16 v[26:29], v[180:183], v[188:191], v[26:29]
	v_mfma_f32_16x16x32_bf16 v[22:25], v[164:167], v[192:195], v[22:25]
	v_mfma_f32_16x16x32_bf16 v[22:25], v[168:171], v[196:199], v[22:25]
	v_mfma_f32_16x16x32_bf16 v[18:21], v[172:175], v[192:195], v[18:21]
	v_mfma_f32_16x16x32_bf16 v[18:21], v[180:183], v[196:199], v[18:21]
	v_mfma_f32_16x16x32_bf16 v[14:17], v[164:167], v[200:203], v[14:17]
	v_mfma_f32_16x16x32_bf16 v[14:17], v[168:171], v[204:207], v[14:17]
	v_mfma_f32_16x16x32_bf16 v[10:13], v[172:175], v[200:203], v[10:13]
	v_mfma_f32_16x16x32_bf16 v[10:13], v[180:183], v[204:207], v[10:13]
	v_mfma_f32_16x16x32_bf16 v[6:9], v[164:167], v[208:211], v[6:9]
	v_mfma_f32_16x16x32_bf16 v[6:9], v[168:171], v[212:215], v[6:9]
	v_mfma_f32_16x16x32_bf16 v[2:5], v[172:175], v[208:211], v[2:5]
	v_mfma_f32_16x16x32_bf16 v[2:5], v[180:183], v[212:215], v[2:5]
	s_barrier
	s_setprio 0
	s_add_i32 s52, s52, 2
	s_add_u32 s14, s14, 0x100
	s_addc_u32 s15, s15, 0
	s_add_u32 s45, s45, 0x100
	s_addc_u32 s51, s51, 0
	s_cmp_gt_u32 s52, 5
	s_cbranch_scc0 .LBB0_2619
	v_readlane_b32 s14, v252, 14
	v_readlane_b32 s15, v252, 15
	s_and_b64 vcc, exec, s[14:15]
	s_cbranch_vccz .LBB0_2622
	s_barrier

; #define PG8_STAGE(bufoff, gbase, voff) do { _Pragma("unroll") for (int _i = 0; _i < 2; ++_i) \
;         __builtin_amdgcn_global_load_lds((const unsigned*)((const char*)(gbase) + (voff)[_i]), (LAS unsigned*)(lds + (bufoff) + ldsw + _i * 8192), 16, 0, 0); } while (0)
; #define PG8_LDA(dst, b, h) do { _Pragma("unroll") for (int m = 0; m < 4; ++m) _Pragma("unroll") for (int k = 0; k < 2; ++k) dst[m][k] = *(const LAS bf16x8*)(lds + PG8_SA(b, h) + aoff + m * 2048 + k * 1024); } while (0)
; #define PG8_LDB(dst, b, h) do { _Pragma("unroll") for (int n = 0; n < 2; ++n) _Pragma("unroll") for (int k = 0; k < 2; ++k) dst[n][k] = *(const LAS bf16x8*)(lds + PG8_SB(b, h) + boff + n * 2048 + k * 1024); } while (0)
; #define PG8_MMA(ai, bj, At, Bt) do { __builtin_amdgcn_s_setprio(1); _Pragma("unroll") for (int m = 0; m < 4; ++m) _Pragma("unroll") for (int n = 0; n < 2; ++n) _Pragma("unroll") for (int k = 0; k < 2; ++k) \
;         acc[ai][bj][m][n] = __builtin_amdgcn_mfma_f32_16x16x32_bf16(Bt[n][k], At[m][k], acc[ai][bj][m][n], 0, 0, 0); __builtin_amdgcn_s_setprio(0); } while (0)
; #define PG8_WAIT_V(n) asm volatile("s_waitcnt vmcnt(" #n ")" ::: "memory")
; #define PG8_WAIT_L(n) asm volatile("s_waitcnt lgkmcnt(" #n ")" ::: "memory")
; #define PG8_BAR __builtin_amdgcn_s_barrier()
; template <class Epi, class Sched, int LDA, int LDB, bool ALIGN_EPI = true>
; __device__ __forceinline__ void gemm_phase(LAS unsigned char* lds, const Gemm g, const Sched& S, const Epi& E, int wave) {
;     ...
;         for (int t = 0; t < nt; t += 2) {
;             const bool last = (t == nt - 2);
;             const char* a1 = cA + (size_t)(t + 1) * kstep;
;             const char* a2 = last ? nA : cA + (size_t)(t + 2) * kstep; const char* b2 = last ? nB : cB + (size_t)(t + 2) * kstep;
;             const char* a3 = a2 + kstep; const char* b3 = b2 + kstep;
;             PG8_LDB(B0, 0, 0); PG8_LDB(B1, 0, 1); PG8_SCHED; PG8_LDA(At, 0, 0); PG8_STAGE(PG8_SA(1, 1), a1 + hstepA, voffA);
;             PG8_WAIT_V(8); PG8_WAIT_L(0); PG8_BAR; PG8_MMA(0, 0, At, B0); PG8_MMA(0, 1, At, B1); PG8_BAR; PG8_SCHED;
;             PG8_LDA(At, 0, 1); PG8_STAGE(PG8_SB(0, 0), b2, voffB); PG8_STAGE(PG8_SB(0, 1), b2 + hstepB, voffB); PG8_STAGE(PG8_SA(0, 0), a2, voffA);
;             PG8_WAIT_V(8); PG8_WAIT_L(0); PG8_BAR; PG8_MMA(1, 0, At, B0); PG8_MMA(1, 1, At, B1); PG8_BAR; PG8_SCHED;
.LBB0_2649:
	ds_read_b128 v[180:183], v163
	ds_read_b128 v[184:187], v163 offset:1024
	ds_read_b128 v[188:191], v163 offset:2048
	ds_read_b128 v[192:195], v163 offset:3072
	ds_read_b128 v[196:199], v163 offset:4096
	ds_read_b128 v[200:203], v163 offset:5120
	ds_read_b128 v[204:207], v163 offset:6144
	ds_read_b128 v[208:211], v163 offset:7168
	s_add_u32 s18, s16, 0xfffe0080
	s_addc_u32 s19, s17, -1
	s_add_i32 s48, 0, 0x10000
	s_cmp_eq_u32 s47, 4
	s_cselect_b32 s25, s7, s19
	s_cselect_b32 s24, s13, s18
	s_cselect_b32 s19, s3, s46
	s_cselect_b32 s18, s44, s45
	s_add_i32 s50, 0, 0x14000
	v_add_u32_e32 v152, s48, v161
	v_add_u32_e32 v172, s50, v161
	ds_read_b128 v[130:133], v152
	ds_read_b128 v[134:137], v152 offset:1024
	ds_read_b128 v[148:151], v152 offset:2048
	ds_read_b128 v[152:155], v152 offset:3072
	ds_read_b128 v[156:159], v172
	ds_read_b128 v[164:167], v172 offset:1024
	ds_read_b128 v[168:171], v172 offset:2048
	ds_read_b128 v[172:175], v172 offset:3072
	v_lshl_add_u64 v[212:213], s[16:17], 0, v[144:145]
	s_add_i32 m0, s15, 0xc000
	s_nop 0
	global_load_lds_dwordx4 v[212:213], off
	v_lshl_add_u64 v[212:213], s[16:17], 0, v[146:147]
	s_add_i32 m0, s15, 0xe000
	s_nop 0
	global_load_lds_dwordx4 v[212:213], off
	s_waitcnt vmcnt(8)
	s_waitcnt lgkmcnt(0)
	s_setprio 1
	s_barrier
	v_mfma_f32_16x16x32_bf16 v[126:129], v[130:133], v[180:183], v[126:129]
	v_mfma_f32_16x16x32_bf16 v[126:129], v[134:137], v[184:187], v[126:129]
	v_mfma_f32_16x16x32_bf16 v[122:125], v[148:151], v[180:183], v[122:125]
	v_mfma_f32_16x16x32_bf16 v[122:125], v[152:155], v[184:187], v[122:125]
	v_mfma_f32_16x16x32_bf16 v[110:113], v[130:133], v[188:191], v[110:113]
	v_mfma_f32_16x16x32_bf16 v[110:113], v[134:137], v[192:195], v[110:113]
	v_mfma_f32_16x16x32_bf16 v[106:109], v[148:151], v[188:191], v[106:109]
	v_mfma_f32_16x16x32_bf16 v[106:109], v[152:155], v[192:195], v[106:109]
	v_mfma_f32_16x16x32_bf16 v[94:97], v[130:133], v[196:199], v[94:97]
	v_mfma_f32_16x16x32_bf16 v[94:97], v[134:137], v[200:203], v[94:97]
	v_mfma_f32_16x16x32_bf16 v[90:93], v[148:151], v[196:199], v[90:93]
	v_mfma_f32_16x16x32_bf16 v[90:93], v[152:155], v[200:203], v[90:93]
	v_mfma_f32_16x16x32_bf16 v[78:81], v[130:133], v[204:207], v[78:81]
	v_mfma_f32_16x16x32_bf16 v[78:81], v[134:137], v[208:211], v[78:81]
	v_mfma_f32_16x16x32_bf16 v[74:77], v[148:151], v[204:207], v[74:77]
	v_mfma_f32_16x16x32_bf16 v[74:77], v[152:155], v[208:211], v[74:77]
	v_mfma_f32_16x16x32_bf16 v[118:121], v[156:159], v[180:183], v[118:121]
	v_mfma_f32_16x16x32_bf16 v[118:121], v[164:167], v[184:187], v[118:121]
	v_mfma_f32_16x16x32_bf16 v[114:117], v[168:171], v[180:183], v[114:117]
	v_mfma_f32_16x16x32_bf16 v[114:117], v[172:175], v[184:187], v[114:117]
	v_mfma_f32_16x16x32_bf16 v[102:105], v[156:159], v[188:191], v[102:105]
	v_mfma_f32_16x16x32_bf16 v[102:105], v[164:167], v[192:195], v[102:105]
	v_mfma_f32_16x16x32_bf16 v[98:101], v[168:171], v[188:191], v[98:101]
	v_mfma_f32_16x16x32_bf16 v[98:101], v[172:175], v[192:195], v[98:101]
	v_mfma_f32_16x16x32_bf16 v[86:89], v[156:159], v[196:199], v[86:89]
	v_mfma_f32_16x16x32_bf16 v[86:89], v[164:167], v[200:203], v[86:89]
	v_mfma_f32_16x16x32_bf16 v[82:85], v[168:171], v[196:199], v[82:85]
	v_mfma_f32_16x16x32_bf16 v[82:85], v[172:175], v[200:203], v[82:85]
	v_mfma_f32_16x16x32_bf16 v[70:73], v[156:159], v[204:207], v[70:73]
	v_mfma_f32_16x16x32_bf16 v[70:73], v[164:167], v[208:211], v[70:73]
	v_mfma_f32_16x16x32_bf16 v[66:69], v[168:171], v[204:207], v[66:69]
	v_mfma_f32_16x16x32_bf16 v[66:69], v[172:175], v[208:211], v[66:69]
	s_barrier
	s_setprio 0
	s_add_i32 s48, s48, s51
	v_lshl_add_u64 v[212:213], s[18:19], 0, v[0:1]
	s_mov_b32 m0, s48
	ds_read_b128 v[180:183], v163 offset:16384
	ds_read_b128 v[184:187], v163 offset:17408
	ds_read_b128 v[188:191], v163 offset:18432
	ds_read_b128 v[192:195], v163 offset:19456
	ds_read_b128 v[196:199], v163 offset:20480
	ds_read_b128 v[200:203], v163 offset:21504
	ds_read_b128 v[204:207], v163 offset:22528
	ds_read_b128 v[208:211], v163 offset:23552
	global_load_lds_dwordx4 v[212:213], off
	s_add_i32 m0, s48, 0x2000
	s_add_u32 s48, s18, 0x20000
	v_lshl_add_u64 v[214:215], s[18:19], 0, v[142:143]
	s_addc_u32 s49, s19, 0
	s_add_i32 s50, s50, s51
	global_load_lds_dwordx4 v[214:215], off
	v_lshl_add_u64 v[216:217], s[48:49], 0, v[0:1]
	s_mov_b32 m0, s50
	v_lshl_add_u64 v[218:219], s[24:25], 0, v[140:141]
	global_load_lds_dwordx4 v[216:217], off
	v_lshl_add_u64 v[216:217], s[48:49], 0, v[142:143]
	s_add_i32 m0, s50, 0x2000
	s_nop 0
	global_load_lds_dwordx4 v[216:217], off
	v_lshl_add_u64 v[216:217], s[24:25], 0, v[138:139]
	s_mov_b32 m0, s15
	s_nop 0
	global_load_lds_dwordx4 v[216:217], off
	s_mov_b32 m0, s28
	s_nop 0
	global_load_lds_dwordx4 v[218:219], off
	s_waitcnt vmcnt(8)
	s_waitcnt lgkmcnt(0)
	s_setprio 1
	s_barrier
; #define PG8_STAGE(bufoff, gbase, voff) do { _Pragma("unroll") for (int _i = 0; _i < 2; ++_i) \
;         __builtin_amdgcn_global_load_lds((const unsigned*)((const char*)(gbase) + (voff)[_i]), (LAS unsigned*)(lds + (bufoff) + ldsw + _i * 8192), 16, 0, 0); } while (0)
; #define PG8_LDA(dst, b, h) do { _Pragma("unroll") for (int m = 0; m < 4; ++m) _Pragma("unroll") for (int k = 0; k < 2; ++k) dst[m][k] = *(const LAS bf16x8*)(lds + PG8_SA(b, h) + aoff + m * 2048 + k * 1024); } while (0)
; #define PG8_LDB(dst, b, h) do { _Pragma("unroll") for (int n = 0; n < 2; ++n) _Pragma("unroll") for (int k = 0; k < 2; ++k) dst[n][k] = *(const LAS bf16x8*)(lds + PG8_SB(b, h) + boff + n * 2048 + k * 1024); } while (0)
; #define PG8_MMA(ai, bj, At, Bt) do { __builtin_amdgcn_s_setprio(1); _Pragma("unroll") for (int m = 0; m < 4; ++m) _Pragma("unroll") for (int n = 0; n < 2; ++n) _Pragma("unroll") for (int k = 0; k < 2; ++k) \
;         acc[ai][bj][m][n] = __builtin_amdgcn_mfma_f32_16x16x32_bf16(Bt[n][k], At[m][k], acc[ai][bj][m][n], 0, 0, 0); __builtin_amdgcn_s_setprio(0); } while (0)
; #define PG8_WAIT_V(n) asm volatile("s_waitcnt vmcnt(" #n ")" ::: "memory")
; #define PG8_WAIT_L(n) asm volatile("s_waitcnt lgkmcnt(" #n ")" ::: "memory")
; #define PG8_BAR __builtin_amdgcn_s_barrier()
; #define PG8_SCHED __builtin_amdgcn_sched_barrier(0)
; template <class Epi, class Sched, int LDA, int LDB, bool ALIGN_EPI = true>
; __device__ __forceinline__ void gemm_phase(LAS unsigned char* lds, const Gemm g, const Sched& S, const Epi& E, int wave) {
;     ...
;             PG8_WAIT_V(8); PG8_WAIT_L(0); PG8_BAR; PG8_MMA(1, 0, At, B0); PG8_MMA(1, 1, At, B1); PG8_BAR; PG8_SCHED;
;             PG8_LDB(B0, 1, 0); PG8_LDB(B1, 1, 1); PG8_SCHED; PG8_LDA(At, 1, 0); PG8_STAGE(PG8_SA(0, 1), a2 + hstepA, voffA);
;             PG8_WAIT_V(8); PG8_WAIT_L(0); PG8_BAR; PG8_MMA(0, 0, At, B0); PG8_MMA(0, 1, At, B1); PG8_BAR; PG8_SCHED;
	v_mfma_f32_16x16x32_bf16 v[62:65], v[130:133], v[180:183], v[62:65]
	v_mfma_f32_16x16x32_bf16 v[62:65], v[134:137], v[184:187], v[62:65]
	v_mfma_f32_16x16x32_bf16 v[58:61], v[148:151], v[180:183], v[58:61]
	v_mfma_f32_16x16x32_bf16 v[58:61], v[152:155], v[184:187], v[58:61]
	v_mfma_f32_16x16x32_bf16 v[46:49], v[130:133], v[188:191], v[46:49]
	v_mfma_f32_16x16x32_bf16 v[46:49], v[134:137], v[192:195], v[46:49]
	v_mfma_f32_16x16x32_bf16 v[42:45], v[148:151], v[188:191], v[42:45]
	v_mfma_f32_16x16x32_bf16 v[42:45], v[152:155], v[192:195], v[42:45]
	v_mfma_f32_16x16x32_bf16 v[30:33], v[130:133], v[196:199], v[30:33]
	v_mfma_f32_16x16x32_bf16 v[30:33], v[134:137], v[200:203], v[30:33]
	v_mfma_f32_16x16x32_bf16 v[26:29], v[148:151], v[196:199], v[26:29]
	v_mfma_f32_16x16x32_bf16 v[26:29], v[152:155], v[200:203], v[26:29]
	v_mfma_f32_16x16x32_bf16 v[14:17], v[130:133], v[204:207], v[14:17]
	v_mfma_f32_16x16x32_bf16 v[14:17], v[134:137], v[208:211], v[14:17]
	v_mfma_f32_16x16x32_bf16 v[10:13], v[148:151], v[204:207], v[10:13]
	v_mfma_f32_16x16x32_bf16 v[10:13], v[152:155], v[208:211], v[10:13]
	v_mfma_f32_16x16x32_bf16 v[54:57], v[156:159], v[180:183], v[54:57]
	v_mfma_f32_16x16x32_bf16 v[54:57], v[164:167], v[184:187], v[54:57]
	v_mfma_f32_16x16x32_bf16 v[50:53], v[168:171], v[180:183], v[50:53]
	v_mfma_f32_16x16x32_bf16 v[50:53], v[172:175], v[184:187], v[50:53]
	v_mfma_f32_16x16x32_bf16 v[38:41], v[156:159], v[188:191], v[38:41]
	v_mfma_f32_16x16x32_bf16 v[38:41], v[164:167], v[192:195], v[38:41]
	v_mfma_f32_16x16x32_bf16 v[34:37], v[168:171], v[188:191], v[34:37]
	v_mfma_f32_16x16x32_bf16 v[34:37], v[172:175], v[192:195], v[34:37]
	v_mfma_f32_16x16x32_bf16 v[22:25], v[156:159], v[196:199], v[22:25]
	v_mfma_f32_16x16x32_bf16 v[22:25], v[164:167], v[200:203], v[22:25]
	v_mfma_f32_16x16x32_bf16 v[18:21], v[168:171], v[196:199], v[18:21]
	v_mfma_f32_16x16x32_bf16 v[18:21], v[172:175], v[200:203], v[18:21]
	v_mfma_f32_16x16x32_bf16 v[6:9], v[156:159], v[204:207], v[6:9]
	v_mfma_f32_16x16x32_bf16 v[6:9], v[164:167], v[208:211], v[6:9]
	v_mfma_f32_16x16x32_bf16 v[2:5], v[168:171], v[204:207], v[2:5]
	v_mfma_f32_16x16x32_bf16 v[2:5], v[172:175], v[208:211], v[2:5]
	s_barrier
	s_setprio 0
	ds_read_b128 v[180:183], v163 offset:32768
	ds_read_b128 v[184:187], v163 offset:33792
	ds_read_b128 v[188:191], v163 offset:34816
	ds_read_b128 v[192:195], v163 offset:35840
	ds_read_b128 v[196:199], v163 offset:36864
	ds_read_b128 v[200:203], v163 offset:37888
	ds_read_b128 v[204:207], v163 offset:38912
	ds_read_b128 v[208:211], v163 offset:39936
	s_add_i32 s48, 0, 0x18000
	s_add_i32 s49, 0, 0x1c000
	v_add_u32_e32 v152, s48, v161
	v_add_u32_e32 v172, s49, v161
	ds_read_b128 v[130:133], v152
	ds_read_b128 v[134:137], v152 offset:1024
	ds_read_b128 v[148:151], v152 offset:2048
	ds_read_b128 v[152:155], v152 offset:3072
	ds_read_b128 v[156:159], v172
	ds_read_b128 v[164:167], v172 offset:1024
	ds_read_b128 v[168:171], v172 offset:2048
	ds_read_b128 v[172:175], v172 offset:3072
	s_add_u32 s24, s24, 0x20000
	s_addc_u32 s25, s25, 0
	s_mov_b32 m0, s29
	v_lshl_add_u64 v[220:221], s[24:25], 0, v[138:139]
	global_load_lds_dwordx4 v[220:221], off
	v_lshl_add_u64 v[220:221], s[24:25], 0, v[140:141]
	s_mov_b32 m0, s34
	s_nop 0
	global_load_lds_dwordx4 v[220:221], off
	s_waitcnt vmcnt(8)
	s_waitcnt lgkmcnt(0)
	s_setprio 1
	s_barrier
	v_mfma_f32_16x16x32_bf16 v[126:129], v[130:133], v[180:183], v[126:129]
	v_mfma_f32_16x16x32_bf16 v[126:129], v[134:137], v[184:187], v[126:129]
	v_mfma_f32_16x16x32_bf16 v[122:125], v[148:151], v[180:183], v[122:125]
	v_mfma_f32_16x16x32_bf16 v[122:125], v[152:155], v[184:187], v[122:125]
	v_mfma_f32_16x16x32_bf16 v[110:113], v[130:133], v[188:191], v[110:113]
	v_mfma_f32_16x16x32_bf16 v[110:113], v[134:137], v[192:195], v[110:113]
	v_mfma_f32_16x16x32_bf16 v[106:109], v[148:151], v[188:191], v[106:109]
	v_mfma_f32_16x16x32_bf16 v[106:109], v[152:155], v[192:195], v[106:109]
	v_mfma_f32_16x16x32_bf16 v[94:97], v[130:133], v[196:199], v[94:97]
	v_mfma_f32_16x16x32_bf16 v[94:97], v[134:137], v[200:203], v[94:97]
	v_mfma_f32_16x16x32_bf16 v[90:93], v[148:151], v[196:199], v[90:93]
	v_mfma_f32_16x16x32_bf16 v[90:93], v[152:155], v[200:203], v[90:93]
	v_mfma_f32_16x16x32_bf16 v[78:81], v[130:133], v[204:207], v[78:81]
	v_mfma_f32_16x16x32_bf16 v[78:81], v[134:137], v[208:211], v[78:81]
	v_mfma_f32_16x16x32_bf16 v[74:77], v[148:151], v[204:207], v[74:77]
	v_mfma_f32_16x16x32_bf16 v[74:77], v[152:155], v[208:211], v[74:77]
	v_mfma_f32_16x16x32_bf16 v[118:121], v[156:159], v[180:183], v[118:121]
	v_mfma_f32_16x16x32_bf16 v[118:121], v[164:167], v[184:187], v[118:121]
	v_mfma_f32_16x16x32_bf16 v[114:117], v[168:171], v[180:183], v[114:117]
	v_mfma_f32_16x16x32_bf16 v[114:117], v[172:175], v[184:187], v[114:117]
	v_mfma_f32_16x16x32_bf16 v[102:105], v[156:159], v[188:191], v[102:105]
	v_mfma_f32_16x16x32_bf16 v[102:105], v[164:167], v[192:195], v[102:105]
	v_mfma_f32_16x16x32_bf16 v[98:101], v[168:171], v[188:191], v[98:101]
	v_mfma_f32_16x16x32_bf16 v[98:101], v[172:175], v[192:195], v[98:101]
	v_mfma_f32_16x16x32_bf16 v[86:89], v[156:159], v[196:199], v[86:89]
	v_mfma_f32_16x16x32_bf16 v[86:89], v[164:167], v[200:203], v[86:89]
	v_mfma_f32_16x16x32_bf16 v[82:85], v[168:171], v[196:199], v[82:85]
	v_mfma_f32_16x16x32_bf16 v[82:85], v[172:175], v[200:203], v[82:85]
	v_mfma_f32_16x16x32_bf16 v[70:73], v[156:159], v[204:207], v[70:73]
	v_mfma_f32_16x16x32_bf16 v[70:73], v[164:167], v[208:211], v[70:73]
	v_mfma_f32_16x16x32_bf16 v[66:69], v[168:171], v[204:207], v[66:69]
	v_mfma_f32_16x16x32_bf16 v[66:69], v[172:175], v[208:211], v[66:69]
	s_barrier
; #define PG8_STAGE(bufoff, gbase, voff) do { _Pragma("unroll") for (int _i = 0; _i < 2; ++_i) \
;         __builtin_amdgcn_global_load_lds((const unsigned*)((const char*)(gbase) + (voff)[_i]), (LAS unsigned*)(lds + (bufoff) + ldsw + _i * 8192), 16, 0, 0); } while (0)
; #define PG8_LDA(dst, b, h) do { _Pragma("unroll") for (int m = 0; m < 4; ++m) _Pragma("unroll") for (int k = 0; k < 2; ++k) dst[m][k] = *(const LAS bf16x8*)(lds + PG8_SA(b, h) + aoff + m * 2048 + k * 1024); } while (0)
; #define PG8_MMA(ai, bj, At, Bt) do { __builtin_amdgcn_s_setprio(1); _Pragma("unroll") for (int m = 0; m < 4; ++m) _Pragma("unroll") for (int n = 0; n < 2; ++n) _Pragma("unroll") for (int k = 0; k < 2; ++k) \
;         acc[ai][bj][m][n] = __builtin_amdgcn_mfma_f32_16x16x32_bf16(Bt[n][k], At[m][k], acc[ai][bj][m][n], 0, 0, 0); __builtin_amdgcn_s_setprio(0); } while (0)
; #define PG8_WAIT_V(n) asm volatile("s_waitcnt vmcnt(" #n ")" ::: "memory")
; #define PG8_WAIT_L(n) asm volatile("s_waitcnt lgkmcnt(" #n ")" ::: "memory")
; #define PG8_BAR __builtin_amdgcn_s_barrier()
; #define PG8_SCHED __builtin_amdgcn_sched_barrier(0)
; template <class Epi, class Sched, int LDA, int LDB, bool ALIGN_EPI = true>
; __device__ __forceinline__ void gemm_phase(LAS unsigned char* lds, const Gemm g, const Sched& S, const Epi& E, int wave) {
;     ...
;             PG8_LDA(At, 1, 1); PG8_STAGE(PG8_SB(1, 0), b3, voffB); PG8_STAGE(PG8_SB(1, 1), b3 + hstepB, voffB); PG8_STAGE(PG8_SA(1, 0), a3, voffA);
;             PG8_WAIT_V(8); PG8_WAIT_L(0); PG8_BAR; PG8_MMA(1, 0, At, B0); PG8_MMA(1, 1, At, B1); PG8_BAR; PG8_SCHED;
;         }
;         if constexpr (ALIGN_EPI) { if (wr == 0) PG8_BAR; }
	s_setprio 0
	s_add_i32 s24, s48, s51
	v_lshl_add_u64 v[212:213], v[212:213], 0, s[52:53]
	s_mov_b32 m0, s24
	ds_read_b128 v[180:183], v163 offset:49152
	ds_read_b128 v[184:187], v163 offset:50176
	ds_read_b128 v[188:191], v163 offset:51200
	ds_read_b128 v[192:195], v163 offset:52224
	ds_read_b128 v[196:199], v163 offset:53248
	ds_read_b128 v[200:203], v163 offset:54272
	ds_read_b128 v[204:207], v163 offset:55296
	ds_read_b128 v[208:211], v163 offset:56320
	global_load_lds_dwordx4 v[212:213], off
	s_add_i32 m0, s24, 0x2000
	s_add_u32 s18, s18, 0x20080
	v_lshl_add_u64 v[212:213], v[214:215], 0, s[52:53]
	s_addc_u32 s19, s19, 0
	s_add_i32 s24, s49, s51
	global_load_lds_dwordx4 v[212:213], off
	v_lshl_add_u64 v[212:213], s[18:19], 0, v[0:1]
	s_mov_b32 m0, s24
	s_nop 0
	global_load_lds_dwordx4 v[212:213], off
	v_lshl_add_u64 v[212:213], s[18:19], 0, v[142:143]
	s_add_i32 m0, s24, 0x2000
	s_nop 0
	global_load_lds_dwordx4 v[212:213], off
	v_lshl_add_u64 v[212:213], v[216:217], 0, s[52:53]
	s_mov_b32 m0, s35
	s_nop 0
	global_load_lds_dwordx4 v[212:213], off
	v_lshl_add_u64 v[212:213], v[218:219], 0, s[52:53]
	s_mov_b32 m0, s36
	s_nop 0
	global_load_lds_dwordx4 v[212:213], off
	s_waitcnt vmcnt(8)
	s_waitcnt lgkmcnt(0)
	s_setprio 1
	s_barrier
	v_mfma_f32_16x16x32_bf16 v[62:65], v[130:133], v[180:183], v[62:65]
	v_mfma_f32_16x16x32_bf16 v[62:65], v[134:137], v[184:187], v[62:65]
	v_mfma_f32_16x16x32_bf16 v[58:61], v[148:151], v[180:183], v[58:61]
	v_mfma_f32_16x16x32_bf16 v[58:61], v[152:155], v[184:187], v[58:61]
	v_mfma_f32_16x16x32_bf16 v[46:49], v[130:133], v[188:191], v[46:49]
	v_mfma_f32_16x16x32_bf16 v[46:49], v[134:137], v[192:195], v[46:49]
	v_mfma_f32_16x16x32_bf16 v[42:45], v[148:151], v[188:191], v[42:45]
	v_mfma_f32_16x16x32_bf16 v[42:45], v[152:155], v[192:195], v[42:45]
	v_mfma_f32_16x16x32_bf16 v[30:33], v[130:133], v[196:199], v[30:33]
	v_mfma_f32_16x16x32_bf16 v[30:33], v[134:137], v[200:203], v[30:33]
	v_mfma_f32_16x16x32_bf16 v[26:29], v[148:151], v[196:199], v[26:29]
	v_mfma_f32_16x16x32_bf16 v[26:29], v[152:155], v[200:203], v[26:29]
	v_mfma_f32_16x16x32_bf16 v[14:17], v[130:133], v[204:207], v[14:17]
	v_mfma_f32_16x16x32_bf16 v[14:17], v[134:137], v[208:211], v[14:17]
	v_mfma_f32_16x16x32_bf16 v[10:13], v[148:151], v[204:207], v[10:13]
	v_mfma_f32_16x16x32_bf16 v[10:13], v[152:155], v[208:211], v[10:13]
	v_mfma_f32_16x16x32_bf16 v[54:57], v[156:159], v[180:183], v[54:57]
	v_mfma_f32_16x16x32_bf16 v[54:57], v[164:167], v[184:187], v[54:57]
	v_mfma_f32_16x16x32_bf16 v[50:53], v[168:171], v[180:183], v[50:53]
	v_mfma_f32_16x16x32_bf16 v[50:53], v[172:175], v[184:187], v[50:53]
	v_mfma_f32_16x16x32_bf16 v[38:41], v[156:159], v[188:191], v[38:41]
	v_mfma_f32_16x16x32_bf16 v[38:41], v[164:167], v[192:195], v[38:41]
	v_mfma_f32_16x16x32_bf16 v[34:37], v[168:171], v[188:191], v[34:37]
	v_mfma_f32_16x16x32_bf16 v[34:37], v[172:175], v[192:195], v[34:37]
	v_mfma_f32_16x16x32_bf16 v[22:25], v[156:159], v[196:199], v[22:25]
	v_mfma_f32_16x16x32_bf16 v[22:25], v[164:167], v[200:203], v[22:25]
	v_mfma_f32_16x16x32_bf16 v[18:21], v[168:171], v[196:199], v[18:21]
	v_mfma_f32_16x16x32_bf16 v[18:21], v[172:175], v[200:203], v[18:21]
	v_mfma_f32_16x16x32_bf16 v[6:9], v[156:159], v[204:207], v[6:9]
	v_mfma_f32_16x16x32_bf16 v[6:9], v[164:167], v[208:211], v[6:9]
	v_mfma_f32_16x16x32_bf16 v[2:5], v[168:171], v[204:207], v[2:5]
	v_mfma_f32_16x16x32_bf16 v[2:5], v[172:175], v[208:211], v[2:5]
	s_barrier
	s_setprio 0
	s_add_i32 s47, s47, 2
	s_add_u32 s16, s16, 0x100
	s_addc_u32 s17, s17, 0
	s_add_u32 s45, s45, 0x100
	s_addc_u32 s46, s46, 0
	s_cmp_gt_u32 s47, 5
	s_cbranch_scc0 .LBB0_2649
	v_readlane_b32 s16, v252, 14
	v_readlane_b32 s17, v252, 15
	s_and_b64 vcc, exec, s[16:17]
	s_cbranch_vccz .LBB0_2652
	s_barrier

; #define PG8_STAGE(bufoff, gbase, voff) do { _Pragma("unroll") for (int _i = 0; _i < 2; ++_i) \
;         __builtin_amdgcn_global_load_lds((const unsigned*)((const char*)(gbase) + (voff)[_i]), (LAS unsigned*)(lds + (bufoff) + ldsw + _i * 8192), 16, 0, 0); } while (0)
; #define PG8_LDA(dst, b, h) do { _Pragma("unroll") for (int m = 0; m < 4; ++m) _Pragma("unroll") for (int k = 0; k < 2; ++k) dst[m][k] = *(const LAS bf16x8*)(lds + PG8_SA(b, h) + aoff + m * 2048 + k * 1024); } while (0)
; #define PG8_LDB(dst, b, h) do { _Pragma("unroll") for (int n = 0; n < 2; ++n) _Pragma("unroll") for (int k = 0; k < 2; ++k) dst[n][k] = *(const LAS bf16x8*)(lds + PG8_SB(b, h) + boff + n * 2048 + k * 1024); } while (0)
; #define PG8_MMA(ai, bj, At, Bt) do { __builtin_amdgcn_s_setprio(1); _Pragma("unroll") for (int m = 0; m < 4; ++m) _Pragma("unroll") for (int n = 0; n < 2; ++n) _Pragma("unroll") for (int k = 0; k < 2; ++k) \
;         acc[ai][bj][m][n] = __builtin_amdgcn_mfma_f32_16x16x32_bf16(Bt[n][k], At[m][k], acc[ai][bj][m][n], 0, 0, 0); __builtin_amdgcn_s_setprio(0); } while (0)
; #define PG8_WAIT_V(n) asm volatile("s_waitcnt vmcnt(" #n ")" ::: "memory")
; #define PG8_WAIT_L(n) asm volatile("s_waitcnt lgkmcnt(" #n ")" ::: "memory")
; #define PG8_BAR __builtin_amdgcn_s_barrier()
; template <class Epi, class Sched, int LDA, int LDB, bool ALIGN_EPI = true>
; __device__ __forceinline__ void gemm_phase(LAS unsigned char* lds, const Gemm g, const Sched& S, const Epi& E, int wave) {
;     ...
;         for (int t = 0; t < nt; t += 2) {
;             const bool last = (t == nt - 2);
;             const char* a1 = cA + (size_t)(t + 1) * kstep;
;             const char* a2 = last ? nA : cA + (size_t)(t + 2) * kstep; const char* b2 = last ? nB : cB + (size_t)(t + 2) * kstep;
;             const char* a3 = a2 + kstep; const char* b3 = b2 + kstep;
;             PG8_LDB(B0, 0, 0); PG8_LDB(B1, 0, 1); PG8_SCHED; PG8_LDA(At, 0, 0); PG8_STAGE(PG8_SA(1, 1), a1 + hstepA, voffA);
;             PG8_WAIT_V(8); PG8_WAIT_L(0); PG8_BAR; PG8_MMA(0, 0, At, B0); PG8_MMA(0, 1, At, B1); PG8_BAR; PG8_SCHED;
;             PG8_LDA(At, 0, 1); PG8_STAGE(PG8_SB(0, 0), b2, voffB); PG8_STAGE(PG8_SB(0, 1), b2 + hstepB, voffB); PG8_STAGE(PG8_SA(0, 0), a2, voffA);
;             PG8_WAIT_V(8); PG8_WAIT_L(0); PG8_BAR; PG8_MMA(1, 0, At, B0); PG8_MMA(1, 1, At, B1); PG8_BAR; PG8_SCHED;
.LBB0_4715:
	ds_read_b128 v[184:187], v155
	ds_read_b128 v[188:191], v155 offset:1024
	ds_read_b128 v[192:195], v155 offset:2048
	ds_read_b128 v[196:199], v155 offset:3072
	ds_read_b128 v[200:203], v155 offset:4096
	ds_read_b128 v[204:207], v155 offset:5120
	ds_read_b128 v[208:211], v155 offset:6144
	ds_read_b128 v[212:215], v155 offset:7168
	s_add_i32 s49, s24, 2
	s_add_u32 s25, s18, 0xfff80080
	s_addc_u32 s28, s19, -1
	s_add_i32 s50, 0, 0x10000
	s_cmp_eq_u32 s17, s24
	s_cselect_b32 s29, s1, s28
	s_cselect_b32 s28, s7, s25
	v_add_u32_e32 v0, s50, v153
	s_cselect_b32 s25, s3, s45
	s_cselect_b32 s24, s15, s44
	s_add_i32 s52, 0, 0x14000
	ds_read_b128 v[144:147], v0
	ds_read_b128 v[148:151], v0 offset:1024
	ds_read_b128 v[156:159], v0 offset:2048
	ds_read_b128 v[160:163], v0 offset:3072
	v_add_u32_e32 v0, s52, v153
	ds_read_b128 v[164:167], v0
	ds_read_b128 v[168:171], v0 offset:1024
	ds_read_b128 v[172:175], v0 offset:2048
	ds_read_b128 v[180:183], v0 offset:3072
	v_lshl_add_u64 v[216:217], s[18:19], 0, v[140:141]
	s_add_i32 m0, s27, 0xc000
	s_nop 0
	global_load_lds_dwordx4 v[216:217], off
	v_lshl_add_u64 v[216:217], s[18:19], 0, v[142:143]
	s_add_i32 m0, s27, 0xe000
	s_nop 0
	global_load_lds_dwordx4 v[216:217], off
	s_waitcnt vmcnt(8)
	s_waitcnt lgkmcnt(0)
	s_setprio 1
	s_barrier
	v_mfma_f32_16x16x32_bf16 v[126:129], v[144:147], v[184:187], v[126:129]
	v_mfma_f32_16x16x32_bf16 v[126:129], v[148:151], v[188:191], v[126:129]
	v_mfma_f32_16x16x32_bf16 v[122:125], v[156:159], v[184:187], v[122:125]
	v_mfma_f32_16x16x32_bf16 v[122:125], v[160:163], v[188:191], v[122:125]
	v_mfma_f32_16x16x32_bf16 v[110:113], v[144:147], v[192:195], v[110:113]
	v_mfma_f32_16x16x32_bf16 v[110:113], v[148:151], v[196:199], v[110:113]
	v_mfma_f32_16x16x32_bf16 v[106:109], v[156:159], v[192:195], v[106:109]
	v_mfma_f32_16x16x32_bf16 v[106:109], v[160:163], v[196:199], v[106:109]
	v_mfma_f32_16x16x32_bf16 v[94:97], v[144:147], v[200:203], v[94:97]
	v_mfma_f32_16x16x32_bf16 v[94:97], v[148:151], v[204:207], v[94:97]
	v_mfma_f32_16x16x32_bf16 v[90:93], v[156:159], v[200:203], v[90:93]
	v_mfma_f32_16x16x32_bf16 v[90:93], v[160:163], v[204:207], v[90:93]
	v_mfma_f32_16x16x32_bf16 v[78:81], v[144:147], v[208:211], v[78:81]
	v_mfma_f32_16x16x32_bf16 v[78:81], v[148:151], v[212:215], v[78:81]
	v_mfma_f32_16x16x32_bf16 v[74:77], v[156:159], v[208:211], v[74:77]
	v_mfma_f32_16x16x32_bf16 v[74:77], v[160:163], v[212:215], v[74:77]
	v_mfma_f32_16x16x32_bf16 v[118:121], v[164:167], v[184:187], v[118:121]
	v_mfma_f32_16x16x32_bf16 v[118:121], v[168:171], v[188:191], v[118:121]
	v_mfma_f32_16x16x32_bf16 v[114:117], v[172:175], v[184:187], v[114:117]
	v_mfma_f32_16x16x32_bf16 v[114:117], v[180:183], v[188:191], v[114:117]
	v_mfma_f32_16x16x32_bf16 v[102:105], v[164:167], v[192:195], v[102:105]
	v_mfma_f32_16x16x32_bf16 v[102:105], v[168:171], v[196:199], v[102:105]
	v_mfma_f32_16x16x32_bf16 v[98:101], v[172:175], v[192:195], v[98:101]
	v_mfma_f32_16x16x32_bf16 v[98:101], v[180:183], v[196:199], v[98:101]
	v_mfma_f32_16x16x32_bf16 v[86:89], v[164:167], v[200:203], v[86:89]
	v_mfma_f32_16x16x32_bf16 v[86:89], v[168:171], v[204:207], v[86:89]
	v_mfma_f32_16x16x32_bf16 v[82:85], v[172:175], v[200:203], v[82:85]
	v_mfma_f32_16x16x32_bf16 v[82:85], v[180:183], v[204:207], v[82:85]
	v_mfma_f32_16x16x32_bf16 v[70:73], v[164:167], v[208:211], v[70:73]
	v_mfma_f32_16x16x32_bf16 v[70:73], v[168:171], v[212:215], v[70:73]
	v_mfma_f32_16x16x32_bf16 v[66:69], v[172:175], v[208:211], v[66:69]
	v_mfma_f32_16x16x32_bf16 v[66:69], v[180:183], v[212:215], v[66:69]
	s_barrier
	s_setprio 0
	s_add_i32 s50, s50, s53
	v_lshl_add_u64 v[216:217], s[24:25], 0, v[132:133]
	s_mov_b32 m0, s50
	ds_read_b128 v[184:187], v155 offset:16384
	ds_read_b128 v[188:191], v155 offset:17408
	ds_read_b128 v[192:195], v155 offset:18432
	ds_read_b128 v[196:199], v155 offset:19456
	ds_read_b128 v[200:203], v155 offset:20480
	ds_read_b128 v[204:207], v155 offset:21504
	ds_read_b128 v[208:211], v155 offset:22528
	ds_read_b128 v[212:215], v155 offset:23552
	global_load_lds_dwordx4 v[216:217], off
	s_add_i32 m0, s50, 0x2000
	s_add_u32 s50, s24, 0x80000
	v_lshl_add_u64 v[218:219], s[24:25], 0, v[136:137]
	s_addc_u32 s51, s25, 0
	s_add_i32 s52, s52, s53
	global_load_lds_dwordx4 v[218:219], off
	v_lshl_add_u64 v[220:221], s[50:51], 0, v[132:133]
	s_mov_b32 m0, s52
	v_lshl_add_u64 v[222:223], s[28:29], 0, v[134:135]
	global_load_lds_dwordx4 v[220:221], off
	v_lshl_add_u64 v[220:221], s[50:51], 0, v[136:137]
	s_add_i32 m0, s52, 0x2000
	s_nop 0
	global_load_lds_dwordx4 v[220:221], off
	v_lshl_add_u64 v[220:221], s[28:29], 0, v[130:131]
	s_mov_b32 m0, s27
	s_nop 0
	global_load_lds_dwordx4 v[220:221], off
	s_mov_b32 m0, s34
	s_nop 0
	global_load_lds_dwordx4 v[222:223], off
	s_waitcnt vmcnt(8)
	s_waitcnt lgkmcnt(0)
	s_setprio 1
	s_barrier
; #define PG8_STAGE(bufoff, gbase, voff) do { _Pragma("unroll") for (int _i = 0; _i < 2; ++_i) \
;         __builtin_amdgcn_global_load_lds((const unsigned*)((const char*)(gbase) + (voff)[_i]), (LAS unsigned*)(lds + (bufoff) + ldsw + _i * 8192), 16, 0, 0); } while (0)
; #define PG8_LDA(dst, b, h) do { _Pragma("unroll") for (int m = 0; m < 4; ++m) _Pragma("unroll") for (int k = 0; k < 2; ++k) dst[m][k] = *(const LAS bf16x8*)(lds + PG8_SA(b, h) + aoff + m * 2048 + k * 1024); } while (0)
; #define PG8_LDB(dst, b, h) do { _Pragma("unroll") for (int n = 0; n < 2; ++n) _Pragma("unroll") for (int k = 0; k < 2; ++k) dst[n][k] = *(const LAS bf16x8*)(lds + PG8_SB(b, h) + boff + n * 2048 + k * 1024); } while (0)
; #define PG8_MMA(ai, bj, At, Bt) do { __builtin_amdgcn_s_setprio(1); _Pragma("unroll") for (int m = 0; m < 4; ++m) _Pragma("unroll") for (int n = 0; n < 2; ++n) _Pragma("unroll") for (int k = 0; k < 2; ++k) \
;         acc[ai][bj][m][n] = __builtin_amdgcn_mfma_f32_16x16x32_bf16(Bt[n][k], At[m][k], acc[ai][bj][m][n], 0, 0, 0); __builtin_amdgcn_s_setprio(0); } while (0)
; #define PG8_WAIT_V(n) asm volatile("s_waitcnt vmcnt(" #n ")" ::: "memory")
; #define PG8_WAIT_L(n) asm volatile("s_waitcnt lgkmcnt(" #n ")" ::: "memory")
; #define PG8_BAR __builtin_amdgcn_s_barrier()
; #define PG8_SCHED __builtin_amdgcn_sched_barrier(0)
; template <class Epi, class Sched, int LDA, int LDB, bool ALIGN_EPI = true>
; __device__ __forceinline__ void gemm_phase(LAS unsigned char* lds, const Gemm g, const Sched& S, const Epi& E, int wave) {
;     ...
;             PG8_WAIT_V(8); PG8_WAIT_L(0); PG8_BAR; PG8_MMA(1, 0, At, B0); PG8_MMA(1, 1, At, B1); PG8_BAR; PG8_SCHED;
;             PG8_LDB(B0, 1, 0); PG8_LDB(B1, 1, 1); PG8_SCHED; PG8_LDA(At, 1, 0); PG8_STAGE(PG8_SA(0, 1), a2 + hstepA, voffA);
;             PG8_WAIT_V(8); PG8_WAIT_L(0); PG8_BAR; PG8_MMA(0, 0, At, B0); PG8_MMA(0, 1, At, B1); PG8_BAR; PG8_SCHED;
	v_mfma_f32_16x16x32_bf16 v[62:65], v[144:147], v[184:187], v[62:65]
	v_mfma_f32_16x16x32_bf16 v[62:65], v[148:151], v[188:191], v[62:65]
	v_mfma_f32_16x16x32_bf16 v[58:61], v[156:159], v[184:187], v[58:61]
	v_mfma_f32_16x16x32_bf16 v[58:61], v[160:163], v[188:191], v[58:61]
	v_mfma_f32_16x16x32_bf16 v[46:49], v[144:147], v[192:195], v[46:49]
	v_mfma_f32_16x16x32_bf16 v[46:49], v[148:151], v[196:199], v[46:49]
	v_mfma_f32_16x16x32_bf16 v[42:45], v[156:159], v[192:195], v[42:45]
	v_mfma_f32_16x16x32_bf16 v[42:45], v[160:163], v[196:199], v[42:45]
	v_mfma_f32_16x16x32_bf16 v[30:33], v[144:147], v[200:203], v[30:33]
	v_mfma_f32_16x16x32_bf16 v[30:33], v[148:151], v[204:207], v[30:33]
	v_mfma_f32_16x16x32_bf16 v[26:29], v[156:159], v[200:203], v[26:29]
	v_mfma_f32_16x16x32_bf16 v[26:29], v[160:163], v[204:207], v[26:29]
	v_mfma_f32_16x16x32_bf16 v[14:17], v[144:147], v[208:211], v[14:17]
	v_mfma_f32_16x16x32_bf16 v[14:17], v[148:151], v[212:215], v[14:17]
	v_mfma_f32_16x16x32_bf16 v[10:13], v[156:159], v[208:211], v[10:13]
	v_mfma_f32_16x16x32_bf16 v[10:13], v[160:163], v[212:215], v[10:13]
	v_mfma_f32_16x16x32_bf16 v[54:57], v[164:167], v[184:187], v[54:57]
	v_mfma_f32_16x16x32_bf16 v[54:57], v[168:171], v[188:191], v[54:57]
	v_mfma_f32_16x16x32_bf16 v[50:53], v[172:175], v[184:187], v[50:53]
	v_mfma_f32_16x16x32_bf16 v[50:53], v[180:183], v[188:191], v[50:53]
	v_mfma_f32_16x16x32_bf16 v[38:41], v[164:167], v[192:195], v[38:41]
	v_mfma_f32_16x16x32_bf16 v[38:41], v[168:171], v[196:199], v[38:41]
	v_mfma_f32_16x16x32_bf16 v[34:37], v[172:175], v[192:195], v[34:37]
	v_mfma_f32_16x16x32_bf16 v[34:37], v[180:183], v[196:199], v[34:37]
	v_mfma_f32_16x16x32_bf16 v[22:25], v[164:167], v[200:203], v[22:25]
	v_mfma_f32_16x16x32_bf16 v[22:25], v[168:171], v[204:207], v[22:25]
	v_mfma_f32_16x16x32_bf16 v[18:21], v[172:175], v[200:203], v[18:21]
	v_mfma_f32_16x16x32_bf16 v[18:21], v[180:183], v[204:207], v[18:21]
	v_mfma_f32_16x16x32_bf16 v[6:9], v[164:167], v[208:211], v[6:9]
	v_mfma_f32_16x16x32_bf16 v[6:9], v[168:171], v[212:215], v[6:9]
	v_mfma_f32_16x16x32_bf16 v[2:5], v[172:175], v[208:211], v[2:5]
	v_mfma_f32_16x16x32_bf16 v[2:5], v[180:183], v[212:215], v[2:5]
	s_barrier
	s_setprio 0
	ds_read_b128 v[184:187], v155 offset:32768
	ds_read_b128 v[188:191], v155 offset:33792
	ds_read_b128 v[192:195], v155 offset:34816
	ds_read_b128 v[196:199], v155 offset:35840
	ds_read_b128 v[200:203], v155 offset:36864
	ds_read_b128 v[204:207], v155 offset:37888
	ds_read_b128 v[208:211], v155 offset:38912
	ds_read_b128 v[212:215], v155 offset:39936
	s_add_i32 s50, 0, 0x18000
	v_add_u32_e32 v0, s50, v153
	s_add_i32 s51, 0, 0x1c000
	ds_read_b128 v[144:147], v0
	ds_read_b128 v[148:151], v0 offset:1024
	ds_read_b128 v[156:159], v0 offset:2048
	ds_read_b128 v[160:163], v0 offset:3072
	v_add_u32_e32 v0, s51, v153
	ds_read_b128 v[164:167], v0
	ds_read_b128 v[168:171], v0 offset:1024
	ds_read_b128 v[172:175], v0 offset:2048
	ds_read_b128 v[180:183], v0 offset:3072
	s_add_u32 s28, s28, 0x80000
	s_addc_u32 s29, s29, 0
	s_mov_b32 m0, s35
	v_lshl_add_u64 v[224:225], s[28:29], 0, v[130:131]
	global_load_lds_dwordx4 v[224:225], off
	v_lshl_add_u64 v[224:225], s[28:29], 0, v[134:135]
	s_mov_b32 m0, s36
	s_nop 0
	global_load_lds_dwordx4 v[224:225], off
	s_waitcnt vmcnt(8)
	s_waitcnt lgkmcnt(0)
	s_setprio 1
	s_barrier
	v_mfma_f32_16x16x32_bf16 v[126:129], v[144:147], v[184:187], v[126:129]
	v_mfma_f32_16x16x32_bf16 v[126:129], v[148:151], v[188:191], v[126:129]
	v_mfma_f32_16x16x32_bf16 v[122:125], v[156:159], v[184:187], v[122:125]
	v_mfma_f32_16x16x32_bf16 v[122:125], v[160:163], v[188:191], v[122:125]
	v_mfma_f32_16x16x32_bf16 v[110:113], v[144:147], v[192:195], v[110:113]
	v_mfma_f32_16x16x32_bf16 v[110:113], v[148:151], v[196:199], v[110:113]
	v_mfma_f32_16x16x32_bf16 v[106:109], v[156:159], v[192:195], v[106:109]
	v_mfma_f32_16x16x32_bf16 v[106:109], v[160:163], v[196:199], v[106:109]
	v_mfma_f32_16x16x32_bf16 v[94:97], v[144:147], v[200:203], v[94:97]
	v_mfma_f32_16x16x32_bf16 v[94:97], v[148:151], v[204:207], v[94:97]
	v_mfma_f32_16x16x32_bf16 v[90:93], v[156:159], v[200:203], v[90:93]
	v_mfma_f32_16x16x32_bf16 v[90:93], v[160:163], v[204:207], v[90:93]
	v_mfma_f32_16x16x32_bf16 v[78:81], v[144:147], v[208:211], v[78:81]
	v_mfma_f32_16x16x32_bf16 v[78:81], v[148:151], v[212:215], v[78:81]
	v_mfma_f32_16x16x32_bf16 v[74:77], v[156:159], v[208:211], v[74:77]
	v_mfma_f32_16x16x32_bf16 v[74:77], v[160:163], v[212:215], v[74:77]
	v_mfma_f32_16x16x32_bf16 v[118:121], v[164:167], v[184:187], v[118:121]
	v_mfma_f32_16x16x32_bf16 v[118:121], v[168:171], v[188:191], v[118:121]
	v_mfma_f32_16x16x32_bf16 v[114:117], v[172:175], v[184:187], v[114:117]
	v_mfma_f32_16x16x32_bf16 v[114:117], v[180:183], v[188:191], v[114:117]
	v_mfma_f32_16x16x32_bf16 v[102:105], v[164:167], v[192:195], v[102:105]
	v_mfma_f32_16x16x32_bf16 v[102:105], v[168:171], v[196:199], v[102:105]
	v_mfma_f32_16x16x32_bf16 v[98:101], v[172:175], v[192:195], v[98:101]
	v_mfma_f32_16x16x32_bf16 v[98:101], v[180:183], v[196:199], v[98:101]
	v_mfma_f32_16x16x32_bf16 v[86:89], v[164:167], v[200:203], v[86:89]
	v_mfma_f32_16x16x32_bf16 v[86:89], v[168:171], v[204:207], v[86:89]
	v_mfma_f32_16x16x32_bf16 v[82:85], v[172:175], v[200:203], v[82:85]
	v_mfma_f32_16x16x32_bf16 v[82:85], v[180:183], v[204:207], v[82:85]
	v_mfma_f32_16x16x32_bf16 v[70:73], v[164:167], v[208:211], v[70:73]
	v_mfma_f32_16x16x32_bf16 v[70:73], v[168:171], v[212:215], v[70:73]
	v_mfma_f32_16x16x32_bf16 v[66:69], v[172:175], v[208:211], v[66:69]
	v_mfma_f32_16x16x32_bf16 v[66:69], v[180:183], v[212:215], v[66:69]
	s_barrier
; #define PG8_STAGE(bufoff, gbase, voff) do { _Pragma("unroll") for (int _i = 0; _i < 2; ++_i) \
;         __builtin_amdgcn_global_load_lds((const unsigned*)((const char*)(gbase) + (voff)[_i]), (LAS unsigned*)(lds + (bufoff) + ldsw + _i * 8192), 16, 0, 0); } while (0)
; #define PG8_LDA(dst, b, h) do { _Pragma("unroll") for (int m = 0; m < 4; ++m) _Pragma("unroll") for (int k = 0; k < 2; ++k) dst[m][k] = *(const LAS bf16x8*)(lds + PG8_SA(b, h) + aoff + m * 2048 + k * 1024); } while (0)
; #define PG8_MMA(ai, bj, At, Bt) do { __builtin_amdgcn_s_setprio(1); _Pragma("unroll") for (int m = 0; m < 4; ++m) _Pragma("unroll") for (int n = 0; n < 2; ++n) _Pragma("unroll") for (int k = 0; k < 2; ++k) \
;         acc[ai][bj][m][n] = __builtin_amdgcn_mfma_f32_16x16x32_bf16(Bt[n][k], At[m][k], acc[ai][bj][m][n], 0, 0, 0); __builtin_amdgcn_s_setprio(0); } while (0)
; #define PG8_WAIT_V(n) asm volatile("s_waitcnt vmcnt(" #n ")" ::: "memory")
; #define PG8_WAIT_L(n) asm volatile("s_waitcnt lgkmcnt(" #n ")" ::: "memory")
; #define PG8_BAR __builtin_amdgcn_s_barrier()
; #define PG8_SCHED __builtin_amdgcn_sched_barrier(0)
; template <class Epi, class Sched, int LDA, int LDB, bool ALIGN_EPI = true>
; __device__ __forceinline__ void gemm_phase(LAS unsigned char* lds, const Gemm g, const Sched& S, const Epi& E, int wave) {
;     ...
;             PG8_LDA(At, 1, 1); PG8_STAGE(PG8_SB(1, 0), b3, voffB); PG8_STAGE(PG8_SB(1, 1), b3 + hstepB, voffB); PG8_STAGE(PG8_SA(1, 0), a3, voffA);
;             PG8_WAIT_V(8); PG8_WAIT_L(0); PG8_BAR; PG8_MMA(1, 0, At, B0); PG8_MMA(1, 1, At, B1); PG8_BAR; PG8_SCHED;
;         }
;         if constexpr (ALIGN_EPI) { if (wr == 0) PG8_BAR; }
	s_setprio 0
	s_add_i32 s28, s50, s53
	v_lshl_add_u64 v[216:217], v[216:217], 0, s[54:55]
	s_mov_b32 m0, s28
	ds_read_b128 v[184:187], v155 offset:49152
	ds_read_b128 v[188:191], v155 offset:50176
	ds_read_b128 v[192:195], v155 offset:51200
	ds_read_b128 v[196:199], v155 offset:52224
	ds_read_b128 v[200:203], v155 offset:53248
	ds_read_b128 v[204:207], v155 offset:54272
	ds_read_b128 v[208:211], v155 offset:55296
	ds_read_b128 v[212:215], v155 offset:56320
	global_load_lds_dwordx4 v[216:217], off
	s_add_i32 m0, s28, 0x2000
	s_add_u32 s24, s24, 0x80080
	v_lshl_add_u64 v[216:217], v[218:219], 0, s[54:55]
	s_addc_u32 s25, s25, 0
	s_add_i32 s28, s51, s53
	global_load_lds_dwordx4 v[216:217], off
	v_lshl_add_u64 v[216:217], s[24:25], 0, v[132:133]
	s_mov_b32 m0, s28
	s_nop 0
	global_load_lds_dwordx4 v[216:217], off
	v_lshl_add_u64 v[216:217], s[24:25], 0, v[136:137]
	s_add_i32 m0, s28, 0x2000
	s_nop 0
	global_load_lds_dwordx4 v[216:217], off
	v_lshl_add_u64 v[216:217], v[220:221], 0, s[54:55]
	s_mov_b32 m0, s37
	s_nop 0
	global_load_lds_dwordx4 v[216:217], off
	v_lshl_add_u64 v[216:217], v[222:223], 0, s[54:55]
	s_mov_b32 m0, s38
	s_nop 0
	global_load_lds_dwordx4 v[216:217], off
	s_waitcnt vmcnt(8)
	s_waitcnt lgkmcnt(0)
	s_setprio 1
	s_barrier
	v_mfma_f32_16x16x32_bf16 v[62:65], v[144:147], v[184:187], v[62:65]
	v_mfma_f32_16x16x32_bf16 v[62:65], v[148:151], v[188:191], v[62:65]
	v_mfma_f32_16x16x32_bf16 v[58:61], v[156:159], v[184:187], v[58:61]
	v_mfma_f32_16x16x32_bf16 v[58:61], v[160:163], v[188:191], v[58:61]
	v_mfma_f32_16x16x32_bf16 v[46:49], v[144:147], v[192:195], v[46:49]
	v_mfma_f32_16x16x32_bf16 v[46:49], v[148:151], v[196:199], v[46:49]
	v_mfma_f32_16x16x32_bf16 v[42:45], v[156:159], v[192:195], v[42:45]
	v_mfma_f32_16x16x32_bf16 v[42:45], v[160:163], v[196:199], v[42:45]
	v_mfma_f32_16x16x32_bf16 v[30:33], v[144:147], v[200:203], v[30:33]
	v_mfma_f32_16x16x32_bf16 v[30:33], v[148:151], v[204:207], v[30:33]
	v_mfma_f32_16x16x32_bf16 v[26:29], v[156:159], v[200:203], v[26:29]
	v_mfma_f32_16x16x32_bf16 v[26:29], v[160:163], v[204:207], v[26:29]
	v_mfma_f32_16x16x32_bf16 v[14:17], v[144:147], v[208:211], v[14:17]
	v_mfma_f32_16x16x32_bf16 v[14:17], v[148:151], v[212:215], v[14:17]
	v_mfma_f32_16x16x32_bf16 v[10:13], v[156:159], v[208:211], v[10:13]
	v_mfma_f32_16x16x32_bf16 v[10:13], v[160:163], v[212:215], v[10:13]
	v_mfma_f32_16x16x32_bf16 v[54:57], v[164:167], v[184:187], v[54:57]
	v_mfma_f32_16x16x32_bf16 v[54:57], v[168:171], v[188:191], v[54:57]
	v_mfma_f32_16x16x32_bf16 v[50:53], v[172:175], v[184:187], v[50:53]
	v_mfma_f32_16x16x32_bf16 v[50:53], v[180:183], v[188:191], v[50:53]
	v_mfma_f32_16x16x32_bf16 v[38:41], v[164:167], v[192:195], v[38:41]
	v_mfma_f32_16x16x32_bf16 v[38:41], v[168:171], v[196:199], v[38:41]
	v_mfma_f32_16x16x32_bf16 v[34:37], v[172:175], v[192:195], v[34:37]
	v_mfma_f32_16x16x32_bf16 v[34:37], v[180:183], v[196:199], v[34:37]
	v_mfma_f32_16x16x32_bf16 v[22:25], v[164:167], v[200:203], v[22:25]
	v_mfma_f32_16x16x32_bf16 v[22:25], v[168:171], v[204:207], v[22:25]
	v_mfma_f32_16x16x32_bf16 v[18:21], v[172:175], v[200:203], v[18:21]
	v_mfma_f32_16x16x32_bf16 v[18:21], v[180:183], v[204:207], v[18:21]
	v_mfma_f32_16x16x32_bf16 v[6:9], v[164:167], v[208:211], v[6:9]
	v_mfma_f32_16x16x32_bf16 v[6:9], v[168:171], v[212:215], v[6:9]
	v_mfma_f32_16x16x32_bf16 v[2:5], v[172:175], v[208:211], v[2:5]
	v_mfma_f32_16x16x32_bf16 v[2:5], v[180:183], v[212:215], v[2:5]
	s_barrier
	s_setprio 0
	s_add_u32 s18, s18, 0x100
	s_addc_u32 s19, s19, 0
	s_add_u32 s44, s44, 0x100
	s_addc_u32 s45, s45, 0
	s_cmp_ge_i32 s49, s43
	s_mov_b32 s24, s49
	s_cbranch_scc0 .LBB0_4715
	v_readlane_b32 s18, v252, 14
	v_readlane_b32 s19, v252, 15
	s_and_b64 vcc, exec, s[18:19]
	s_cbranch_vccz .LBB0_4718
	s_barrier

; #define PG8_STAGE(bufoff, gbase, voff) do { _Pragma("unroll") for (int _i = 0; _i < 2; ++_i) \
;         __builtin_amdgcn_global_load_lds((const unsigned*)((const char*)(gbase) + (voff)[_i]), (LAS unsigned*)(lds + (bufoff) + ldsw + _i * 8192), 16, 0, 0); } while (0)
; #define PG8_LDA(dst, b, h) do { _Pragma("unroll") for (int m = 0; m < 4; ++m) _Pragma("unroll") for (int k = 0; k < 2; ++k) dst[m][k] = *(const LAS bf16x8*)(lds + PG8_SA(b, h) + aoff + m * 2048 + k * 1024); } while (0)
; #define PG8_LDB(dst, b, h) do { _Pragma("unroll") for (int n = 0; n < 2; ++n) _Pragma("unroll") for (int k = 0; k < 2; ++k) dst[n][k] = *(const LAS bf16x8*)(lds + PG8_SB(b, h) + boff + n * 2048 + k * 1024); } while (0)
; #define PG8_MMA(ai, bj, At, Bt) do { __builtin_amdgcn_s_setprio(1); _Pragma("unroll") for (int m = 0; m < 4; ++m) _Pragma("unroll") for (int n = 0; n < 2; ++n) _Pragma("unroll") for (int k = 0; k < 2; ++k) \
;         acc[ai][bj][m][n] = __builtin_amdgcn_mfma_f32_16x16x32_bf16(Bt[n][k], At[m][k], acc[ai][bj][m][n], 0, 0, 0); __builtin_amdgcn_s_setprio(0); } while (0)
; #define PG8_WAIT_V(n) asm volatile("s_waitcnt vmcnt(" #n ")" ::: "memory")
; #define PG8_WAIT_L(n) asm volatile("s_waitcnt lgkmcnt(" #n ")" ::: "memory")
; #define PG8_BAR __builtin_amdgcn_s_barrier()
; #define PG8_SCHED __builtin_amdgcn_sched_barrier(0)
; template <class Epi, class Sched, int LDA, int LDB, bool ALIGN_EPI = true>
; __device__ __forceinline__ void gemm_phase(LAS unsigned char* lds, const Gemm g, const Sched& S, const Epi& E, int wave) {
;     ...
;         for (int t = 0; t < nt; t += 2) {
;             const bool last = (t == nt - 2);
;             const char* a1 = cA + (size_t)(t + 1) * kstep;
;             const char* a2 = last ? nA : cA + (size_t)(t + 2) * kstep; const char* b2 = last ? nB : cB + (size_t)(t + 2) * kstep;
;             const char* a3 = a2 + kstep; const char* b3 = b2 + kstep;
;             PG8_LDB(B0, 0, 0); PG8_LDB(B1, 0, 1); PG8_SCHED; PG8_LDA(At, 0, 0); PG8_STAGE(PG8_SA(1, 1), a1 + hstepA, voffA);
;             PG8_WAIT_V(8); PG8_WAIT_L(0); PG8_BAR; PG8_MMA(0, 0, At, B0); PG8_MMA(0, 1, At, B1); PG8_BAR; PG8_SCHED;
;             PG8_LDA(At, 0, 1); PG8_STAGE(PG8_SB(0, 0), b2, voffB); PG8_STAGE(PG8_SB(0, 1), b2 + hstepB, voffB); PG8_STAGE(PG8_SA(0, 0), a2, voffA);
.LBB0_4901:
	ds_read_b128 v[172:175], v215
	ds_read_b128 v[180:183], v215 offset:1024
	ds_read_b128 v[184:187], v215 offset:2048
	ds_read_b128 v[188:191], v215 offset:3072
	ds_read_b128 v[192:195], v215 offset:4096
	ds_read_b128 v[196:199], v215 offset:5120
	ds_read_b128 v[200:203], v215 offset:6144
	ds_read_b128 v[204:207], v215 offset:7168
	s_add_i32 s65, s36, 2
	s_add_u32 s37, s34, 0xfff80080
	s_addc_u32 s38, s35, -1
	s_add_i32 s66, 0, 0x10000
	s_cmp_eq_u32 s29, s36
	s_cselect_b32 s39, s9, s38
	s_cselect_b32 s38, s13, s37
	s_cselect_b32 s37, s11, s64
	s_cselect_b32 s36, s25, s59
	s_add_i32 s72, 0, 0x14000
	v_add_u32_e32 v70, s66, v213
	v_add_u32_e32 v168, s72, v213
	ds_read_b128 v[50:53], v70
	ds_read_b128 v[54:57], v70 offset:1024
	ds_read_b128 v[66:69], v70 offset:2048
	ds_read_b128 v[70:73], v70 offset:3072
	ds_read_b128 v[156:159], v168
	ds_read_b128 v[160:163], v168 offset:1024
	ds_read_b128 v[164:167], v168 offset:2048
	ds_read_b128 v[168:171], v168 offset:3072
	v_lshl_add_u64 v[208:209], s[34:35], 0, v[152:153]
	s_add_i32 m0, s27, 0xc000
	s_nop 0
	global_load_lds_dwordx4 v[208:209], off
	v_lshl_add_u64 v[208:209], s[34:35], 0, v[154:155]
	s_add_i32 m0, s27, 0xe000
	s_nop 0
	global_load_lds_dwordx4 v[208:209], off
	s_waitcnt vmcnt(8)
	s_waitcnt lgkmcnt(0)
	s_setprio 1
	s_barrier
	v_mfma_f32_16x16x32_bf16 v[142:145], v[50:53], v[172:175], v[142:145]
	v_mfma_f32_16x16x32_bf16 v[142:145], v[54:57], v[180:183], v[142:145]
	v_mfma_f32_16x16x32_bf16 v[138:141], v[66:69], v[172:175], v[138:141]
	v_mfma_f32_16x16x32_bf16 v[138:141], v[70:73], v[180:183], v[138:141]
	v_mfma_f32_16x16x32_bf16 v[126:129], v[50:53], v[184:187], v[126:129]
	v_mfma_f32_16x16x32_bf16 v[126:129], v[54:57], v[188:191], v[126:129]
	v_mfma_f32_16x16x32_bf16 v[122:125], v[66:69], v[184:187], v[122:125]
	v_mfma_f32_16x16x32_bf16 v[122:125], v[70:73], v[188:191], v[122:125]
	v_mfma_f32_16x16x32_bf16 v[110:113], v[50:53], v[192:195], v[110:113]
	v_mfma_f32_16x16x32_bf16 v[110:113], v[54:57], v[196:199], v[110:113]
	v_mfma_f32_16x16x32_bf16 v[106:109], v[66:69], v[192:195], v[106:109]
	v_mfma_f32_16x16x32_bf16 v[106:109], v[70:73], v[196:199], v[106:109]
	v_mfma_f32_16x16x32_bf16 v[94:97], v[50:53], v[200:203], v[94:97]
	v_mfma_f32_16x16x32_bf16 v[94:97], v[54:57], v[204:207], v[94:97]
	v_mfma_f32_16x16x32_bf16 v[90:93], v[66:69], v[200:203], v[90:93]
	v_mfma_f32_16x16x32_bf16 v[90:93], v[70:73], v[204:207], v[90:93]
	v_mfma_f32_16x16x32_bf16 v[134:137], v[156:159], v[172:175], v[134:137]
	v_mfma_f32_16x16x32_bf16 v[134:137], v[160:163], v[180:183], v[134:137]
	v_mfma_f32_16x16x32_bf16 v[130:133], v[164:167], v[172:175], v[130:133]
	v_mfma_f32_16x16x32_bf16 v[130:133], v[168:171], v[180:183], v[130:133]
	v_mfma_f32_16x16x32_bf16 v[118:121], v[156:159], v[184:187], v[118:121]
	v_mfma_f32_16x16x32_bf16 v[118:121], v[160:163], v[188:191], v[118:121]
	v_mfma_f32_16x16x32_bf16 v[114:117], v[164:167], v[184:187], v[114:117]
	v_mfma_f32_16x16x32_bf16 v[114:117], v[168:171], v[188:191], v[114:117]
	v_mfma_f32_16x16x32_bf16 v[102:105], v[156:159], v[192:195], v[102:105]
	v_mfma_f32_16x16x32_bf16 v[102:105], v[160:163], v[196:199], v[102:105]
	v_mfma_f32_16x16x32_bf16 v[98:101], v[164:167], v[192:195], v[98:101]
	v_mfma_f32_16x16x32_bf16 v[98:101], v[168:171], v[196:199], v[98:101]
	v_mfma_f32_16x16x32_bf16 v[86:89], v[156:159], v[200:203], v[86:89]
	v_mfma_f32_16x16x32_bf16 v[86:89], v[160:163], v[204:207], v[86:89]
	v_mfma_f32_16x16x32_bf16 v[82:85], v[164:167], v[200:203], v[82:85]
	v_mfma_f32_16x16x32_bf16 v[82:85], v[168:171], v[204:207], v[82:85]
	s_barrier
	s_setprio 0
	s_add_i32 s66, s66, s60
	v_lshl_add_u64 v[208:209], s[36:37], 0, v[0:1]
	s_mov_b32 m0, s66
	ds_read_b128 v[172:175], v215 offset:16384
	ds_read_b128 v[180:183], v215 offset:17408
	ds_read_b128 v[184:187], v215 offset:18432
	ds_read_b128 v[188:191], v215 offset:19456
	ds_read_b128 v[192:195], v215 offset:20480
	ds_read_b128 v[196:199], v215 offset:21504
	ds_read_b128 v[200:203], v215 offset:22528
	ds_read_b128 v[204:207], v215 offset:23552
	global_load_lds_dwordx4 v[208:209], off
	s_add_i32 m0, s66, 0x2000
	s_add_u32 s66, s36, 0x80000
	v_lshl_add_u64 v[210:211], s[36:37], 0, v[150:151]
	s_addc_u32 s67, s37, 0
	s_add_i32 s72, s72, s60
	global_load_lds_dwordx4 v[210:211], off
	v_lshl_add_u64 v[216:217], s[66:67], 0, v[0:1]
	s_mov_b32 m0, s72
	v_lshl_add_u64 v[218:219], s[38:39], 0, v[148:149]
	global_load_lds_dwordx4 v[216:217], off
	v_lshl_add_u64 v[216:217], s[66:67], 0, v[150:151]
	s_add_i32 m0, s72, 0x2000
	s_nop 0
	global_load_lds_dwordx4 v[216:217], off
	v_lshl_add_u64 v[216:217], s[38:39], 0, v[146:147]
	s_mov_b32 m0, s27
	s_nop 0
	global_load_lds_dwordx4 v[216:217], off
	s_mov_b32 m0, s44
	s_nop 0
	global_load_lds_dwordx4 v[218:219], off
	s_waitcnt vmcnt(8)
	s_waitcnt lgkmcnt(0)
	s_setprio 1
	s_barrier
; #define PG8_STAGE(bufoff, gbase, voff) do { _Pragma("unroll") for (int _i = 0; _i < 2; ++_i) \
;         __builtin_amdgcn_global_load_lds((const unsigned*)((const char*)(gbase) + (voff)[_i]), (LAS unsigned*)(lds + (bufoff) + ldsw + _i * 8192), 16, 0, 0); } while (0)
; #define PG8_LDA(dst, b, h) do { _Pragma("unroll") for (int m = 0; m < 4; ++m) _Pragma("unroll") for (int k = 0; k < 2; ++k) dst[m][k] = *(const LAS bf16x8*)(lds + PG8_SA(b, h) + aoff + m * 2048 + k * 1024); } while (0)
; #define PG8_LDB(dst, b, h) do { _Pragma("unroll") for (int n = 0; n < 2; ++n) _Pragma("unroll") for (int k = 0; k < 2; ++k) dst[n][k] = *(const LAS bf16x8*)(lds + PG8_SB(b, h) + boff + n * 2048 + k * 1024); } while (0)
; #define PG8_MMA(ai, bj, At, Bt) do { __builtin_amdgcn_s_setprio(1); _Pragma("unroll") for (int m = 0; m < 4; ++m) _Pragma("unroll") for (int n = 0; n < 2; ++n) _Pragma("unroll") for (int k = 0; k < 2; ++k) \
;         acc[ai][bj][m][n] = __builtin_amdgcn_mfma_f32_16x16x32_bf16(Bt[n][k], At[m][k], acc[ai][bj][m][n], 0, 0, 0); __builtin_amdgcn_s_setprio(0); } while (0)
; #define PG8_WAIT_V(n) asm volatile("s_waitcnt vmcnt(" #n ")" ::: "memory")
; #define PG8_WAIT_L(n) asm volatile("s_waitcnt lgkmcnt(" #n ")" ::: "memory")
; #define PG8_BAR __builtin_amdgcn_s_barrier()
; #define PG8_SCHED __builtin_amdgcn_sched_barrier(0)
; template <class Epi, class Sched, int LDA, int LDB, bool ALIGN_EPI = true>
; __device__ __forceinline__ void gemm_phase(LAS unsigned char* lds, const Gemm g, const Sched& S, const Epi& E, int wave) {
;     ...
;             PG8_WAIT_V(8); PG8_WAIT_L(0); PG8_BAR; PG8_MMA(0, 0, At, B0); PG8_MMA(0, 1, At, B1); PG8_BAR; PG8_SCHED;
;             PG8_LDA(At, 0, 1); PG8_STAGE(PG8_SB(0, 0), b2, voffB); PG8_STAGE(PG8_SB(0, 1), b2 + hstepB, voffB); PG8_STAGE(PG8_SA(0, 0), a2, voffA);
;             PG8_WAIT_V(8); PG8_WAIT_L(0); PG8_BAR; PG8_MMA(1, 0, At, B0); PG8_MMA(1, 1, At, B1); PG8_BAR; PG8_SCHED;
;             PG8_LDB(B0, 1, 0); PG8_LDB(B1, 1, 1); PG8_SCHED; PG8_LDA(At, 1, 0); PG8_STAGE(PG8_SA(0, 1), a2 + hstepA, voffA);
;             PG8_WAIT_V(8); PG8_WAIT_L(0); PG8_BAR; PG8_MMA(0, 0, At, B0); PG8_MMA(0, 1, At, B1); PG8_BAR; PG8_SCHED;
;             PG8_LDA(At, 1, 1); PG8_STAGE(PG8_SB(1, 0), b3, voffB); PG8_STAGE(PG8_SB(1, 1), b3 + hstepB, voffB); PG8_STAGE(PG8_SA(1, 0), a3, voffA);
	v_mfma_f32_16x16x32_bf16 v[78:81], v[50:53], v[172:175], v[78:81]
	v_mfma_f32_16x16x32_bf16 v[74:77], v[66:69], v[172:175], v[74:77]
	v_mfma_f32_16x16x32_bf16 v[46:49], v[50:53], v[184:187], v[46:49]
	v_mfma_f32_16x16x32_bf16 v[42:45], v[66:69], v[184:187], v[42:45]
	v_mfma_f32_16x16x32_bf16 v[30:33], v[50:53], v[192:195], v[30:33]
	v_mfma_f32_16x16x32_bf16 v[26:29], v[66:69], v[192:195], v[26:29]
	v_mfma_f32_16x16x32_bf16 v[14:17], v[50:53], v[200:203], v[14:17]
	v_mfma_f32_16x16x32_bf16 v[10:13], v[66:69], v[200:203], v[10:13]
	v_mfma_f32_16x16x32_bf16 v[78:81], v[54:57], v[180:183], v[78:81]
	v_mfma_f32_16x16x32_bf16 v[74:77], v[70:73], v[180:183], v[74:77]
	v_mfma_f32_16x16x32_bf16 v[46:49], v[54:57], v[188:191], v[46:49]
	v_mfma_f32_16x16x32_bf16 v[42:45], v[70:73], v[188:191], v[42:45]
	v_mfma_f32_16x16x32_bf16 v[30:33], v[54:57], v[196:199], v[30:33]
	v_mfma_f32_16x16x32_bf16 v[26:29], v[70:73], v[196:199], v[26:29]
	v_mfma_f32_16x16x32_bf16 v[14:17], v[54:57], v[204:207], v[14:17]
	v_mfma_f32_16x16x32_bf16 v[10:13], v[70:73], v[204:207], v[10:13]
	v_mfma_f32_16x16x32_bf16 v[38:41], v[156:159], v[184:187], v[38:41]
	v_mfma_f32_16x16x32_bf16 v[34:37], v[164:167], v[184:187], v[34:37]
	v_mfma_f32_16x16x32_bf16 v[22:25], v[156:159], v[192:195], v[22:25]
	v_mfma_f32_16x16x32_bf16 v[18:21], v[164:167], v[192:195], v[18:21]
	v_mfma_f32_16x16x32_bf16 v[6:9], v[156:159], v[200:203], v[6:9]
	v_mfma_f32_16x16x32_bf16 v[2:5], v[164:167], v[200:203], v[2:5]
	v_mfma_f32_16x16x32_bf16 v[50:53], v[156:159], v[172:175], v[62:65]
	v_mfma_f32_16x16x32_bf16 v[54:57], v[164:167], v[172:175], v[58:61]
	v_mfma_f32_16x16x32_bf16 v[38:41], v[160:163], v[188:191], v[38:41]
	v_mfma_f32_16x16x32_bf16 v[34:37], v[168:171], v[188:191], v[34:37]
	v_mfma_f32_16x16x32_bf16 v[22:25], v[160:163], v[196:199], v[22:25]
	v_mfma_f32_16x16x32_bf16 v[18:21], v[168:171], v[196:199], v[18:21]
	v_mfma_f32_16x16x32_bf16 v[6:9], v[160:163], v[204:207], v[6:9]
	v_mfma_f32_16x16x32_bf16 v[2:5], v[168:171], v[204:207], v[2:5]
	v_mfma_f32_16x16x32_bf16 v[50:53], v[160:163], v[180:183], v[50:53]
	v_mfma_f32_16x16x32_bf16 v[54:57], v[168:171], v[180:183], v[54:57]
	s_barrier
	s_setprio 0
	ds_read_b128 v[172:175], v215 offset:32768
	ds_read_b128 v[180:183], v215 offset:33792
	ds_read_b128 v[184:187], v215 offset:34816
	ds_read_b128 v[188:191], v215 offset:35840
	ds_read_b128 v[192:195], v215 offset:36864
	ds_read_b128 v[196:199], v215 offset:37888
	ds_read_b128 v[200:203], v215 offset:38912
	ds_read_b128 v[204:207], v215 offset:39936
	s_add_i32 s66, 0, 0x18000
	s_add_i32 s67, 0, 0x1c000
	v_add_u32_e32 v70, s66, v213
	v_add_u32_e32 v168, s67, v213
	ds_read_b128 v[58:61], v70
	ds_read_b128 v[62:65], v70 offset:1024
	ds_read_b128 v[66:69], v70 offset:2048
	ds_read_b128 v[70:73], v70 offset:3072
	ds_read_b128 v[156:159], v168
	ds_read_b128 v[160:163], v168 offset:1024
	ds_read_b128 v[164:167], v168 offset:2048
	ds_read_b128 v[168:171], v168 offset:3072
	s_add_u32 s38, s38, 0x80000
	s_addc_u32 s39, s39, 0
	s_mov_b32 m0, s45
	v_lshl_add_u64 v[220:221], s[38:39], 0, v[146:147]
	global_load_lds_dwordx4 v[220:221], off
	v_lshl_add_u64 v[220:221], s[38:39], 0, v[148:149]
	s_mov_b32 m0, s46
	s_nop 0
	global_load_lds_dwordx4 v[220:221], off
	s_waitcnt vmcnt(8)
	s_waitcnt lgkmcnt(0)
	s_setprio 1
	s_barrier
	v_mfma_f32_16x16x32_bf16 v[142:145], v[58:61], v[172:175], v[142:145]
	v_mfma_f32_16x16x32_bf16 v[142:145], v[62:65], v[180:183], v[142:145]
	v_mfma_f32_16x16x32_bf16 v[138:141], v[66:69], v[172:175], v[138:141]
	v_mfma_f32_16x16x32_bf16 v[138:141], v[70:73], v[180:183], v[138:141]
	v_mfma_f32_16x16x32_bf16 v[126:129], v[58:61], v[184:187], v[126:129]
	v_mfma_f32_16x16x32_bf16 v[126:129], v[62:65], v[188:191], v[126:129]
	v_mfma_f32_16x16x32_bf16 v[122:125], v[66:69], v[184:187], v[122:125]
	v_mfma_f32_16x16x32_bf16 v[122:125], v[70:73], v[188:191], v[122:125]
	v_mfma_f32_16x16x32_bf16 v[110:113], v[58:61], v[192:195], v[110:113]
	v_mfma_f32_16x16x32_bf16 v[110:113], v[62:65], v[196:199], v[110:113]
	v_mfma_f32_16x16x32_bf16 v[106:109], v[66:69], v[192:195], v[106:109]
	v_mfma_f32_16x16x32_bf16 v[106:109], v[70:73], v[196:199], v[106:109]
	v_mfma_f32_16x16x32_bf16 v[94:97], v[58:61], v[200:203], v[94:97]
	v_mfma_f32_16x16x32_bf16 v[94:97], v[62:65], v[204:207], v[94:97]
	v_mfma_f32_16x16x32_bf16 v[90:93], v[66:69], v[200:203], v[90:93]
	v_mfma_f32_16x16x32_bf16 v[90:93], v[70:73], v[204:207], v[90:93]
	v_mfma_f32_16x16x32_bf16 v[134:137], v[156:159], v[172:175], v[134:137]
	v_mfma_f32_16x16x32_bf16 v[134:137], v[160:163], v[180:183], v[134:137]
	v_mfma_f32_16x16x32_bf16 v[130:133], v[164:167], v[172:175], v[130:133]
	v_mfma_f32_16x16x32_bf16 v[130:133], v[168:171], v[180:183], v[130:133]
	v_mfma_f32_16x16x32_bf16 v[118:121], v[156:159], v[184:187], v[118:121]
	v_mfma_f32_16x16x32_bf16 v[118:121], v[160:163], v[188:191], v[118:121]
	v_mfma_f32_16x16x32_bf16 v[114:117], v[164:167], v[184:187], v[114:117]
	v_mfma_f32_16x16x32_bf16 v[114:117], v[168:171], v[188:191], v[114:117]
	v_mfma_f32_16x16x32_bf16 v[102:105], v[156:159], v[192:195], v[102:105]
	v_mfma_f32_16x16x32_bf16 v[102:105], v[160:163], v[196:199], v[102:105]
	v_mfma_f32_16x16x32_bf16 v[98:101], v[164:167], v[192:195], v[98:101]
	v_mfma_f32_16x16x32_bf16 v[98:101], v[168:171], v[196:199], v[98:101]
	v_mfma_f32_16x16x32_bf16 v[86:89], v[156:159], v[200:203], v[86:89]
	v_mfma_f32_16x16x32_bf16 v[86:89], v[160:163], v[204:207], v[86:89]
	v_mfma_f32_16x16x32_bf16 v[82:85], v[164:167], v[200:203], v[82:85]
	v_mfma_f32_16x16x32_bf16 v[82:85], v[168:171], v[204:207], v[82:85]
	s_barrier
; #define PG8_STAGE(bufoff, gbase, voff) do { _Pragma("unroll") for (int _i = 0; _i < 2; ++_i) \
;         __builtin_amdgcn_global_load_lds((const unsigned*)((const char*)(gbase) + (voff)[_i]), (LAS unsigned*)(lds + (bufoff) + ldsw + _i * 8192), 16, 0, 0); } while (0)
; #define PG8_LDA(dst, b, h) do { _Pragma("unroll") for (int m = 0; m < 4; ++m) _Pragma("unroll") for (int k = 0; k < 2; ++k) dst[m][k] = *(const LAS bf16x8*)(lds + PG8_SA(b, h) + aoff + m * 2048 + k * 1024); } while (0)
; #define PG8_LDB(dst, b, h) do { _Pragma("unroll") for (int n = 0; n < 2; ++n) _Pragma("unroll") for (int k = 0; k < 2; ++k) dst[n][k] = *(const LAS bf16x8*)(lds + PG8_SB(b, h) + boff + n * 2048 + k * 1024); } while (0)
; #define PG8_MMA(ai, bj, At, Bt) do { __builtin_amdgcn_s_setprio(1); _Pragma("unroll") for (int m = 0; m < 4; ++m) _Pragma("unroll") for (int n = 0; n < 2; ++n) _Pragma("unroll") for (int k = 0; k < 2; ++k) \
;         acc[ai][bj][m][n] = __builtin_amdgcn_mfma_f32_16x16x32_bf16(Bt[n][k], At[m][k], acc[ai][bj][m][n], 0, 0, 0); __builtin_amdgcn_s_setprio(0); } while (0)
; #define PG8_WAIT_V(n) asm volatile("s_waitcnt vmcnt(" #n ")" ::: "memory")
; #define PG8_WAIT_L(n) asm volatile("s_waitcnt lgkmcnt(" #n ")" ::: "memory")
; #define PG8_BAR __builtin_amdgcn_s_barrier()
; #define PG8_SCHED __builtin_amdgcn_sched_barrier(0)
; template <class Epi, class Sched, int LDA, int LDB, bool ALIGN_EPI = true>
; __device__ __forceinline__ void gemm_phase(LAS unsigned char* lds, const Gemm g, const Sched& S, const Epi& E, int wave) {
;     ...
;             PG8_LDB(B0, 1, 0); PG8_LDB(B1, 1, 1); PG8_SCHED; PG8_LDA(At, 1, 0); PG8_STAGE(PG8_SA(0, 1), a2 + hstepA, voffA);
;             PG8_WAIT_V(8); PG8_WAIT_L(0); PG8_BAR; PG8_MMA(0, 0, At, B0); PG8_MMA(0, 1, At, B1); PG8_BAR; PG8_SCHED;
;             PG8_LDA(At, 1, 1); PG8_STAGE(PG8_SB(1, 0), b3, voffB); PG8_STAGE(PG8_SB(1, 1), b3 + hstepB, voffB); PG8_STAGE(PG8_SA(1, 0), a3, voffA);
;             PG8_WAIT_V(8); PG8_WAIT_L(0); PG8_BAR; PG8_MMA(1, 0, At, B0); PG8_MMA(1, 1, At, B1); PG8_BAR; PG8_SCHED;
;         }
;         if constexpr (ALIGN_EPI) { if (wr == 0) PG8_BAR; }
	s_setprio 0
	s_add_i32 s38, s66, s60
	v_lshl_add_u64 v[208:209], v[208:209], 0, s[70:71]
	s_mov_b32 m0, s38
	ds_read_b128 v[172:175], v215 offset:49152
	ds_read_b128 v[180:183], v215 offset:50176
	ds_read_b128 v[184:187], v215 offset:51200
	ds_read_b128 v[188:191], v215 offset:52224
	ds_read_b128 v[192:195], v215 offset:53248
	ds_read_b128 v[196:199], v215 offset:54272
	ds_read_b128 v[200:203], v215 offset:55296
	ds_read_b128 v[204:207], v215 offset:56320
	global_load_lds_dwordx4 v[208:209], off
	s_add_i32 m0, s38, 0x2000
	s_add_u32 s36, s36, 0x80080
	v_lshl_add_u64 v[208:209], v[210:211], 0, s[70:71]
	s_addc_u32 s37, s37, 0
	s_add_i32 s38, s67, s60
	global_load_lds_dwordx4 v[208:209], off
	v_lshl_add_u64 v[208:209], s[36:37], 0, v[0:1]
	s_mov_b32 m0, s38
	s_nop 0
	global_load_lds_dwordx4 v[208:209], off
	v_lshl_add_u64 v[208:209], s[36:37], 0, v[150:151]
	s_add_i32 m0, s38, 0x2000
	s_nop 0
	global_load_lds_dwordx4 v[208:209], off
	v_lshl_add_u64 v[208:209], v[216:217], 0, s[70:71]
	s_mov_b32 m0, s51
	s_nop 0
	global_load_lds_dwordx4 v[208:209], off
	v_lshl_add_u64 v[208:209], v[218:219], 0, s[70:71]
	s_mov_b32 m0, s52
	s_nop 0
	global_load_lds_dwordx4 v[208:209], off
	s_waitcnt vmcnt(8)
	s_waitcnt lgkmcnt(0)
	s_setprio 1
	s_barrier
	v_mfma_f32_16x16x32_bf16 v[78:81], v[58:61], v[172:175], v[78:81]
	v_mfma_f32_16x16x32_bf16 v[74:77], v[66:69], v[172:175], v[74:77]
	v_mfma_f32_16x16x32_bf16 v[46:49], v[58:61], v[184:187], v[46:49]
	v_mfma_f32_16x16x32_bf16 v[42:45], v[66:69], v[184:187], v[42:45]
	v_mfma_f32_16x16x32_bf16 v[30:33], v[58:61], v[192:195], v[30:33]
	v_mfma_f32_16x16x32_bf16 v[26:29], v[66:69], v[192:195], v[26:29]
	v_mfma_f32_16x16x32_bf16 v[14:17], v[58:61], v[200:203], v[14:17]
	v_mfma_f32_16x16x32_bf16 v[10:13], v[66:69], v[200:203], v[10:13]
	v_mfma_f32_16x16x32_bf16 v[78:81], v[62:65], v[180:183], v[78:81]
	v_mfma_f32_16x16x32_bf16 v[74:77], v[70:73], v[180:183], v[74:77]
	v_mfma_f32_16x16x32_bf16 v[46:49], v[62:65], v[188:191], v[46:49]
	v_mfma_f32_16x16x32_bf16 v[42:45], v[70:73], v[188:191], v[42:45]
	v_mfma_f32_16x16x32_bf16 v[30:33], v[62:65], v[196:199], v[30:33]
	v_mfma_f32_16x16x32_bf16 v[26:29], v[70:73], v[196:199], v[26:29]
	v_mfma_f32_16x16x32_bf16 v[14:17], v[62:65], v[204:207], v[14:17]
	v_mfma_f32_16x16x32_bf16 v[10:13], v[70:73], v[204:207], v[10:13]
	v_mfma_f32_16x16x32_bf16 v[50:53], v[156:159], v[172:175], v[50:53]
	v_mfma_f32_16x16x32_bf16 v[62:65], v[160:163], v[180:183], v[50:53]
	v_mfma_f32_16x16x32_bf16 v[50:53], v[164:167], v[172:175], v[54:57]
	v_mfma_f32_16x16x32_bf16 v[38:41], v[156:159], v[184:187], v[38:41]
	v_mfma_f32_16x16x32_bf16 v[34:37], v[164:167], v[184:187], v[34:37]
	v_mfma_f32_16x16x32_bf16 v[22:25], v[156:159], v[192:195], v[22:25]
	v_mfma_f32_16x16x32_bf16 v[18:21], v[164:167], v[192:195], v[18:21]
	v_mfma_f32_16x16x32_bf16 v[6:9], v[156:159], v[200:203], v[6:9]
	v_mfma_f32_16x16x32_bf16 v[2:5], v[164:167], v[200:203], v[2:5]
	v_mfma_f32_16x16x32_bf16 v[58:61], v[168:171], v[180:183], v[50:53]
	v_mfma_f32_16x16x32_bf16 v[38:41], v[160:163], v[188:191], v[38:41]
	v_mfma_f32_16x16x32_bf16 v[34:37], v[168:171], v[188:191], v[34:37]
	v_mfma_f32_16x16x32_bf16 v[22:25], v[160:163], v[196:199], v[22:25]
	v_mfma_f32_16x16x32_bf16 v[18:21], v[168:171], v[196:199], v[18:21]
	v_mfma_f32_16x16x32_bf16 v[6:9], v[160:163], v[204:207], v[6:9]
	v_mfma_f32_16x16x32_bf16 v[2:5], v[168:171], v[204:207], v[2:5]
	s_barrier
	s_setprio 0
	s_add_u32 s34, s34, 0x100
	s_addc_u32 s35, s35, 0
	s_add_u32 s59, s59, 0x100
	s_addc_u32 s64, s64, 0
	s_cmp_ge_i32 s65, s43
	s_mov_b32 s36, s65
	s_cbranch_scc0 .LBB0_4901
	v_readlane_b32 s34, v252, 14
	v_readlane_b32 s35, v252, 15
	s_and_b64 vcc, exec, s[34:35]
	s_cbranch_vccz .LBB0_4904
	s_barrier
